# mixer B LayerNorm loop: all 32 bf16 loads of an 8-token iteration issued up front (one round trip instead of eight); mask ops re-spaced in attention
# speedup vs baseline: 1.0541x; 1.0126x over previous
.Lat_pb0:
	s_waitcnt vmcnt(8)
	v_mfma_f32_32x32x16_bf16 v[198:213], v[140:143], v[50:53], v[198:213]
	v_lshrrev_b32_e32 v171, v139, v173
	v_lshrrev_b32_e32 v172, v139, v174
	s_add_i32 s26, s8, 1
	s_min_i32 s26, s26, s9
	v_mfma_f32_32x32x16_bf16 v[220:235], v[214:217], v[50:53], v[220:235]
	s_lshl_b32 s27, s26, 12
	s_lshl_b32 s34, s26, 7
	s_add_u32 s30, s20, s34
	s_addc_u32 s31, s21, 0
	v_mfma_f32_32x32x16_bf16 v[198:213], v[152:155], v[54:57], v[198:213]
	s_add_u32 s28, s10, s27
	s_addc_u32 s29, s11, 0
	s_cmp_gt_u32 s8, s35
	s_cselect_b32 s82, 0, -1
	v_mfma_f32_32x32x16_bf16 v[220:235], v[236:239], v[54:57], v[220:235]
	v_and_b32_e32 v171, s82, v171
	global_load_dword v173, v176, s[30:31] sc1
	global_load_dword v174, v177, s[30:31] sc1
	global_load_dwordx4 v[140:143], v175, s[28:29]
	global_load_dwordx4 v[152:155], v175, s[28:29] offset:1024
	global_load_dwordx4 v[214:217], v175, s[28:29] offset:2048
	global_load_dwordx4 v[236:239], v175, s[28:29] offset:3072
	v_mfma_f32_32x32x16_bf16 v[50:65], v[66:69], v[114:117], 0
	v_bfe_i32 v178, v171, 0, 1
	v_bfe_i32 v180, v171, 1, 1
	v_bfe_i32 v248, v171, 2, 1
	v_bfe_i32 v249, v171, 3, 1
	v_bitop3_b32 v34, v34, s96, v178 bitop3:0xe4
	v_bfe_i32 v178, v171, 8, 1
	v_bitop3_b32 v35, v35, s96, v180 bitop3:0xe4
	v_bfe_i32 v180, v171, 9, 1
	v_bitop3_b32 v36, v36, s96, v248 bitop3:0xe4
	v_mfma_f32_32x32x16_bf16 v[50:65], v[70:73], v[118:121], v[50:65]
	v_bfe_i32 v248, v171, 10, 1
	v_bitop3_b32 v37, v37, s96, v249 bitop3:0xe4
	v_bfe_i32 v249, v171, 11, 1
	v_bitop3_b32 v38, v38, s96, v178 bitop3:0xe4
	v_bfe_i32 v178, v171, 16, 1
	v_bitop3_b32 v39, v39, s96, v180 bitop3:0xe4
	v_bfe_i32 v180, v171, 17, 1
	v_bitop3_b32 v40, v40, s96, v248 bitop3:0xe4
	v_bfe_i32 v248, v171, 18, 1
	v_mfma_f32_32x32x16_bf16 v[50:65], v[74:77], v[122:125], v[50:65]
	v_bitop3_b32 v41, v41, s96, v249 bitop3:0xe4
	v_bfe_i32 v249, v171, 19, 1
	v_bitop3_b32 v42, v42, s96, v178 bitop3:0xe4
	v_bfe_i32 v178, v171, 24, 1
	v_bitop3_b32 v43, v43, s96, v180 bitop3:0xe4
	v_bfe_i32 v180, v171, 25, 1
	v_bitop3_b32 v44, v44, s96, v248 bitop3:0xe4
	v_bfe_i32 v248, v171, 26, 1
	v_bitop3_b32 v45, v45, s96, v249 bitop3:0xe4
	v_mfma_f32_32x32x16_bf16 v[50:65], v[78:81], v[126:129], v[50:65]
	v_bfe_i32 v249, v171, 27, 1
	v_bitop3_b32 v46, v46, s96, v178 bitop3:0xe4
	v_bitop3_b32 v47, v47, s96, v180 bitop3:0xe4
	v_bitop3_b32 v48, v48, s96, v248 bitop3:0xe4
	v_bitop3_b32 v49, v49, s96, v249 bitop3:0xe4
	s_add_i32 s26, s8, 2
	s_min_i32 s26, s26, s9
	s_lshl_b32 s27, s26, 12
	s_add_u32 s26, s6, s27
	s_addc_u32 s27, s7, 0
	global_load_dwordx4 v[66:69], v175, s[26:27]
	global_load_dwordx4 v[70:73], v175, s[26:27] offset:1024
	global_load_dwordx4 v[74:77], v175, s[26:27] offset:2048
	global_load_dwordx4 v[78:81], v175, s[26:27] offset:3072
	v_exp_f32_e32 v34, v34
	v_exp_f32_e32 v35, v35
	v_exp_f32_e32 v36, v36
	v_add_f32_e32 v196, v34, v35
	v_exp_f32_e32 v37, v37
	v_add_f32_e32 v196, v196, v36
	v_exp_f32_e32 v38, v38
	v_add_f32_e32 v196, v196, v37
	v_exp_f32_e32 v39, v39
	v_add_f32_e32 v196, v196, v38
	v_exp_f32_e32 v40, v40
	v_add_f32_e32 v196, v196, v39
	v_exp_f32_e32 v41, v41
	v_add_f32_e32 v196, v196, v40
	v_exp_f32_e32 v42, v42
	v_add_f32_e32 v196, v196, v41
	v_exp_f32_e32 v43, v43
	v_add_f32_e32 v196, v196, v42
	v_exp_f32_e32 v44, v44
	v_add_f32_e32 v196, v196, v43
	v_exp_f32_e32 v45, v45
	v_add_f32_e32 v196, v196, v44
	v_exp_f32_e32 v46, v46
	v_add_f32_e32 v196, v196, v45
	v_exp_f32_e32 v47, v47
	v_add_f32_e32 v196, v196, v46
	v_exp_f32_e32 v48, v48
	v_add_f32_e32 v196, v196, v47
	v_exp_f32_e32 v49, v49
	v_add_f32_e32 v196, v196, v48
	s_nop 0
	v_add_f32_e32 v196, v196, v49
	v_add_f32_e32 v167, v167, v196
	v_cvt_pk_bf16_f32 v34, v34, v35
	v_cvt_pk_bf16_f32 v35, v36, v37
	v_cvt_pk_bf16_f32 v36, v38, v39
	v_cvt_pk_bf16_f32 v37, v40, v41
	v_cvt_pk_bf16_f32 v38, v42, v43
	v_cvt_pk_bf16_f32 v39, v44, v45
	v_cvt_pk_bf16_f32 v40, v46, v47
	v_cvt_pk_bf16_f32 v41, v48, v49
	s_waitcnt vmcnt(14)
	v_bfe_i32 v178, v172, 0, 1
	v_bfe_i32 v180, v172, 1, 1
	v_mfma_f32_32x32x16_bf16 v[18:33], v[98:101], v[34:37], v[18:33]
	v_bfe_i32 v248, v172, 2, 1
	v_bfe_i32 v249, v172, 3, 1
	v_bitop3_b32 v50, v50, s96, v178 bitop3:0xe4
	v_bfe_i32 v178, v172, 8, 1
	v_bitop3_b32 v51, v51, s96, v180 bitop3:0xe4
	v_bfe_i32 v180, v172, 9, 1
	v_bitop3_b32 v52, v52, s96, v248 bitop3:0xe4
	v_bfe_i32 v248, v172, 10, 1
	v_mfma_f32_32x32x16_bf16 v[2:17], v[106:109], v[34:37], v[2:17]
	v_bitop3_b32 v53, v53, s96, v249 bitop3:0xe4
	v_bfe_i32 v249, v172, 11, 1
	v_bitop3_b32 v54, v54, s96, v178 bitop3:0xe4
	v_bfe_i32 v178, v172, 16, 1
	v_bitop3_b32 v55, v55, s96, v180 bitop3:0xe4
	v_bfe_i32 v180, v172, 17, 1
	v_bitop3_b32 v56, v56, s96, v248 bitop3:0xe4
	v_bfe_i32 v248, v172, 18, 1
	v_mfma_f32_32x32x16_bf16 v[18:33], v[102:105], v[38:41], v[18:33]
	v_bitop3_b32 v57, v57, s96, v249 bitop3:0xe4
	v_bfe_i32 v249, v172, 19, 1
	v_bitop3_b32 v58, v58, s96, v178 bitop3:0xe4
	v_bfe_i32 v178, v172, 24, 1
	v_bitop3_b32 v59, v59, s96, v180 bitop3:0xe4
	v_bfe_i32 v180, v172, 25, 1
	v_bitop3_b32 v60, v60, s96, v248 bitop3:0xe4
	v_bfe_i32 v248, v172, 26, 1
	v_mfma_f32_32x32x16_bf16 v[2:17], v[110:113], v[38:41], v[2:17]
	v_bitop3_b32 v61, v61, s96, v249 bitop3:0xe4
	v_bfe_i32 v249, v172, 27, 1
	v_bitop3_b32 v62, v62, s96, v178 bitop3:0xe4
	v_bitop3_b32 v63, v63, s96, v180 bitop3:0xe4
	v_bitop3_b32 v64, v64, s96, v248 bitop3:0xe4
	v_bitop3_b32 v65, v65, s96, v249 bitop3:0xe4
	v_exp_f32_e32 v50, v50
	s_waitcnt vmcnt(10)
	v_mfma_f32_32x32x16_bf16 v[34:49], v[130:133], v[82:85], 0
	v_exp_f32_e32 v51, v51
	v_exp_f32_e32 v52, v52
	v_add_f32_e32 v196, v50, v51
	v_exp_f32_e32 v53, v53
	v_add_f32_e32 v196, v196, v52
	v_exp_f32_e32 v54, v54
	v_add_f32_e32 v196, v196, v53
	v_exp_f32_e32 v55, v55
	v_mfma_f32_32x32x16_bf16 v[34:49], v[134:137], v[86:89], v[34:49]
	v_add_f32_e32 v196, v196, v54
	v_exp_f32_e32 v56, v56
	v_add_f32_e32 v196, v196, v55
	v_exp_f32_e32 v57, v57
	v_add_f32_e32 v196, v196, v56
	v_exp_f32_e32 v58, v58
	v_add_f32_e32 v196, v196, v57
	v_exp_f32_e32 v59, v59
	v_mfma_f32_32x32x16_bf16 v[34:49], v[182:185], v[90:93], v[34:49]
	v_add_f32_e32 v196, v196, v58
	v_exp_f32_e32 v60, v60
	v_add_f32_e32 v196, v196, v59
	v_exp_f32_e32 v61, v61
	v_add_f32_e32 v196, v196, v60
	v_exp_f32_e32 v62, v62
	v_add_f32_e32 v196, v196, v61
	v_exp_f32_e32 v63, v63
	v_mfma_f32_32x32x16_bf16 v[34:49], v[186:189], v[94:97], v[34:49]
	v_add_f32_e32 v196, v196, v62
	v_exp_f32_e32 v64, v64
	v_add_f32_e32 v196, v196, v63
	v_exp_f32_e32 v65, v65
	v_add_f32_e32 v196, v196, v64
	s_nop 0
	v_add_f32_e32 v196, v196, v65
	v_add_f32_e32 v169, v169, v196
	v_cvt_pk_bf16_f32 v50, v50, v51
	v_cvt_pk_bf16_f32 v51, v52, v53
	v_cvt_pk_bf16_f32 v52, v54, v55
	v_cvt_pk_bf16_f32 v53, v56, v57
	v_cvt_pk_bf16_f32 v54, v58, v59
	v_cvt_pk_bf16_f32 v55, v60, v61
	v_cvt_pk_bf16_f32 v56, v62, v63
	v_cvt_pk_bf16_f32 v57, v64, v65
	s_add_i32 s8, s8, 1
	s_cmp_lt_i32 s8, s19
	s_cbranch_scc0 .Lat_px0
.Lat_pb1:
	s_waitcnt vmcnt(8)
	v_mfma_f32_32x32x16_bf16 v[198:213], v[98:101], v[50:53], v[198:213]
	v_lshrrev_b32_e32 v171, v139, v173
	v_lshrrev_b32_e32 v172, v139, v174
	s_add_i32 s26, s8, 1
	s_min_i32 s26, s26, s9
	v_mfma_f32_32x32x16_bf16 v[220:235], v[106:109], v[50:53], v[220:235]
	s_lshl_b32 s27, s26, 12
	s_lshl_b32 s34, s26, 7
	s_add_u32 s30, s20, s34
	s_addc_u32 s31, s21, 0
	v_mfma_f32_32x32x16_bf16 v[198:213], v[102:105], v[54:57], v[198:213]
	s_add_u32 s28, s10, s27
	s_addc_u32 s29, s11, 0
	s_cmp_gt_u32 s8, s35
	s_cselect_b32 s82, 0, -1
	v_mfma_f32_32x32x16_bf16 v[220:235], v[110:113], v[54:57], v[220:235]
	v_and_b32_e32 v171, s82, v171
	global_load_dword v173, v176, s[30:31] sc1
	global_load_dword v174, v177, s[30:31] sc1
	global_load_dwordx4 v[98:101], v175, s[28:29]
	global_load_dwordx4 v[102:105], v175, s[28:29] offset:1024
	global_load_dwordx4 v[106:109], v175, s[28:29] offset:2048
	global_load_dwordx4 v[110:113], v175, s[28:29] offset:3072
	v_mfma_f32_32x32x16_bf16 v[50:65], v[130:133], v[114:117], 0
	v_bfe_i32 v178, v171, 0, 1
	v_bfe_i32 v180, v171, 1, 1
	v_bfe_i32 v248, v171, 2, 1
	v_bfe_i32 v249, v171, 3, 1
	v_bitop3_b32 v34, v34, s96, v178 bitop3:0xe4
	v_bfe_i32 v178, v171, 8, 1
	v_bitop3_b32 v35, v35, s96, v180 bitop3:0xe4
	v_bfe_i32 v180, v171, 9, 1
	v_bitop3_b32 v36, v36, s96, v248 bitop3:0xe4
	v_mfma_f32_32x32x16_bf16 v[50:65], v[134:137], v[118:121], v[50:65]
	v_bfe_i32 v248, v171, 10, 1
	v_bitop3_b32 v37, v37, s96, v249 bitop3:0xe4
	v_bfe_i32 v249, v171, 11, 1
	v_bitop3_b32 v38, v38, s96, v178 bitop3:0xe4
	v_bfe_i32 v178, v171, 16, 1
	v_bitop3_b32 v39, v39, s96, v180 bitop3:0xe4
	v_bfe_i32 v180, v171, 17, 1
	v_bitop3_b32 v40, v40, s96, v248 bitop3:0xe4
	v_bfe_i32 v248, v171, 18, 1
	v_mfma_f32_32x32x16_bf16 v[50:65], v[182:185], v[122:125], v[50:65]
	v_bitop3_b32 v41, v41, s96, v249 bitop3:0xe4
	v_bfe_i32 v249, v171, 19, 1
	v_bitop3_b32 v42, v42, s96, v178 bitop3:0xe4
	v_bfe_i32 v178, v171, 24, 1
	v_bitop3_b32 v43, v43, s96, v180 bitop3:0xe4
	v_bfe_i32 v180, v171, 25, 1
	v_bitop3_b32 v44, v44, s96, v248 bitop3:0xe4
	v_bfe_i32 v248, v171, 26, 1
	v_bitop3_b32 v45, v45, s96, v249 bitop3:0xe4
	v_mfma_f32_32x32x16_bf16 v[50:65], v[186:189], v[126:129], v[50:65]
	v_bfe_i32 v249, v171, 27, 1
	v_bitop3_b32 v46, v46, s96, v178 bitop3:0xe4
	v_bitop3_b32 v47, v47, s96, v180 bitop3:0xe4
	v_bitop3_b32 v48, v48, s96, v248 bitop3:0xe4
	v_bitop3_b32 v49, v49, s96, v249 bitop3:0xe4
	s_add_i32 s26, s8, 2
	s_min_i32 s26, s26, s9
	s_lshl_b32 s27, s26, 12
	s_add_u32 s26, s6, s27
	s_addc_u32 s27, s7, 0
	global_load_dwordx4 v[130:133], v175, s[26:27]
	global_load_dwordx4 v[134:137], v175, s[26:27] offset:1024
	global_load_dwordx4 v[182:185], v175, s[26:27] offset:2048
	global_load_dwordx4 v[186:189], v175, s[26:27] offset:3072
	v_exp_f32_e32 v34, v34
	v_exp_f32_e32 v35, v35
	v_exp_f32_e32 v36, v36
	v_add_f32_e32 v196, v34, v35
	v_exp_f32_e32 v37, v37
	v_add_f32_e32 v196, v196, v36
	v_exp_f32_e32 v38, v38
	v_add_f32_e32 v196, v196, v37
	v_exp_f32_e32 v39, v39
	v_add_f32_e32 v196, v196, v38
	v_exp_f32_e32 v40, v40
	v_add_f32_e32 v196, v196, v39
	v_exp_f32_e32 v41, v41
	v_add_f32_e32 v196, v196, v40
	v_exp_f32_e32 v42, v42
	v_add_f32_e32 v196, v196, v41
	v_exp_f32_e32 v43, v43
	v_add_f32_e32 v196, v196, v42
	v_exp_f32_e32 v44, v44
	v_add_f32_e32 v196, v196, v43
	v_exp_f32_e32 v45, v45
	v_add_f32_e32 v196, v196, v44
	v_exp_f32_e32 v46, v46
	v_add_f32_e32 v196, v196, v45
	v_exp_f32_e32 v47, v47
	v_add_f32_e32 v196, v196, v46
	v_exp_f32_e32 v48, v48
	v_add_f32_e32 v196, v196, v47
	v_exp_f32_e32 v49, v49
	v_add_f32_e32 v196, v196, v48
	s_nop 0
	v_add_f32_e32 v196, v196, v49
	v_add_f32_e32 v167, v167, v196
	v_cvt_pk_bf16_f32 v34, v34, v35
	v_cvt_pk_bf16_f32 v35, v36, v37
	v_cvt_pk_bf16_f32 v36, v38, v39
	v_cvt_pk_bf16_f32 v37, v40, v41
	v_cvt_pk_bf16_f32 v38, v42, v43
	v_cvt_pk_bf16_f32 v39, v44, v45
	v_cvt_pk_bf16_f32 v40, v46, v47
	v_cvt_pk_bf16_f32 v41, v48, v49
	s_waitcnt vmcnt(14)
	v_bfe_i32 v178, v172, 0, 1
	v_bfe_i32 v180, v172, 1, 1
	v_mfma_f32_32x32x16_bf16 v[18:33], v[140:143], v[34:37], v[18:33]
	v_bfe_i32 v248, v172, 2, 1
	v_bfe_i32 v249, v172, 3, 1
	v_bitop3_b32 v50, v50, s96, v178 bitop3:0xe4
	v_bfe_i32 v178, v172, 8, 1
	v_bitop3_b32 v51, v51, s96, v180 bitop3:0xe4
	v_bfe_i32 v180, v172, 9, 1
	v_bitop3_b32 v52, v52, s96, v248 bitop3:0xe4
	v_bfe_i32 v248, v172, 10, 1
	v_mfma_f32_32x32x16_bf16 v[2:17], v[214:217], v[34:37], v[2:17]
	v_bitop3_b32 v53, v53, s96, v249 bitop3:0xe4
	v_bfe_i32 v249, v172, 11, 1
	v_bitop3_b32 v54, v54, s96, v178 bitop3:0xe4
	v_bfe_i32 v178, v172, 16, 1
	v_bitop3_b32 v55, v55, s96, v180 bitop3:0xe4
	v_bfe_i32 v180, v172, 17, 1
	v_bitop3_b32 v56, v56, s96, v248 bitop3:0xe4
	v_bfe_i32 v248, v172, 18, 1
	v_mfma_f32_32x32x16_bf16 v[18:33], v[152:155], v[38:41], v[18:33]
	v_bitop3_b32 v57, v57, s96, v249 bitop3:0xe4
	v_bfe_i32 v249, v172, 19, 1
	v_bitop3_b32 v58, v58, s96, v178 bitop3:0xe4
	v_bfe_i32 v178, v172, 24, 1
	v_bitop3_b32 v59, v59, s96, v180 bitop3:0xe4
	v_bfe_i32 v180, v172, 25, 1
	v_bitop3_b32 v60, v60, s96, v248 bitop3:0xe4
	v_bfe_i32 v248, v172, 26, 1
	v_mfma_f32_32x32x16_bf16 v[2:17], v[236:239], v[38:41], v[2:17]
	v_bitop3_b32 v61, v61, s96, v249 bitop3:0xe4
	v_bfe_i32 v249, v172, 27, 1
	v_bitop3_b32 v62, v62, s96, v178 bitop3:0xe4
	v_bitop3_b32 v63, v63, s96, v180 bitop3:0xe4
	v_bitop3_b32 v64, v64, s96, v248 bitop3:0xe4
	v_bitop3_b32 v65, v65, s96, v249 bitop3:0xe4
	v_exp_f32_e32 v50, v50
	s_waitcnt vmcnt(10)
	v_mfma_f32_32x32x16_bf16 v[34:49], v[66:69], v[82:85], 0
	v_exp_f32_e32 v51, v51
	v_exp_f32_e32 v52, v52
	v_add_f32_e32 v196, v50, v51
	v_exp_f32_e32 v53, v53
	v_add_f32_e32 v196, v196, v52
	v_exp_f32_e32 v54, v54
	v_add_f32_e32 v196, v196, v53
	v_exp_f32_e32 v55, v55
	v_mfma_f32_32x32x16_bf16 v[34:49], v[70:73], v[86:89], v[34:49]
	v_add_f32_e32 v196, v196, v54
	v_exp_f32_e32 v56, v56
	v_add_f32_e32 v196, v196, v55
	v_exp_f32_e32 v57, v57
	v_add_f32_e32 v196, v196, v56
	v_exp_f32_e32 v58, v58
	v_add_f32_e32 v196, v196, v57
	v_exp_f32_e32 v59, v59
	v_mfma_f32_32x32x16_bf16 v[34:49], v[74:77], v[90:93], v[34:49]
	v_add_f32_e32 v196, v196, v58
	v_exp_f32_e32 v60, v60
	v_add_f32_e32 v196, v196, v59
	v_exp_f32_e32 v61, v61
	v_add_f32_e32 v196, v196, v60
	v_exp_f32_e32 v62, v62
	v_add_f32_e32 v196, v196, v61
	v_exp_f32_e32 v63, v63
	v_mfma_f32_32x32x16_bf16 v[34:49], v[78:81], v[94:97], v[34:49]
	v_add_f32_e32 v196, v196, v62
	v_exp_f32_e32 v64, v64
	v_add_f32_e32 v196, v196, v63
	v_exp_f32_e32 v65, v65
	v_add_f32_e32 v196, v196, v64
	s_nop 0
	v_add_f32_e32 v196, v196, v65
	v_add_f32_e32 v169, v169, v196
	v_cvt_pk_bf16_f32 v50, v50, v51
	v_cvt_pk_bf16_f32 v51, v52, v53
	v_cvt_pk_bf16_f32 v52, v54, v55
	v_cvt_pk_bf16_f32 v53, v56, v57
	v_cvt_pk_bf16_f32 v54, v58, v59
	v_cvt_pk_bf16_f32 v55, v60, v61
	v_cvt_pk_bf16_f32 v56, v62, v63
	v_cvt_pk_bf16_f32 v57, v64, v65
	s_add_i32 s8, s8, 1
	s_cmp_lt_i32 s8, s19
	s_cbranch_scc1 .Lat_pb0
	v_mfma_f32_32x32x16_bf16 v[198:213], v[140:143], v[50:53], v[198:213]
	v_mfma_f32_32x32x16_bf16 v[220:235], v[214:217], v[50:53], v[220:235]
	v_mfma_f32_32x32x16_bf16 v[198:213], v[152:155], v[54:57], v[198:213]
	v_mfma_f32_32x32x16_bf16 v[220:235], v[236:239], v[54:57], v[220:235]
	s_branch .Lat_pxd

; __device__ __forceinline__ unsigned cvt_pk_bf16(float lo, float hi) { unsigned r; asm volatile("v_cvt_pk_bf16_f32 %0, %1, %2" : "=v"(r) : "v"(lo), "v"(hi)); return r; }
; __device__ __forceinline__ float bf2f(unsigned short h) { return __uint_as_float((unsigned)h << 16); }
; __device__ __forceinline__ void mixer_bd(const bf16_t* __restrict__ Z, bf16_t* __restrict__ Y, const float* __restrict__ lng, const float* __restrict__ lnb, const float* __restrict__ wsp, const float* __restrict__ bsp, ...
;     ...
;         for (int k = 0; k < 16; ++k) {
;             const int s = wave * 16 + k; const bf16_t* zr = Z + (row0 + s) * NZ + 4 * 256;
;             const float v0 = bf2f(zr[lane]), v1 = bf2f(zr[lane + 64]), v2 = bf2f(zr[lane + 128]), v3 = bf2f(zr[lane + 192]);
;             const float mean = wave_sum((v0 + v1) + (v2 + v3)) * (1.f / 256.f);
;             const float d0 = v0 - mean, d1 = v1 - mean, d2 = v2 - mean, d3 = v3 - mean;
;             const float var = wave_sum((d0 * d0 + d1 * d1) + (d2 * d2 + d3 * d3)) * (1.f / 256.f);
;             const float rstd = __builtin_amdgcn_rsqf(var + 1e-5f);
;             const int ca = hf * 128 + lane, cb = ca + 64;
;             const float a = (hf ? d2 : d0) * rstd * lng[ca] + lnb[ca], b = (hf ? d3 : d1) * rstd * lng[cb] + lnb[cb];
;             const unsigned pk = cvt_pk_bf16(a, b);
;             vt[lane * VP + s] = (bf16_t)(pk & 0xffffu); vt[(lane + 64) * VP + s] = (bf16_t)(pk >> 16);
;         }
.LBB0_249:
	s_nop 0
	v_lshl_add_u64 v[44:45], v[42:43], 0, s[72:73]
	s_mov_b32 s82, 0x8400000
	v_lshl_add_u64 v[198:199], v[44:45], 0, s[82:83]
	s_mov_b32 s82, 0x8402000
	v_lshl_add_u64 v[200:201], v[44:45], 0, s[82:83]
	s_mov_b32 s82, 0x8403000
	v_lshl_add_u64 v[202:203], v[44:45], 0, s[82:83]
	s_mov_b32 s82, 0x8405000
	v_lshl_add_u64 v[204:205], v[44:45], 0, s[82:83]
	s_mov_b32 s82, 0x8406000
	v_lshl_add_u64 v[206:207], v[44:45], 0, s[82:83]
	s_mov_b32 s82, 0x8408000
	v_lshl_add_u64 v[208:209], v[44:45], 0, s[82:83]
	s_mov_b32 s82, 0x8409000
	v_lshl_add_u64 v[210:211], v[44:45], 0, s[82:83]
	s_mov_b32 s82, 0x840b000
	v_lshl_add_u64 v[212:213], v[44:45], 0, s[82:83]
	global_load_ushort v214, v[198:199], off offset:2048
	global_load_ushort v215, v[198:199], off offset:2176
	global_load_ushort v216, v[198:199], off offset:2304
	global_load_ushort v217, v[198:199], off offset:2432
	global_load_ushort v219, v[200:201], off
	global_load_ushort v220, v[200:201], off offset:128
	global_load_ushort v221, v[200:201], off offset:256
	global_load_ushort v222, v[200:201], off offset:384
	global_load_ushort v223, v[202:203], off offset:2048
	global_load_ushort v224, v[202:203], off offset:2176
	global_load_ushort v225, v[202:203], off offset:2304
	global_load_ushort v226, v[202:203], off offset:2432
	global_load_ushort v227, v[204:205], off
	global_load_ushort v228, v[204:205], off offset:256
	global_load_ushort v229, v[204:205], off offset:128
	global_load_ushort v230, v[204:205], off offset:384
	global_load_ushort v231, v[206:207], off offset:2048
	global_load_ushort v232, v[206:207], off offset:2176
	global_load_ushort v233, v[206:207], off offset:2304
	global_load_ushort v234, v[206:207], off offset:2432
	global_load_ushort v235, v[208:209], off
	global_load_ushort v236, v[208:209], off offset:128
	global_load_ushort v237, v[208:209], off offset:256
	global_load_ushort v238, v[208:209], off offset:384
	global_load_ushort v239, v[210:211], off offset:2048
	global_load_ushort v243, v[210:211], off offset:2176
	global_load_ushort v244, v[210:211], off offset:2304
	global_load_ushort v245, v[210:211], off offset:2432
	global_load_ushort v246, v[212:213], off
	global_load_ushort v248, v[212:213], off offset:128
	global_load_ushort v249, v[212:213], off offset:256
	global_load_ushort v250, v[212:213], off offset:384
	v_add_co_u32_e32 v86, vcc, 0x8400000, v44
	s_add_u32 s72, s72, 0xc000
	s_nop 0
	v_addc_co_u32_e32 v87, vcc, 0, v45, vcc
	s_waitcnt vmcnt(28)
	v_mov_b32_e32 v65, v214
	v_mov_b32_e32 v67, v215
	v_mov_b32_e32 v88, v216
	s_addc_u32 s73, s73, 0
	v_mov_b32_e32 v86, v217
	s_cmp_eq_u32 s72, 0x18000
	v_lshlrev_b32_e32 v65, 16, v65
	v_lshlrev_b32_e32 v67, 16, v67
	v_lshlrev_b32_e32 v88, 16, v88
	v_add_f32_e32 v87, v65, v67
	v_lshlrev_b32_e32 v86, 16, v86
	v_add_f32_e32 v140, v88, v86
	v_add_f32_e32 v87, v87, v140
	v_mov_b32_e32 v140, 0
	s_nop 0
	v_add_f32_dpp v87, v87, v87 row_shr:1 row_mask:0xf bank_mask:0xf bound_ctrl:1
	s_nop 1
	v_add_f32_dpp v87, v87, v87 row_shr:2 row_mask:0xf bank_mask:0xf bound_ctrl:1
	s_nop 1
	v_add_f32_dpp v87, v87, v87 row_shr:4 row_mask:0xf bank_mask:0xf bound_ctrl:1
	s_nop 1
	v_add_f32_dpp v87, v87, v87 row_shr:8 row_mask:0xf bank_mask:0xf bound_ctrl:1
	s_nop 1
	v_mov_b32_dpp v140, v87 row_bcast:15 row_mask:0xa bank_mask:0xf
	v_add_f32_e32 v87, v87, v140
	v_mov_b32_e32 v140, 0
	s_nop 1
	v_mov_b32_dpp v140, v87 row_bcast:31 row_mask:0xc bank_mask:0xf
	v_add_f32_e32 v87, v87, v140
	s_nop 0
	v_readlane_b32 s82, v87, 63
	s_nop 1
	v_fmac_f32_e32 v67, s82, v241
	v_fmac_f32_e32 v86, s82, v241
	v_fmac_f32_e32 v65, s82, v241
	v_fmac_f32_e32 v88, s82, v241
	v_mul_f32_e32 v87, v67, v67
	v_mul_f32_e32 v140, v86, v86
	v_fmac_f32_e32 v87, v65, v65
	v_fmac_f32_e32 v140, v88, v88
	v_add_f32_e32 v87, v87, v140
	v_mov_b32_e32 v140, 0
	v_cndmask_b32_e64 v65, v88, v65, s[70:71]
	v_add_f32_dpp v87, v87, v87 row_shr:1 row_mask:0xf bank_mask:0xf bound_ctrl:1
	v_cndmask_b32_e64 v67, v86, v67, s[70:71]
	s_nop 0
	v_add_f32_dpp v87, v87, v87 row_shr:2 row_mask:0xf bank_mask:0xf bound_ctrl:1
	s_nop 1
	v_add_f32_dpp v87, v87, v87 row_shr:4 row_mask:0xf bank_mask:0xf bound_ctrl:1
	s_nop 1
	v_add_f32_dpp v87, v87, v87 row_shr:8 row_mask:0xf bank_mask:0xf bound_ctrl:1
	s_nop 1
	v_mov_b32_dpp v140, v87 row_bcast:15 row_mask:0xa bank_mask:0xf
	v_add_f32_e32 v87, v87, v140
	v_mov_b32_e32 v140, 0
	s_nop 1
	v_mov_b32_dpp v140, v87 row_bcast:31 row_mask:0xc bank_mask:0xf
	v_add_f32_e32 v87, v87, v140
	s_nop 0
	v_readlane_b32 s82, v87, 63
	s_nop 1
	v_fma_f32 v87, s82, v242, v197
	v_rsq_f32_e32 v87, v87
	s_mov_b32 s82, 0x8402000
	v_add_co_u32_e32 v86, vcc, s82, v44
	v_mul_f32_e32 v65, v65, v87
	v_fma_f32 v65, v46, v65, v47
	v_mul_f32_e32 v67, v67, v87
	v_fma_f32 v67, v48, v67, v49
	v_cvt_pk_bf16_f32 v65, v65, v67
	ds_write_b16 v63, v65
	ds_write_b16_d16_hi v63, v65 offset:16896
	v_addc_co_u32_e32 v87, vcc, 0, v45, vcc
	s_waitcnt vmcnt(24)
; __device__ __forceinline__ unsigned cvt_pk_bf16(float lo, float hi) { unsigned r; asm volatile("v_cvt_pk_bf16_f32 %0, %1, %2" : "=v"(r) : "v"(lo), "v"(hi)); return r; }
; __device__ __forceinline__ float bf2f(unsigned short h) { return __uint_as_float((unsigned)h << 16); }
; __device__ __forceinline__ void mixer_bd(const bf16_t* __restrict__ Z, bf16_t* __restrict__ Y, const float* __restrict__ lng, const float* __restrict__ lnb, const float* __restrict__ wsp, const float* __restrict__ bsp, ...
;     ...
;         for (int k = 0; k < 16; ++k) {
;             const int s = wave * 16 + k; const bf16_t* zr = Z + (row0 + s) * NZ + 4 * 256;
;             const float v0 = bf2f(zr[lane]), v1 = bf2f(zr[lane + 64]), v2 = bf2f(zr[lane + 128]), v3 = bf2f(zr[lane + 192]);
;             const float mean = wave_sum((v0 + v1) + (v2 + v3)) * (1.f / 256.f);
;             const float d0 = v0 - mean, d1 = v1 - mean, d2 = v2 - mean, d3 = v3 - mean;
;             const float var = wave_sum((d0 * d0 + d1 * d1) + (d2 * d2 + d3 * d3)) * (1.f / 256.f);
;             const float rstd = __builtin_amdgcn_rsqf(var + 1e-5f);
;             const int ca = hf * 128 + lane, cb = ca + 64;
;             const float a = (hf ? d2 : d0) * rstd * lng[ca] + lnb[ca], b = (hf ? d3 : d1) * rstd * lng[cb] + lnb[cb];
;             const unsigned pk = cvt_pk_bf16(a, b);
;             vt[lane * VP + s] = (bf16_t)(pk & 0xffffu); vt[(lane + 64) * VP + s] = (bf16_t)(pk >> 16);
;         }
	v_mov_b32_e32 v65, v219
	v_mov_b32_e32 v67, v220
	v_mov_b32_e32 v88, v221
	v_lshlrev_b32_e32 v65, 16, v65
	v_mov_b32_e32 v86, v222
	v_lshlrev_b32_e32 v67, 16, v67
	v_lshlrev_b32_e32 v88, 16, v88
	v_add_f32_e32 v87, v65, v67
	v_lshlrev_b32_e32 v86, 16, v86
	v_add_f32_e32 v140, v88, v86
	v_add_f32_e32 v87, v87, v140
	v_mov_b32_e32 v140, 0
	s_nop 0
	v_add_f32_dpp v87, v87, v87 row_shr:1 row_mask:0xf bank_mask:0xf bound_ctrl:1
	s_nop 1
	v_add_f32_dpp v87, v87, v87 row_shr:2 row_mask:0xf bank_mask:0xf bound_ctrl:1
	s_nop 1
	v_add_f32_dpp v87, v87, v87 row_shr:4 row_mask:0xf bank_mask:0xf bound_ctrl:1
	s_nop 1
	v_add_f32_dpp v87, v87, v87 row_shr:8 row_mask:0xf bank_mask:0xf bound_ctrl:1
	s_nop 1
	v_mov_b32_dpp v140, v87 row_bcast:15 row_mask:0xa bank_mask:0xf
	v_add_f32_e32 v87, v87, v140
	v_mov_b32_e32 v140, 0
	s_nop 1
	v_mov_b32_dpp v140, v87 row_bcast:31 row_mask:0xc bank_mask:0xf
	v_add_f32_e32 v87, v87, v140
	s_nop 0
	v_readlane_b32 s82, v87, 63
	s_nop 1
	v_fmac_f32_e32 v67, s82, v241
	v_fmac_f32_e32 v86, s82, v241
	v_fmac_f32_e32 v65, s82, v241
	v_fmac_f32_e32 v88, s82, v241
	v_mul_f32_e32 v87, v67, v67
	v_mul_f32_e32 v140, v86, v86
	v_fmac_f32_e32 v87, v65, v65
	v_fmac_f32_e32 v140, v88, v88
	v_add_f32_e32 v87, v87, v140
	v_mov_b32_e32 v140, 0
	v_cndmask_b32_e64 v65, v88, v65, s[70:71]
	v_add_f32_dpp v87, v87, v87 row_shr:1 row_mask:0xf bank_mask:0xf bound_ctrl:1
	v_cndmask_b32_e64 v67, v86, v67, s[70:71]
	s_nop 0
	v_add_f32_dpp v87, v87, v87 row_shr:2 row_mask:0xf bank_mask:0xf bound_ctrl:1
	s_nop 1
	v_add_f32_dpp v87, v87, v87 row_shr:4 row_mask:0xf bank_mask:0xf bound_ctrl:1
	s_nop 1
	v_add_f32_dpp v87, v87, v87 row_shr:8 row_mask:0xf bank_mask:0xf bound_ctrl:1
	s_nop 1
	v_mov_b32_dpp v140, v87 row_bcast:15 row_mask:0xa bank_mask:0xf
	v_add_f32_e32 v87, v87, v140
	v_mov_b32_e32 v140, 0
	s_nop 1
	v_mov_b32_dpp v140, v87 row_bcast:31 row_mask:0xc bank_mask:0xf
	v_add_f32_e32 v87, v87, v140
	s_nop 0
	v_readlane_b32 s82, v87, 63
	s_nop 1
	v_fma_f32 v87, s82, v242, v197
	v_rsq_f32_e32 v87, v87
	s_mov_b32 s82, 0x8403000
	v_add_co_u32_e32 v86, vcc, s82, v44
	v_mul_f32_e32 v65, v65, v87
	v_fma_f32 v65, v46, v65, v47
	v_mul_f32_e32 v67, v67, v87
	v_fma_f32 v67, v48, v67, v49
	v_cvt_pk_bf16_f32 v65, v65, v67
	ds_write_b16 v63, v65 offset:2
	ds_write_b16_d16_hi v63, v65 offset:16898
	v_addc_co_u32_e32 v87, vcc, 0, v45, vcc
	s_waitcnt vmcnt(20)
	v_mov_b32_e32 v65, v223
	v_mov_b32_e32 v67, v224
	v_mov_b32_e32 v88, v225
	v_lshlrev_b32_e32 v65, 16, v65
	v_mov_b32_e32 v86, v226
	v_lshlrev_b32_e32 v67, 16, v67
	v_lshlrev_b32_e32 v88, 16, v88
	v_add_f32_e32 v87, v65, v67
	v_lshlrev_b32_e32 v86, 16, v86
	v_add_f32_e32 v140, v88, v86
	v_add_f32_e32 v87, v87, v140
	v_mov_b32_e32 v140, 0
	s_nop 0
	v_add_f32_dpp v87, v87, v87 row_shr:1 row_mask:0xf bank_mask:0xf bound_ctrl:1
	s_nop 1
	v_add_f32_dpp v87, v87, v87 row_shr:2 row_mask:0xf bank_mask:0xf bound_ctrl:1
	s_nop 1
	v_add_f32_dpp v87, v87, v87 row_shr:4 row_mask:0xf bank_mask:0xf bound_ctrl:1
	s_nop 1
	v_add_f32_dpp v87, v87, v87 row_shr:8 row_mask:0xf bank_mask:0xf bound_ctrl:1
	s_nop 1
	v_mov_b32_dpp v140, v87 row_bcast:15 row_mask:0xa bank_mask:0xf
	v_add_f32_e32 v87, v87, v140
	v_mov_b32_e32 v140, 0
	s_nop 1
	v_mov_b32_dpp v140, v87 row_bcast:31 row_mask:0xc bank_mask:0xf
	v_add_f32_e32 v87, v87, v140
	s_nop 0
	v_readlane_b32 s82, v87, 63
	s_nop 1
	v_fmac_f32_e32 v67, s82, v241
	v_fmac_f32_e32 v86, s82, v241
	v_fmac_f32_e32 v65, s82, v241
	v_fmac_f32_e32 v88, s82, v241
	v_mul_f32_e32 v87, v67, v67
	v_mul_f32_e32 v140, v86, v86
	v_fmac_f32_e32 v87, v65, v65
	v_fmac_f32_e32 v140, v88, v88
	v_add_f32_e32 v87, v87, v140
	v_mov_b32_e32 v140, 0
	v_cndmask_b32_e64 v65, v88, v65, s[70:71]
	v_add_f32_dpp v87, v87, v87 row_shr:1 row_mask:0xf bank_mask:0xf bound_ctrl:1
	v_cndmask_b32_e64 v67, v86, v67, s[70:71]
	s_nop 0
	v_add_f32_dpp v87, v87, v87 row_shr:2 row_mask:0xf bank_mask:0xf bound_ctrl:1
	s_nop 1
	v_add_f32_dpp v87, v87, v87 row_shr:4 row_mask:0xf bank_mask:0xf bound_ctrl:1
	s_nop 1
	v_add_f32_dpp v87, v87, v87 row_shr:8 row_mask:0xf bank_mask:0xf bound_ctrl:1
	s_nop 1
	v_mov_b32_dpp v140, v87 row_bcast:15 row_mask:0xa bank_mask:0xf
	v_add_f32_e32 v87, v87, v140
	v_mov_b32_e32 v140, 0
	s_nop 1
	v_mov_b32_dpp v140, v87 row_bcast:31 row_mask:0xc bank_mask:0xf
	v_add_f32_e32 v87, v87, v140
	s_nop 0
	v_readlane_b32 s82, v87, 63
	s_nop 1
	v_fma_f32 v87, s82, v242, v197
	v_rsq_f32_e32 v87, v87
	s_mov_b32 s82, 0x8405000
	v_add_co_u32_e32 v140, vcc, s82, v44
	v_mul_f32_e32 v65, v65, v87
	v_fma_f32 v65, v46, v65, v47
	v_mul_f32_e32 v67, v67, v87
	v_fma_f32 v67, v48, v67, v49
	v_cvt_pk_bf16_f32 v65, v65, v67
	ds_write_b16 v63, v65 offset:4
	ds_write_b16_d16_hi v63, v65 offset:16900
	v_addc_co_u32_e32 v141, vcc, 0, v45, vcc
	s_waitcnt vmcnt(16)
; __device__ __forceinline__ unsigned cvt_pk_bf16(float lo, float hi) { unsigned r; asm volatile("v_cvt_pk_bf16_f32 %0, %1, %2" : "=v"(r) : "v"(lo), "v"(hi)); return r; }
; __device__ __forceinline__ float bf2f(unsigned short h) { return __uint_as_float((unsigned)h << 16); }
; __device__ __forceinline__ void mixer_bd(const bf16_t* __restrict__ Z, bf16_t* __restrict__ Y, const float* __restrict__ lng, const float* __restrict__ lnb, const float* __restrict__ wsp, const float* __restrict__ bsp, ...
;     ...
;         for (int k = 0; k < 16; ++k) {
;             const int s = wave * 16 + k; const bf16_t* zr = Z + (row0 + s) * NZ + 4 * 256;
;             const float v0 = bf2f(zr[lane]), v1 = bf2f(zr[lane + 64]), v2 = bf2f(zr[lane + 128]), v3 = bf2f(zr[lane + 192]);
;             const float mean = wave_sum((v0 + v1) + (v2 + v3)) * (1.f / 256.f);
;             const float d0 = v0 - mean, d1 = v1 - mean, d2 = v2 - mean, d3 = v3 - mean;
;             const float var = wave_sum((d0 * d0 + d1 * d1) + (d2 * d2 + d3 * d3)) * (1.f / 256.f);
;             const float rstd = __builtin_amdgcn_rsqf(var + 1e-5f);
;             const int ca = hf * 128 + lane, cb = ca + 64;
;             const float a = (hf ? d2 : d0) * rstd * lng[ca] + lnb[ca], b = (hf ? d3 : d1) * rstd * lng[cb] + lnb[cb];
;             const unsigned pk = cvt_pk_bf16(a, b);
;             vt[lane * VP + s] = (bf16_t)(pk & 0xffffu); vt[(lane + 64) * VP + s] = (bf16_t)(pk >> 16);
;         }
	v_mov_b32_e32 v65, v227
	v_mov_b32_e32 v86, v228
	v_lshlrev_b32_e32 v67, 16, v65
	v_mov_b32_e32 v65, v229
	v_lshlrev_b32_e32 v87, 16, v86
	v_mov_b32_e32 v86, v230
	v_lshlrev_b32_e32 v65, 16, v65
	v_add_f32_e32 v88, v67, v65
	v_lshlrev_b32_e32 v86, 16, v86
	v_add_f32_e32 v140, v87, v86
	v_add_f32_e32 v88, v88, v140
	v_mov_b32_e32 v140, 0
	s_nop 0
	v_add_f32_dpp v88, v88, v88 row_shr:1 row_mask:0xf bank_mask:0xf bound_ctrl:1
	s_nop 1
	v_add_f32_dpp v88, v88, v88 row_shr:2 row_mask:0xf bank_mask:0xf bound_ctrl:1
	s_nop 1
	v_add_f32_dpp v88, v88, v88 row_shr:4 row_mask:0xf bank_mask:0xf bound_ctrl:1
	s_nop 1
	v_add_f32_dpp v88, v88, v88 row_shr:8 row_mask:0xf bank_mask:0xf bound_ctrl:1
	s_nop 1
	v_mov_b32_dpp v140, v88 row_bcast:15 row_mask:0xa bank_mask:0xf
	v_add_f32_e32 v88, v88, v140
	v_mov_b32_e32 v140, 0
	s_nop 1
	v_mov_b32_dpp v140, v88 row_bcast:31 row_mask:0xc bank_mask:0xf
	v_add_f32_e32 v88, v88, v140
	s_nop 0
	v_readlane_b32 s82, v88, 63
	s_nop 1
	v_fmac_f32_e32 v65, s82, v241
	v_fmac_f32_e32 v86, s82, v241
	v_fmac_f32_e32 v67, s82, v241
	v_fmac_f32_e32 v87, s82, v241
	v_mul_f32_e32 v88, v65, v65
	v_mul_f32_e32 v140, v86, v86
	v_fmac_f32_e32 v88, v67, v67
	v_fmac_f32_e32 v140, v87, v87
	v_add_f32_e32 v88, v88, v140
	v_mov_b32_e32 v140, 0
	v_cndmask_b32_e64 v65, v86, v65, s[70:71]
	v_add_f32_dpp v88, v88, v88 row_shr:1 row_mask:0xf bank_mask:0xf bound_ctrl:1
	v_cndmask_b32_e64 v67, v87, v67, s[70:71]
	s_nop 0
	v_add_f32_dpp v88, v88, v88 row_shr:2 row_mask:0xf bank_mask:0xf bound_ctrl:1
	s_nop 1
	v_add_f32_dpp v88, v88, v88 row_shr:4 row_mask:0xf bank_mask:0xf bound_ctrl:1
	s_nop 1
	v_add_f32_dpp v88, v88, v88 row_shr:8 row_mask:0xf bank_mask:0xf bound_ctrl:1
	s_nop 1
	v_mov_b32_dpp v140, v88 row_bcast:15 row_mask:0xa bank_mask:0xf
	v_add_f32_e32 v88, v88, v140
	v_mov_b32_e32 v140, 0
	s_nop 1
	v_mov_b32_dpp v140, v88 row_bcast:31 row_mask:0xc bank_mask:0xf
	v_add_f32_e32 v88, v88, v140
	s_nop 0
	v_readlane_b32 s82, v88, 63
	s_nop 1
	v_fma_f32 v88, s82, v242, v197
	v_rsq_f32_e32 v88, v88
	s_mov_b32 s82, 0x8406000
	v_add_co_u32_e32 v86, vcc, s82, v44
	v_mul_f32_e32 v65, v65, v88
	v_mul_f32_e32 v67, v67, v88
	v_fma_f32 v65, v48, v65, v49
	v_fma_f32 v67, v46, v67, v47
	v_cvt_pk_bf16_f32 v65, v67, v65
	ds_write_b16 v63, v65 offset:6
	ds_write_b16_d16_hi v63, v65 offset:16902
	v_addc_co_u32_e32 v87, vcc, 0, v45, vcc
	s_waitcnt vmcnt(12)
	v_mov_b32_e32 v65, v231
	v_mov_b32_e32 v67, v232
	v_mov_b32_e32 v88, v233
	v_lshlrev_b32_e32 v65, 16, v65
	v_mov_b32_e32 v86, v234
	v_lshlrev_b32_e32 v67, 16, v67
	v_lshlrev_b32_e32 v88, 16, v88
	v_add_f32_e32 v87, v65, v67
	v_lshlrev_b32_e32 v86, 16, v86
	v_add_f32_e32 v140, v88, v86
	v_add_f32_e32 v87, v87, v140
	v_mov_b32_e32 v140, 0
	s_nop 0
	v_add_f32_dpp v87, v87, v87 row_shr:1 row_mask:0xf bank_mask:0xf bound_ctrl:1
	s_nop 1
	v_add_f32_dpp v87, v87, v87 row_shr:2 row_mask:0xf bank_mask:0xf bound_ctrl:1
	s_nop 1
	v_add_f32_dpp v87, v87, v87 row_shr:4 row_mask:0xf bank_mask:0xf bound_ctrl:1
	s_nop 1
	v_add_f32_dpp v87, v87, v87 row_shr:8 row_mask:0xf bank_mask:0xf bound_ctrl:1
	s_nop 1
	v_mov_b32_dpp v140, v87 row_bcast:15 row_mask:0xa bank_mask:0xf
	v_add_f32_e32 v87, v87, v140
	v_mov_b32_e32 v140, 0
	s_nop 1
	v_mov_b32_dpp v140, v87 row_bcast:31 row_mask:0xc bank_mask:0xf
	v_add_f32_e32 v87, v87, v140
	s_nop 0
	v_readlane_b32 s82, v87, 63
	s_nop 1
	v_fmac_f32_e32 v67, s82, v241
	v_fmac_f32_e32 v86, s82, v241
	v_fmac_f32_e32 v65, s82, v241
	v_fmac_f32_e32 v88, s82, v241
	v_mul_f32_e32 v87, v67, v67
	v_mul_f32_e32 v140, v86, v86
	v_fmac_f32_e32 v87, v65, v65
	v_fmac_f32_e32 v140, v88, v88
	v_add_f32_e32 v87, v87, v140
	v_mov_b32_e32 v140, 0
	v_cndmask_b32_e64 v65, v88, v65, s[70:71]
	v_add_f32_dpp v87, v87, v87 row_shr:1 row_mask:0xf bank_mask:0xf bound_ctrl:1
	v_cndmask_b32_e64 v67, v86, v67, s[70:71]
	s_nop 0
	v_add_f32_dpp v87, v87, v87 row_shr:2 row_mask:0xf bank_mask:0xf bound_ctrl:1
	s_nop 1
	v_add_f32_dpp v87, v87, v87 row_shr:4 row_mask:0xf bank_mask:0xf bound_ctrl:1
	s_nop 1
	v_add_f32_dpp v87, v87, v87 row_shr:8 row_mask:0xf bank_mask:0xf bound_ctrl:1
	s_nop 1
	v_mov_b32_dpp v140, v87 row_bcast:15 row_mask:0xa bank_mask:0xf
	v_add_f32_e32 v87, v87, v140
	v_mov_b32_e32 v140, 0
	s_nop 1
	v_mov_b32_dpp v140, v87 row_bcast:31 row_mask:0xc bank_mask:0xf
	v_add_f32_e32 v87, v87, v140
	s_nop 0
	v_readlane_b32 s82, v87, 63
	s_nop 1
	v_fma_f32 v87, s82, v242, v197
	v_rsq_f32_e32 v87, v87
	s_mov_b32 s82, 0x8408000
	v_add_co_u32_e32 v86, vcc, s82, v44
	v_mul_f32_e32 v65, v65, v87
	v_fma_f32 v65, v46, v65, v47
	v_mul_f32_e32 v67, v67, v87
	v_fma_f32 v67, v48, v67, v49
	v_cvt_pk_bf16_f32 v65, v65, v67
	ds_write_b16 v63, v65 offset:8
	ds_write_b16_d16_hi v63, v65 offset:16904
	v_addc_co_u32_e32 v87, vcc, 0, v45, vcc
	s_waitcnt vmcnt(8)
; __device__ __forceinline__ unsigned cvt_pk_bf16(float lo, float hi) { unsigned r; asm volatile("v_cvt_pk_bf16_f32 %0, %1, %2" : "=v"(r) : "v"(lo), "v"(hi)); return r; }
; __device__ __forceinline__ float bf2f(unsigned short h) { return __uint_as_float((unsigned)h << 16); }
; __device__ __forceinline__ void mixer_bd(const bf16_t* __restrict__ Z, bf16_t* __restrict__ Y, const float* __restrict__ lng, const float* __restrict__ lnb, const float* __restrict__ wsp, const float* __restrict__ bsp, ...
;     ...
;         for (int k = 0; k < 16; ++k) {
;             const int s = wave * 16 + k; const bf16_t* zr = Z + (row0 + s) * NZ + 4 * 256;
;             const float v0 = bf2f(zr[lane]), v1 = bf2f(zr[lane + 64]), v2 = bf2f(zr[lane + 128]), v3 = bf2f(zr[lane + 192]);
;             const float mean = wave_sum((v0 + v1) + (v2 + v3)) * (1.f / 256.f);
;             const float d0 = v0 - mean, d1 = v1 - mean, d2 = v2 - mean, d3 = v3 - mean;
;             const float var = wave_sum((d0 * d0 + d1 * d1) + (d2 * d2 + d3 * d3)) * (1.f / 256.f);
;             const float rstd = __builtin_amdgcn_rsqf(var + 1e-5f);
;             const int ca = hf * 128 + lane, cb = ca + 64;
;             const float a = (hf ? d2 : d0) * rstd * lng[ca] + lnb[ca], b = (hf ? d3 : d1) * rstd * lng[cb] + lnb[cb];
;             const unsigned pk = cvt_pk_bf16(a, b);
;             vt[lane * VP + s] = (bf16_t)(pk & 0xffffu); vt[(lane + 64) * VP + s] = (bf16_t)(pk >> 16);
;         }
	v_mov_b32_e32 v65, v235
	v_mov_b32_e32 v67, v236
	v_mov_b32_e32 v88, v237
	v_lshlrev_b32_e32 v65, 16, v65
	v_mov_b32_e32 v86, v238
	v_lshlrev_b32_e32 v67, 16, v67
	v_lshlrev_b32_e32 v88, 16, v88
	v_add_f32_e32 v87, v65, v67
	v_lshlrev_b32_e32 v86, 16, v86
	v_add_f32_e32 v140, v88, v86
	v_add_f32_e32 v87, v87, v140
	v_mov_b32_e32 v140, 0
	s_nop 0
	v_add_f32_dpp v87, v87, v87 row_shr:1 row_mask:0xf bank_mask:0xf bound_ctrl:1
	s_nop 1
	v_add_f32_dpp v87, v87, v87 row_shr:2 row_mask:0xf bank_mask:0xf bound_ctrl:1
	s_nop 1
	v_add_f32_dpp v87, v87, v87 row_shr:4 row_mask:0xf bank_mask:0xf bound_ctrl:1
	s_nop 1
	v_add_f32_dpp v87, v87, v87 row_shr:8 row_mask:0xf bank_mask:0xf bound_ctrl:1
	s_nop 1
	v_mov_b32_dpp v140, v87 row_bcast:15 row_mask:0xa bank_mask:0xf
	v_add_f32_e32 v87, v87, v140
	v_mov_b32_e32 v140, 0
	s_nop 1
	v_mov_b32_dpp v140, v87 row_bcast:31 row_mask:0xc bank_mask:0xf
	v_add_f32_e32 v87, v87, v140
	s_nop 0
	v_readlane_b32 s82, v87, 63
	s_nop 1
	v_fmac_f32_e32 v67, s82, v241
	v_fmac_f32_e32 v86, s82, v241
	v_fmac_f32_e32 v65, s82, v241
	v_fmac_f32_e32 v88, s82, v241
	v_mul_f32_e32 v87, v67, v67
	v_mul_f32_e32 v140, v86, v86
	v_fmac_f32_e32 v87, v65, v65
	v_fmac_f32_e32 v140, v88, v88
	v_add_f32_e32 v87, v87, v140
	v_mov_b32_e32 v140, 0
	v_cndmask_b32_e64 v65, v88, v65, s[70:71]
	v_add_f32_dpp v87, v87, v87 row_shr:1 row_mask:0xf bank_mask:0xf bound_ctrl:1
	v_cndmask_b32_e64 v67, v86, v67, s[70:71]
	s_nop 0
	v_add_f32_dpp v87, v87, v87 row_shr:2 row_mask:0xf bank_mask:0xf bound_ctrl:1
	s_nop 1
	v_add_f32_dpp v87, v87, v87 row_shr:4 row_mask:0xf bank_mask:0xf bound_ctrl:1
	s_nop 1
	v_add_f32_dpp v87, v87, v87 row_shr:8 row_mask:0xf bank_mask:0xf bound_ctrl:1
	s_nop 1
	v_mov_b32_dpp v140, v87 row_bcast:15 row_mask:0xa bank_mask:0xf
	v_add_f32_e32 v87, v87, v140
	v_mov_b32_e32 v140, 0
	s_nop 1
	v_mov_b32_dpp v140, v87 row_bcast:31 row_mask:0xc bank_mask:0xf
	v_add_f32_e32 v87, v87, v140
	s_nop 0
	v_readlane_b32 s82, v87, 63
	s_nop 1
	v_fma_f32 v87, s82, v242, v197
	v_rsq_f32_e32 v87, v87
	s_mov_b32 s82, 0x8409000
	v_add_co_u32_e32 v86, vcc, s82, v44
	v_mul_f32_e32 v65, v65, v87
	v_fma_f32 v65, v46, v65, v47
	v_mul_f32_e32 v67, v67, v87
	v_fma_f32 v67, v48, v67, v49
	v_cvt_pk_bf16_f32 v65, v65, v67
	ds_write_b16 v63, v65 offset:10
	ds_write_b16_d16_hi v63, v65 offset:16906
	v_addc_co_u32_e32 v87, vcc, 0, v45, vcc
	s_waitcnt vmcnt(4)
	v_mov_b32_e32 v65, v239
	v_mov_b32_e32 v67, v243
	v_mov_b32_e32 v88, v244
	v_lshlrev_b32_e32 v65, 16, v65
	v_mov_b32_e32 v86, v245
	v_lshlrev_b32_e32 v67, 16, v67
	v_lshlrev_b32_e32 v88, 16, v88
	v_add_f32_e32 v87, v65, v67
	v_lshlrev_b32_e32 v86, 16, v86
	v_add_f32_e32 v140, v88, v86
	v_add_f32_e32 v87, v87, v140
	v_mov_b32_e32 v140, 0
	s_nop 0
	v_add_f32_dpp v87, v87, v87 row_shr:1 row_mask:0xf bank_mask:0xf bound_ctrl:1
	s_nop 1
	v_add_f32_dpp v87, v87, v87 row_shr:2 row_mask:0xf bank_mask:0xf bound_ctrl:1
	s_nop 1
	v_add_f32_dpp v87, v87, v87 row_shr:4 row_mask:0xf bank_mask:0xf bound_ctrl:1
	s_nop 1
	v_add_f32_dpp v87, v87, v87 row_shr:8 row_mask:0xf bank_mask:0xf bound_ctrl:1
	s_nop 1
	v_mov_b32_dpp v140, v87 row_bcast:15 row_mask:0xa bank_mask:0xf
	v_add_f32_e32 v87, v87, v140
	v_mov_b32_e32 v140, 0
	s_nop 1
	v_mov_b32_dpp v140, v87 row_bcast:31 row_mask:0xc bank_mask:0xf
	v_add_f32_e32 v87, v87, v140
	s_nop 0
	v_readlane_b32 s82, v87, 63
	s_nop 1
	v_fmac_f32_e32 v67, s82, v241
	v_fmac_f32_e32 v86, s82, v241
	v_fmac_f32_e32 v65, s82, v241
	v_fmac_f32_e32 v88, s82, v241
	v_mul_f32_e32 v87, v67, v67
	v_mul_f32_e32 v140, v86, v86
	v_fmac_f32_e32 v87, v65, v65
	v_fmac_f32_e32 v140, v88, v88
	v_add_f32_e32 v87, v87, v140
	v_mov_b32_e32 v140, 0
	v_cndmask_b32_e64 v65, v88, v65, s[70:71]
	v_add_f32_dpp v87, v87, v87 row_shr:1 row_mask:0xf bank_mask:0xf bound_ctrl:1
	v_cndmask_b32_e64 v67, v86, v67, s[70:71]
	s_nop 0
	v_add_f32_dpp v87, v87, v87 row_shr:2 row_mask:0xf bank_mask:0xf bound_ctrl:1
	s_nop 1
	v_add_f32_dpp v87, v87, v87 row_shr:4 row_mask:0xf bank_mask:0xf bound_ctrl:1
	s_nop 1
	v_add_f32_dpp v87, v87, v87 row_shr:8 row_mask:0xf bank_mask:0xf bound_ctrl:1
	s_nop 1
	v_mov_b32_dpp v140, v87 row_bcast:15 row_mask:0xa bank_mask:0xf
	v_add_f32_e32 v87, v87, v140
	v_mov_b32_e32 v140, 0
	s_nop 1
	v_mov_b32_dpp v140, v87 row_bcast:31 row_mask:0xc bank_mask:0xf
	v_add_f32_e32 v87, v87, v140
	s_nop 0
	v_readlane_b32 s82, v87, 63
	s_nop 1
	v_fma_f32 v87, s82, v242, v197
	v_rsq_f32_e32 v87, v87
	s_mov_b32 s82, 0x840b000
	v_add_co_u32_e32 v44, vcc, s82, v44
	v_mul_f32_e32 v65, v65, v87
	v_fma_f32 v65, v46, v65, v47
	v_mul_f32_e32 v67, v67, v87
	v_fma_f32 v67, v48, v67, v49
	v_cvt_pk_bf16_f32 v65, v65, v67
	ds_write_b16 v63, v65 offset:12
	ds_write_b16_d16_hi v63, v65 offset:16908
	v_addc_co_u32_e32 v45, vcc, 0, v45, vcc
	s_waitcnt vmcnt(0)
; __device__ __forceinline__ unsigned cvt_pk_bf16(float lo, float hi) { unsigned r; asm volatile("v_cvt_pk_bf16_f32 %0, %1, %2" : "=v"(r) : "v"(lo), "v"(hi)); return r; }
; __device__ __forceinline__ float bf2f(unsigned short h) { return __uint_as_float((unsigned)h << 16); }
; __device__ __forceinline__ void mixer_bd(const bf16_t* __restrict__ Z, bf16_t* __restrict__ Y, const float* __restrict__ lng, const float* __restrict__ lnb, const float* __restrict__ wsp, const float* __restrict__ bsp, ...
;     ...
;         for (int k = 0; k < 16; ++k) {
;             const int s = wave * 16 + k; const bf16_t* zr = Z + (row0 + s) * NZ + 4 * 256;
;             const float v0 = bf2f(zr[lane]), v1 = bf2f(zr[lane + 64]), v2 = bf2f(zr[lane + 128]), v3 = bf2f(zr[lane + 192]);
;             const float mean = wave_sum((v0 + v1) + (v2 + v3)) * (1.f / 256.f);
;             const float d0 = v0 - mean, d1 = v1 - mean, d2 = v2 - mean, d3 = v3 - mean;
;             const float var = wave_sum((d0 * d0 + d1 * d1) + (d2 * d2 + d3 * d3)) * (1.f / 256.f);
;             const float rstd = __builtin_amdgcn_rsqf(var + 1e-5f);
;             const int ca = hf * 128 + lane, cb = ca + 64;
;             const float a = (hf ? d2 : d0) * rstd * lng[ca] + lnb[ca], b = (hf ? d3 : d1) * rstd * lng[cb] + lnb[cb];
;             const unsigned pk = cvt_pk_bf16(a, b);
;             vt[lane * VP + s] = (bf16_t)(pk & 0xffffu); vt[(lane + 64) * VP + s] = (bf16_t)(pk >> 16);
;         }
	v_mov_b32_e32 v65, v246
	v_mov_b32_e32 v67, v248
	v_mov_b32_e32 v86, v249
	v_lshlrev_b32_e32 v65, 16, v65
	v_mov_b32_e32 v44, v250
	v_lshlrev_b32_e32 v67, 16, v67
	v_lshlrev_b32_e32 v86, 16, v86
	v_add_f32_e32 v45, v65, v67
	v_lshlrev_b32_e32 v44, 16, v44
	v_add_f32_e32 v87, v86, v44
	v_add_f32_e32 v45, v45, v87
	v_mov_b32_e32 v87, 0
	s_nop 0
	v_add_f32_dpp v45, v45, v45 row_shr:1 row_mask:0xf bank_mask:0xf bound_ctrl:1
	s_nop 1
	v_add_f32_dpp v45, v45, v45 row_shr:2 row_mask:0xf bank_mask:0xf bound_ctrl:1
	s_nop 1
	v_add_f32_dpp v45, v45, v45 row_shr:4 row_mask:0xf bank_mask:0xf bound_ctrl:1
	s_nop 1
	v_add_f32_dpp v45, v45, v45 row_shr:8 row_mask:0xf bank_mask:0xf bound_ctrl:1
	s_nop 1
	v_mov_b32_dpp v87, v45 row_bcast:15 row_mask:0xa bank_mask:0xf
	v_add_f32_e32 v45, v45, v87
	v_mov_b32_e32 v87, 0
	s_nop 1
	v_mov_b32_dpp v87, v45 row_bcast:31 row_mask:0xc bank_mask:0xf
	v_add_f32_e32 v45, v45, v87
	s_nop 0
	v_readlane_b32 s82, v45, 63
	s_nop 1
	v_fmac_f32_e32 v67, s82, v241
	v_fmac_f32_e32 v44, s82, v241
	v_fmac_f32_e32 v65, s82, v241
	v_fmac_f32_e32 v86, s82, v241
	v_mul_f32_e32 v45, v67, v67
	v_mul_f32_e32 v87, v44, v44
	v_fmac_f32_e32 v45, v65, v65
	v_fmac_f32_e32 v87, v86, v86
	v_add_f32_e32 v45, v45, v87
	v_mov_b32_e32 v87, 0
	v_cndmask_b32_e64 v44, v44, v67, s[70:71]
	v_add_f32_dpp v45, v45, v45 row_shr:1 row_mask:0xf bank_mask:0xf bound_ctrl:1
	v_cndmask_b32_e64 v65, v86, v65, s[70:71]
	s_nop 0
	v_add_f32_dpp v45, v45, v45 row_shr:2 row_mask:0xf bank_mask:0xf bound_ctrl:1
	s_nop 1
	v_add_f32_dpp v45, v45, v45 row_shr:4 row_mask:0xf bank_mask:0xf bound_ctrl:1
	s_nop 1
	v_add_f32_dpp v45, v45, v45 row_shr:8 row_mask:0xf bank_mask:0xf bound_ctrl:1
	s_nop 1
	v_mov_b32_dpp v87, v45 row_bcast:15 row_mask:0xa bank_mask:0xf
	v_add_f32_e32 v45, v45, v87
	v_mov_b32_e32 v87, 0
	s_nop 1
	v_mov_b32_dpp v87, v45 row_bcast:31 row_mask:0xc bank_mask:0xf
	v_add_f32_e32 v45, v45, v87
	s_nop 0
	v_readlane_b32 s82, v45, 63
	s_nop 1
	v_fma_f32 v45, s82, v242, v197
	v_rsq_f32_e32 v45, v45
	s_nop 0
	v_mul_f32_e32 v44, v44, v45
	v_mul_f32_e32 v65, v65, v45
	v_fma_f32 v44, v48, v44, v49
	v_fma_f32 v65, v46, v65, v47
	v_cvt_pk_bf16_f32 v44, v65, v44
	ds_write_b16 v63, v44 offset:14
	ds_write_b16_d16_hi v63, v44 offset:16910
	v_add_u32_e32 v63, 16, v63
	s_cbranch_scc0 .LBB0_249
	s_lshl_b32 s70, s86, 6
	s_and_b32 s71, s70, 0xfc0
	s_sub_i32 s71, 29, s71
	v_cmp_lt_i32_e32 vcc, s71, v123
	v_mov_b64_e32 v[86:87], s[0:1]
	s_movk_i32 s82, 0x1000
	v_cndmask_b32_e32 v42, 0, v124, vcc
	v_add_u32_e32 v42, s70, v42
	v_mad_i64_i32 v[42:43], s[72:73], v42, s33, v[86:87]
	v_lshl_add_u64 v[42:43], v[42:43], 0, v[0:1]
	v_cndmask_b32_e64 v88, 0, 1.0, vcc
	v_add_co_u32_e32 v46, vcc, s82, v42
	v_mov_b32_e32 v67, v1
	s_nop 0
	v_addc_co_u32_e32 v47, vcc, 0, v43, vcc
	global_load_dwordx4 v[42:45], v[46:47], off offset:512
	s_nop 0
	global_load_dwordx4 v[46:49], v[46:47], off offset:1024
	v_cmp_lt_i32_e32 vcc, s71, v126
	v_add_u32_e32 v148, s77, v54
	v_ashrrev_i32_e32 v149, 31, v148
	s_add_i32 s86, s86, s97
	s_waitcnt vmcnt(1)
	v_lshlrev_b32_e32 v142, 16, v42
	s_waitcnt vmcnt(0)
	v_lshlrev_b32_e32 v63, 16, v46
	v_and_b32_e32 v46, 0xffff0000, v46
	v_and_b32_e32 v143, 0xffff0000, v42
	v_lshlrev_b32_e32 v42, 16, v47
	v_mul_f32_e32 v63, 0xbfb8aa3b, v63
	v_mul_f32_e32 v46, 0xbfb8aa3b, v46
	v_mul_f32_e32 v42, 0xbfb8aa3b, v42
	v_exp_f32_e32 v63, v63
	v_exp_f32_e32 v46, v46
	v_exp_f32_e32 v42, v42
	v_add_f32_e32 v63, 1.0, v63
	v_add_f32_e32 v46, 1.0, v46
	v_add_f32_e32 v42, 1.0, v42
	v_rcp_f32_e32 v140, v63
	v_rcp_f32_e32 v141, v46
	v_rcp_f32_e32 v46, v42
	v_and_b32_e32 v42, 0xffff0000, v47
	v_mul_f32_e32 v42, 0xbfb8aa3b, v42
	v_exp_f32_e32 v42, v42
	v_pk_mul_f32 v[140:141], v[140:141], v[142:143]
	v_lshlrev_b32_e32 v142, 16, v44
	v_and_b32_e32 v143, 0xffff0000, v44
	v_lshlrev_b32_e32 v44, 16, v49
	v_mul_f32_e32 v44, 0xbfb8aa3b, v44
	v_add_f32_e32 v42, 1.0, v42
	v_exp_f32_e32 v44, v44
	v_rcp_f32_e32 v47, v42
	v_lshlrev_b32_e32 v42, 16, v43
	v_and_b32_e32 v43, 0xffff0000, v43
	v_add_f32_e32 v44, 1.0, v44
	v_pk_mul_f32 v[42:43], v[46:47], v[42:43]
	v_lshlrev_b32_e32 v46, 16, v48
	v_and_b32_e32 v47, 0xffff0000, v48
	v_rcp_f32_e32 v48, v44
	v_and_b32_e32 v44, 0xffff0000, v49
	v_mul_f32_e32 v46, 0xbfb8aa3b, v46
	v_mul_f32_e32 v47, 0xbfb8aa3b, v47
	v_mul_f32_e32 v44, 0xbfb8aa3b, v44
	v_exp_f32_e32 v46, v46
	v_exp_f32_e32 v47, v47
	v_exp_f32_e32 v44, v44
	v_mov_b32_e32 v63, v1
	v_add_f32_e32 v46, 1.0, v46
	v_add_f32_e32 v47, 1.0, v47
	v_add_f32_e32 v44, 1.0, v44
	v_rcp_f32_e32 v46, v46
	v_rcp_f32_e32 v47, v47
	v_rcp_f32_e32 v49, v44
	v_lshlrev_b32_e32 v44, 16, v45
	v_and_b32_e32 v45, 0xffff0000, v45
	v_pk_mul_f32 v[46:47], v[46:47], v[142:143]
	v_pk_mul_f32 v[48:49], v[48:49], v[44:45]
	v_pk_mul_f32 v[44:45], v[88:89], v[42:43] op_sel_hi:[0,1]
	v_pk_mul_f32 v[42:43], v[88:89], v[140:141] op_sel_hi:[0,1]
	ds_write_b128 v125, v[42:45] offset:36864
	v_pk_mul_f32 v[44:45], v[88:89], v[48:49] op_sel_hi:[0,1]
	v_pk_mul_f32 v[42:43], v[88:89], v[46:47] op_sel_hi:[0,1]
	ds_write_b128 v125, v[42:45] offset:36880
	v_cndmask_b32_e32 v42, 0, v127, vcc
	v_add_u32_e32 v42, s70, v42
	v_mad_i64_i32 v[42:43], s[72:73], v42, s33, v[86:87]
	v_lshl_add_u64 v[42:43], v[42:43], 0, v[62:63]
	v_cndmask_b32_e64 v88, 0, 1.0, vcc
	v_add_co_u32_e32 v46, vcc, s82, v42
	s_nop 1
	v_addc_co_u32_e32 v47, vcc, 0, v43, vcc
	global_load_dwordx4 v[42:45], v[46:47], off offset:512
	s_nop 0
	global_load_dwordx4 v[46:49], v[46:47], off offset:1024
	v_cmp_lt_i32_e32 vcc, s71, v129
	s_waitcnt vmcnt(1)
	v_lshlrev_b32_e32 v142, 16, v42
	s_waitcnt vmcnt(0)
; __device__ __forceinline__ void mixer_bd(const bf16_t* __restrict__ Z, bf16_t* __restrict__ Y, const float* __restrict__ lng, const float* __restrict__ lnb, const float* __restrict__ wsp, const float* __restrict__ bsp, ...
;     ...
;         __syncthreads();
	v_lshlrev_b32_e32 v65, 16, v46
	v_and_b32_e32 v46, 0xffff0000, v46
	v_and_b32_e32 v143, 0xffff0000, v42
	v_lshlrev_b32_e32 v42, 16, v47
	v_mul_f32_e32 v65, 0xbfb8aa3b, v65
	v_mul_f32_e32 v46, 0xbfb8aa3b, v46
	v_mul_f32_e32 v42, 0xbfb8aa3b, v42
	v_exp_f32_e32 v65, v65
	v_exp_f32_e32 v46, v46
	v_exp_f32_e32 v42, v42
	v_add_f32_e32 v65, 1.0, v65
	v_add_f32_e32 v46, 1.0, v46
	v_add_f32_e32 v42, 1.0, v42
	v_rcp_f32_e32 v140, v65
	v_rcp_f32_e32 v141, v46
	v_rcp_f32_e32 v46, v42
	v_and_b32_e32 v42, 0xffff0000, v47
	v_mul_f32_e32 v42, 0xbfb8aa3b, v42
	v_exp_f32_e32 v42, v42
	v_pk_mul_f32 v[140:141], v[140:141], v[142:143]
	v_lshlrev_b32_e32 v142, 16, v44
	v_and_b32_e32 v143, 0xffff0000, v44
	v_lshlrev_b32_e32 v44, 16, v49
	v_mul_f32_e32 v44, 0xbfb8aa3b, v44
	v_add_f32_e32 v42, 1.0, v42
	v_exp_f32_e32 v44, v44
	v_rcp_f32_e32 v47, v42
	v_lshlrev_b32_e32 v42, 16, v43
	v_and_b32_e32 v43, 0xffff0000, v43
	v_add_f32_e32 v44, 1.0, v44
	v_pk_mul_f32 v[42:43], v[46:47], v[42:43]
	v_lshlrev_b32_e32 v46, 16, v48
	v_and_b32_e32 v47, 0xffff0000, v48
	v_rcp_f32_e32 v48, v44
	v_and_b32_e32 v44, 0xffff0000, v49
	v_mul_f32_e32 v46, 0xbfb8aa3b, v46
	v_mul_f32_e32 v47, 0xbfb8aa3b, v47
	v_mul_f32_e32 v44, 0xbfb8aa3b, v44
	v_exp_f32_e32 v46, v46
	v_exp_f32_e32 v47, v47
	v_exp_f32_e32 v44, v44
	v_mov_b32_e32 v65, v1
	v_add_f32_e32 v46, 1.0, v46
	v_add_f32_e32 v47, 1.0, v47
	v_add_f32_e32 v44, 1.0, v44
	v_rcp_f32_e32 v46, v46
	v_rcp_f32_e32 v47, v47
	v_rcp_f32_e32 v49, v44
	v_lshlrev_b32_e32 v44, 16, v45
	v_and_b32_e32 v45, 0xffff0000, v45
	v_pk_mul_f32 v[46:47], v[46:47], v[142:143]
	v_pk_mul_f32 v[48:49], v[48:49], v[44:45]
	v_pk_mul_f32 v[44:45], v[88:89], v[42:43] op_sel_hi:[0,1]
	v_pk_mul_f32 v[42:43], v[88:89], v[140:141] op_sel_hi:[0,1]
	ds_write_b128 v128, v[42:45] offset:36864
	v_pk_mul_f32 v[44:45], v[88:89], v[48:49] op_sel_hi:[0,1]
	v_pk_mul_f32 v[42:43], v[88:89], v[46:47] op_sel_hi:[0,1]
	ds_write_b128 v128, v[42:45] offset:36880
	v_cndmask_b32_e32 v43, 0, v130, vcc
	v_add_u32_e32 v43, s70, v43
	v_mad_i64_i32 v[44:45], s[72:73], v43, s33, v[86:87]
	v_lshl_add_u64 v[44:45], v[44:45], 0, v[64:65]
	v_cndmask_b32_e64 v42, 0, 1.0, vcc
	v_add_co_u32_e32 v48, vcc, s82, v44
	s_nop 1
	v_addc_co_u32_e32 v49, vcc, 0, v45, vcc
	global_load_dwordx4 v[44:47], v[48:49], off offset:512
	global_load_dwordx4 v[140:143], v[48:49], off offset:1024
	v_cmp_lt_i32_e32 vcc, s71, v132
	v_readlane_b32 s71, v255, 46
	s_waitcnt vmcnt(1)
	v_lshlrev_b32_e32 v144, 16, v44
	s_waitcnt vmcnt(0)
	v_lshlrev_b32_e32 v43, 16, v140
	v_mul_f32_e32 v43, 0xbfb8aa3b, v43
	v_exp_f32_e32 v43, v43
	v_and_b32_e32 v145, 0xffff0000, v44
	v_lshlrev_b32_e32 v44, 16, v45
	v_and_b32_e32 v45, 0xffff0000, v45
	v_add_f32_e32 v43, 1.0, v43
	v_rcp_f32_e32 v48, v43
	v_and_b32_e32 v43, 0xffff0000, v140
	v_mul_f32_e32 v43, 0xbfb8aa3b, v43
	v_exp_f32_e32 v43, v43
	v_cndmask_b32_e64 v88, 0, 1.0, vcc
	v_add_f32_e32 v43, 1.0, v43
	v_rcp_f32_e32 v49, v43
	v_lshlrev_b32_e32 v43, 16, v141
	v_mul_f32_e32 v43, 0xbfb8aa3b, v43
	v_exp_f32_e32 v43, v43
	v_pk_mul_f32 v[48:49], v[48:49], v[144:145]
	v_lshlrev_b32_e32 v144, 16, v46
	v_and_b32_e32 v145, 0xffff0000, v46
	v_add_f32_e32 v43, 1.0, v43
	v_rcp_f32_e32 v140, v43
	v_and_b32_e32 v43, 0xffff0000, v141
	v_mul_f32_e32 v43, 0xbfb8aa3b, v43
	v_exp_f32_e32 v43, v43
	v_lshlrev_b32_e32 v46, 16, v47
	v_and_b32_e32 v47, 0xffff0000, v47
	v_add_f32_e32 v43, 1.0, v43
	v_rcp_f32_e32 v141, v43
	v_lshlrev_b32_e32 v43, 16, v142
	v_mul_f32_e32 v43, 0xbfb8aa3b, v43
	v_exp_f32_e32 v43, v43
	v_pk_mul_f32 v[44:45], v[140:141], v[44:45]
	v_add_f32_e32 v43, 1.0, v43
	v_rcp_f32_e32 v140, v43
	v_and_b32_e32 v43, 0xffff0000, v142
	v_mul_f32_e32 v43, 0xbfb8aa3b, v43
	v_exp_f32_e32 v43, v43
	s_nop 0
	v_add_f32_e32 v43, 1.0, v43
	v_rcp_f32_e32 v141, v43
	v_lshlrev_b32_e32 v43, 16, v143
	v_mul_f32_e32 v43, 0xbfb8aa3b, v43
	v_exp_f32_e32 v43, v43
	v_pk_mul_f32 v[140:141], v[140:141], v[144:145]
	v_add_f32_e32 v43, 1.0, v43
	v_rcp_f32_e32 v142, v43
	v_and_b32_e32 v43, 0xffff0000, v143
	v_mul_f32_e32 v43, 0xbfb8aa3b, v43
	v_exp_f32_e32 v43, v43
	s_nop 0
	v_add_f32_e32 v43, 1.0, v43
	v_rcp_f32_e32 v143, v43
	s_nop 0
	v_pk_mul_f32 v[142:143], v[142:143], v[46:47]
	v_pk_mul_f32 v[46:47], v[42:43], v[44:45] op_sel_hi:[0,1]
	v_pk_mul_f32 v[44:45], v[42:43], v[48:49] op_sel_hi:[0,1]
	ds_write_b128 v131, v[44:47] offset:36864
	v_pk_mul_f32 v[44:45], v[42:43], v[142:143] op_sel_hi:[0,1]
	v_pk_mul_f32 v[42:43], v[42:43], v[140:141] op_sel_hi:[0,1]
	ds_write_b128 v131, v[42:45] offset:36880
	v_cndmask_b32_e32 v42, 0, v133, vcc
	v_add_u32_e32 v42, s70, v42
	v_mad_i64_i32 v[42:43], s[72:73], v42, s33, v[86:87]
	v_lshl_add_u64 v[42:43], v[42:43], 0, v[66:67]
	v_add_co_u32_e32 v46, vcc, s82, v42
	v_readlane_b32 s72, v255, 30
	s_nop 0
	v_addc_co_u32_e32 v47, vcc, 0, v43, vcc
	global_load_dwordx4 v[42:45], v[46:47], off offset:512
	s_nop 0
	global_load_dwordx4 v[46:49], v[46:47], off offset:1024
	v_readlane_b32 s73, v255, 31
	s_waitcnt vmcnt(1)
	v_lshlrev_b32_e32 v142, 16, v42
	s_waitcnt vmcnt(0)
	v_lshlrev_b32_e32 v140, 16, v46
	v_and_b32_e32 v46, 0xffff0000, v46
	v_and_b32_e32 v143, 0xffff0000, v42
	v_lshlrev_b32_e32 v42, 16, v47
	v_mul_f32_e32 v140, 0xbfb8aa3b, v140
	v_mul_f32_e32 v46, 0xbfb8aa3b, v46
	v_mul_f32_e32 v42, 0xbfb8aa3b, v42
	v_exp_f32_e32 v140, v140
	v_exp_f32_e32 v46, v46
	v_exp_f32_e32 v42, v42
	v_add_f32_e32 v140, 1.0, v140
	v_add_f32_e32 v46, 1.0, v46
	v_add_f32_e32 v42, 1.0, v42
	v_rcp_f32_e32 v140, v140
	v_rcp_f32_e32 v141, v46
	v_rcp_f32_e32 v46, v42
	v_and_b32_e32 v42, 0xffff0000, v47
	v_mul_f32_e32 v42, 0xbfb8aa3b, v42
	v_exp_f32_e32 v42, v42
	v_pk_mul_f32 v[140:141], v[140:141], v[142:143]
	v_lshlrev_b32_e32 v142, 16, v44
	v_and_b32_e32 v143, 0xffff0000, v44
	v_lshlrev_b32_e32 v44, 16, v49
	v_mul_f32_e32 v44, 0xbfb8aa3b, v44
	v_add_f32_e32 v42, 1.0, v42
	v_exp_f32_e32 v44, v44
	v_rcp_f32_e32 v47, v42
	v_lshlrev_b32_e32 v42, 16, v43
	v_and_b32_e32 v43, 0xffff0000, v43
	v_add_f32_e32 v44, 1.0, v44
	v_pk_mul_f32 v[42:43], v[46:47], v[42:43]
	v_lshlrev_b32_e32 v46, 16, v48
	v_and_b32_e32 v47, 0xffff0000, v48
	v_rcp_f32_e32 v48, v44
	v_and_b32_e32 v44, 0xffff0000, v49
	v_mul_f32_e32 v46, 0xbfb8aa3b, v46
	v_mul_f32_e32 v47, 0xbfb8aa3b, v47
	v_mul_f32_e32 v44, 0xbfb8aa3b, v44
	v_exp_f32_e32 v46, v46
	v_exp_f32_e32 v47, v47
	v_exp_f32_e32 v44, v44
	v_add_f32_e32 v46, 1.0, v46
	v_add_f32_e32 v47, 1.0, v47
	v_add_f32_e32 v44, 1.0, v44
	v_rcp_f32_e32 v46, v46
	v_rcp_f32_e32 v47, v47
	v_rcp_f32_e32 v49, v44
	v_lshlrev_b32_e32 v44, 16, v45
	v_and_b32_e32 v45, 0xffff0000, v45
	v_pk_mul_f32 v[46:47], v[46:47], v[142:143]
	v_pk_mul_f32 v[48:49], v[48:49], v[44:45]
	v_pk_mul_f32 v[44:45], v[88:89], v[42:43] op_sel_hi:[0,1]
	v_pk_mul_f32 v[42:43], v[88:89], v[140:141] op_sel_hi:[0,1]
	ds_write_b128 v134, v[42:45] offset:36864
	v_pk_mul_f32 v[44:45], v[88:89], v[48:49] op_sel_hi:[0,1]
	v_pk_mul_f32 v[42:43], v[88:89], v[46:47] op_sel_hi:[0,1]
	v_add_u32_e32 v46, 0x1080, v135
	v_add_u32_e32 v88, 0x2100, v135
	ds_write_b128 v134, v[42:45] offset:36880
	s_waitcnt lgkmcnt(0)
	s_barrier
; __device__ __forceinline__ unsigned cvt_pk_bf16(float lo, float hi) { unsigned r; asm volatile("v_cvt_pk_bf16_f32 %0, %1, %2" : "=v"(r) : "v"(lo), "v"(hi)); return r; }
; #define LAS __attribute__((address_space(3)))
; __device__ __forceinline__ float bflo(unsigned w) { return __uint_as_float(w << 16); }
; __device__ __forceinline__ float bfhi(unsigned w) { return __uint_as_float(w & 0xffff0000u); }
; __device__ __forceinline__ void mixer_bd(const bf16_t* __restrict__ Z, bf16_t* __restrict__ Y, const float* __restrict__ lng, const float* __restrict__ lnb, const float* __restrict__ wsp, const float* __restrict__ bsp, ...
;     ...
;         for (int hh = 0; hh < 2; ++hh) {
;             const int h = hf * 2 + hh;
;             f32x4 acc[4];
; #pragma unroll
;             for (int nt = 0; nt < 4; ++nt) acc[nt] = (f32x4){0.f, 0.f, 0.f, 0.f};
; #pragma unroll
;             for (int ks = 0; ks < 4; ++ks) {
;                 const int s0 = ks * 32 + fq * 8;
; #pragma unroll
;                 for (int nt = 0; nt < 4; ++nt) {
;                     const LAS bf16_t* vp = vt + (hh * 64 + nt * 16 + fr) * VP + s0;
;                     const u32x2 lo = *(const LAS u32x2*)vp, hi2 = *(const LAS u32x2*)(vp + 4);
;                     u32x4 vv; vv.x = lo.x; vv.y = lo.y; vv.z = hi2.x; vv.w = hi2.y;
;                     acc[nt] = __builtin_amdgcn_mfma_f32_16x16x32_bf16(__builtin_bit_cast(bf16x8, vv), wf[hh][ks], acc[nt], 0, 0, 0);
;                 }
;             }
; #pragma unroll
;             for (int nt = 0; nt < 4; ++nt) {
;                 const int col = h * 64 + nt * 16 + fq * 4; const u32x2 u2 = uu[hh][nt]; const float bs_ = bias[hh];
;                 u32x2 o; o.x = cvt_pk_bf16((acc[nt][0] + bs_) * bflo(u2.x), (acc[nt][1] + bs_) * bfhi(u2.x)); o.y = cvt_pk_bf16((acc[nt][2] + bs_) * bflo(u2.y), (acc[nt][3] + bs_) * bfhi(u2.y));
;                 *(u32x2*)(Y + row * DM + 256 + col) = o;
;             }
;         }
	v_lshlrev_b64 v[42:43], 11, v[76:77]
	ds_read2_b64 v[46:49], v46 offset1:1
	ds_read2_b64 v[140:143], v88 offset1:1
	v_add_u32_e32 v88, 0x3180, v135
	v_lshl_add_u64 v[76:77], s[72:73], 0, v[42:43]
	ds_read2_b64 v[42:45], v135 offset1:1
	ds_read2_b64 v[144:147], v88 offset1:1
	s_waitcnt lgkmcnt(1)
	v_mfma_f32_16x16x32_bf16 v[42:45], v[42:45], v[10:13], 0
	v_add_u32_e32 v88, 0x10c0, v135
	s_add_i32 s72, s70, s84
	s_ashr_i32 s73, s72, 31
	v_mfma_f32_16x16x32_bf16 v[46:49], v[46:49], v[10:13], 0
	s_lshl_b64 s[72:73], s[72:73], 11
	v_mfma_f32_16x16x32_bf16 v[140:143], v[140:143], v[10:13], 0
	s_waitcnt lgkmcnt(0)
	v_mfma_f32_16x16x32_bf16 v[10:13], v[144:147], v[10:13], 0
	ds_read2_b64 v[144:147], v135 offset0:8 offset1:9
	s_waitcnt lgkmcnt(0)
	v_mfma_f32_16x16x32_bf16 v[42:45], v[144:147], v[14:17], v[42:45]
	ds_read2_b64 v[144:147], v88 offset1:1
	v_add_u32_e32 v88, 0x2140, v135
	s_waitcnt lgkmcnt(0)
	v_mfma_f32_16x16x32_bf16 v[46:49], v[144:147], v[14:17], v[46:49]
	ds_read2_b64 v[144:147], v88 offset1:1
	v_add_u32_e32 v88, 0x31c0, v135
	s_waitcnt lgkmcnt(0)
	v_mfma_f32_16x16x32_bf16 v[140:143], v[144:147], v[14:17], v[140:143]
	ds_read2_b64 v[144:147], v88 offset1:1
	v_add_u32_e32 v88, 0x3200, v135
	s_waitcnt lgkmcnt(0)
	v_mfma_f32_16x16x32_bf16 v[10:13], v[144:147], v[14:17], v[10:13]
	ds_read2_b64 v[14:17], v135 offset0:16 offset1:17
	s_waitcnt lgkmcnt(0)
	v_mfma_f32_16x16x32_bf16 v[14:17], v[14:17], v[18:21], v[42:45]
	s_nop 2
	v_add_u32_e32 v42, 0x1100, v135
	ds_read2_b64 v[42:45], v42 offset1:1
	s_waitcnt lgkmcnt(0)
	v_mfma_f32_16x16x32_bf16 v[42:45], v[42:45], v[18:21], v[46:49]
	s_nop 2
	v_add_u32_e32 v46, 0x2180, v135
	ds_read2_b64 v[46:49], v46 offset1:1
	s_waitcnt lgkmcnt(0)
	v_mfma_f32_16x16x32_bf16 v[46:49], v[46:49], v[18:21], v[140:143]
	s_nop 2
	ds_read2_b64 v[140:143], v88 offset1:1
	s_waitcnt lgkmcnt(0)
	v_mfma_f32_16x16x32_bf16 v[10:13], v[140:143], v[18:21], v[10:13]
	ds_read2_b64 v[18:21], v135 offset0:24 offset1:25
	s_waitcnt lgkmcnt(0)
	v_mfma_f32_16x16x32_bf16 v[14:17], v[18:21], v[26:29], v[14:17]
	v_add_u32_e32 v18, 0x1140, v135
	ds_read2_b64 v[18:21], v18 offset1:1
	s_waitcnt lgkmcnt(0)
	v_mfma_f32_16x16x32_bf16 v[18:21], v[18:21], v[26:29], v[42:45]
	s_nop 2
	v_add_u32_e32 v42, 0x21c0, v135
	ds_read2_b64 v[42:45], v42 offset1:1
	s_waitcnt lgkmcnt(0)
	v_mfma_f32_16x16x32_bf16 v[42:45], v[42:45], v[26:29], v[46:49]
	s_nop 2
	v_add_u32_e32 v46, 0x3240, v135
	ds_read2_b64 v[46:49], v46 offset1:1
	s_waitcnt lgkmcnt(0)
	v_mfma_f32_16x16x32_bf16 v[26:29], v[46:49], v[26:29], v[10:13]
	s_nop 2
	v_add_f32_e32 v10, v138, v14
	v_lshlrev_b32_e32 v11, 16, v74
	v_mul_f32_e32 v10, v10, v11
	v_add_f32_e32 v11, v138, v15
	v_and_b32_e32 v12, 0xffff0000, v74
	v_mul_f32_e32 v11, v11, v12
	v_cvt_pk_bf16_f32 v12, v10, v11
	v_add_f32_e32 v10, v138, v16
	v_lshlrev_b32_e32 v11, 16, v75
	v_mul_f32_e32 v10, v10, v11
	v_add_f32_e32 v11, v138, v17
	v_and_b32_e32 v13, 0xffff0000, v75
	v_mul_f32_e32 v11, v11, v13
	v_cvt_pk_bf16_f32 v13, v10, v11
	v_lshl_add_u64 v[10:11], v[148:149], 1, v[76:77]
	global_store_dwordx2 v[10:11], v[12:13], off offset:512
	v_add_f32_e32 v12, v138, v18
	v_lshlrev_b32_e32 v13, 16, v72
	v_mul_f32_e32 v12, v12, v13
	v_add_f32_e32 v13, v138, v19
	v_and_b32_e32 v14, 0xffff0000, v72
	v_mul_f32_e32 v13, v13, v14
	v_cvt_pk_bf16_f32 v12, v12, v13
	v_add_f32_e32 v13, v138, v20
	v_lshlrev_b32_e32 v14, 16, v73
	v_mul_f32_e32 v13, v13, v14
	v_add_f32_e32 v14, v138, v21
	v_and_b32_e32 v15, 0xffff0000, v73
	v_mul_f32_e32 v14, v14, v15
	v_cvt_pk_bf16_f32 v13, v13, v14
	global_store_dwordx2 v[10:11], v[12:13], off offset:544
	v_add_f32_e32 v12, v138, v42
	v_lshlrev_b32_e32 v13, 16, v70
	v_mul_f32_e32 v12, v12, v13
	v_add_f32_e32 v13, v138, v43
	v_and_b32_e32 v14, 0xffff0000, v70
	v_mul_f32_e32 v13, v13, v14
	v_cvt_pk_bf16_f32 v12, v12, v13
	v_add_f32_e32 v13, v138, v44
	v_lshlrev_b32_e32 v14, 16, v71
	v_mul_f32_e32 v13, v13, v14
	v_add_f32_e32 v14, v138, v45
	v_and_b32_e32 v15, 0xffff0000, v71
	v_mul_f32_e32 v14, v14, v15
	v_cvt_pk_bf16_f32 v13, v13, v14
	global_store_dwordx2 v[10:11], v[12:13], off offset:576
	v_add_f32_e32 v12, v138, v26
	v_lshlrev_b32_e32 v13, 16, v68
	v_mul_f32_e32 v12, v12, v13
	v_add_f32_e32 v13, v138, v27
	v_and_b32_e32 v14, 0xffff0000, v68
	v_mul_f32_e32 v13, v13, v14
	v_cvt_pk_bf16_f32 v12, v12, v13
	v_add_f32_e32 v13, v138, v28
	v_lshlrev_b32_e32 v14, 16, v69
	v_mul_f32_e32 v13, v13, v14
	v_add_f32_e32 v14, v138, v29
	v_and_b32_e32 v15, 0xffff0000, v69
	v_add_u32_e32 v20, 0x6300, v135
	v_mul_f32_e32 v14, v14, v15
	v_cvt_pk_bf16_f32 v13, v13, v14
	global_store_dwordx2 v[10:11], v[12:13], off offset:608
	v_add_u32_e32 v12, 0x4200, v135
	v_add_u32_e32 v16, 0x5280, v135
	ds_read2_b64 v[26:29], v20 offset1:1
	v_add_u32_e32 v20, 0x7380, v135
	ds_read2_b64 v[12:15], v12 offset1:1
	ds_read2_b64 v[16:19], v16 offset1:1
	ds_read2_b64 v[42:45], v20 offset1:1
	s_waitcnt lgkmcnt(2)
	v_mfma_f32_16x16x32_bf16 v[12:15], v[12:15], v[22:25], 0
	s_waitcnt lgkmcnt(1)
	v_mfma_f32_16x16x32_bf16 v[16:19], v[16:19], v[22:25], 0
	v_mfma_f32_16x16x32_bf16 v[26:29], v[26:29], v[22:25], 0
	s_waitcnt lgkmcnt(0)
	v_mfma_f32_16x16x32_bf16 v[20:23], v[42:45], v[22:25], 0
	v_add_u32_e32 v24, 0x4240, v135
	ds_read2_b64 v[42:45], v24 offset1:1
	v_add_u32_e32 v24, 0x52c0, v135
	s_waitcnt lgkmcnt(0)
	v_mfma_f32_16x16x32_bf16 v[12:15], v[42:45], v[30:33], v[12:15]
	ds_read2_b64 v[42:45], v24 offset1:1
	v_add_u32_e32 v24, 0x6340, v135
	s_waitcnt lgkmcnt(0)
	v_mfma_f32_16x16x32_bf16 v[16:19], v[42:45], v[30:33], v[16:19]
	ds_read2_b64 v[42:45], v24 offset1:1
	s_waitcnt lgkmcnt(0)
; __device__ __forceinline__ unsigned cvt_pk_bf16(float lo, float hi) { unsigned r; asm volatile("v_cvt_pk_bf16_f32 %0, %1, %2" : "=v"(r) : "v"(lo), "v"(hi)); return r; }
; #define LAS __attribute__((address_space(3)))
; __device__ __forceinline__ float bflo(unsigned w) { return __uint_as_float(w << 16); }
; __device__ __forceinline__ float bfhi(unsigned w) { return __uint_as_float(w & 0xffff0000u); }
; __device__ __forceinline__ void mixer_bd(const bf16_t* __restrict__ Z, bf16_t* __restrict__ Y, const float* __restrict__ lng, const float* __restrict__ lnb, const float* __restrict__ wsp, const float* __restrict__ bsp, ...
;     ...
;         for (int hh = 0; hh < 2; ++hh) {
;             const int h = hf * 2 + hh;
;             f32x4 acc[4];
; #pragma unroll
;             for (int nt = 0; nt < 4; ++nt) acc[nt] = (f32x4){0.f, 0.f, 0.f, 0.f};
; #pragma unroll
;             for (int ks = 0; ks < 4; ++ks) {
;                 const int s0 = ks * 32 + fq * 8;
; #pragma unroll
;                 for (int nt = 0; nt < 4; ++nt) {
;                     const LAS bf16_t* vp = vt + (hh * 64 + nt * 16 + fr) * VP + s0;
;                     const u32x2 lo = *(const LAS u32x2*)vp, hi2 = *(const LAS u32x2*)(vp + 4);
;                     u32x4 vv; vv.x = lo.x; vv.y = lo.y; vv.z = hi2.x; vv.w = hi2.y;
;                     acc[nt] = __builtin_amdgcn_mfma_f32_16x16x32_bf16(__builtin_bit_cast(bf16x8, vv), wf[hh][ks], acc[nt], 0, 0, 0);
;                 }
;             }
; #pragma unroll
;             for (int nt = 0; nt < 4; ++nt) {
;                 const int col = h * 64 + nt * 16 + fq * 4; const u32x2 u2 = uu[hh][nt]; const float bs_ = bias[hh];
;                 u32x2 o; o.x = cvt_pk_bf16((acc[nt][0] + bs_) * bflo(u2.x), (acc[nt][1] + bs_) * bfhi(u2.x)); o.y = cvt_pk_bf16((acc[nt][2] + bs_) * bflo(u2.y), (acc[nt][3] + bs_) * bfhi(u2.y));
;                 *(u32x2*)(Y + row * DM + 256 + col) = o;
;             }
;         }
	v_mfma_f32_16x16x32_bf16 v[24:27], v[42:45], v[30:33], v[26:29]
	s_nop 2
	v_add_u32_e32 v28, 0x73c0, v135
	ds_read2_b64 v[42:45], v28 offset1:1
	v_add_u32_e32 v28, 0x4280, v135
	s_waitcnt lgkmcnt(0)
	v_mfma_f32_16x16x32_bf16 v[20:23], v[42:45], v[30:33], v[20:23]
	ds_read2_b64 v[28:31], v28 offset1:1
	s_waitcnt lgkmcnt(0)
	v_mfma_f32_16x16x32_bf16 v[12:15], v[28:31], v[34:37], v[12:15]
	v_add_u32_e32 v28, 0x5300, v135
	ds_read2_b64 v[28:31], v28 offset1:1
	s_waitcnt lgkmcnt(0)
	v_mfma_f32_16x16x32_bf16 v[16:19], v[28:31], v[34:37], v[16:19]
	v_add_u32_e32 v28, 0x6380, v135
	ds_read2_b64 v[28:31], v28 offset1:1
	s_waitcnt lgkmcnt(0)
	v_mfma_f32_16x16x32_bf16 v[24:27], v[28:31], v[34:37], v[24:27]
	v_add_u32_e32 v28, 0x7400, v135
	ds_read2_b64 v[28:31], v28 offset1:1
	s_waitcnt lgkmcnt(0)
	v_mfma_f32_16x16x32_bf16 v[20:23], v[28:31], v[34:37], v[20:23]
	v_add_u32_e32 v28, 0x42c0, v135
	ds_read2_b64 v[28:31], v28 offset1:1
	s_waitcnt lgkmcnt(0)
	v_mfma_f32_16x16x32_bf16 v[12:15], v[28:31], v[38:41], v[12:15]
	v_add_u32_e32 v28, 0x5340, v135
	ds_read2_b64 v[28:31], v28 offset1:1
	s_nop 5
	v_add_f32_e32 v12, v139, v12
	s_waitcnt lgkmcnt(0)
	v_mfma_f32_16x16x32_bf16 v[16:19], v[28:31], v[38:41], v[16:19]
	v_add_u32_e32 v28, 0x63c0, v135
	ds_read2_b64 v[28:31], v28 offset1:1
	v_add_f32_e32 v13, v139, v13
	s_waitcnt lgkmcnt(0)
	v_mfma_f32_16x16x32_bf16 v[24:27], v[28:31], v[38:41], v[24:27]
	v_add_u32_e32 v28, 0x7440, v135
	ds_read2_b64 v[28:31], v28 offset1:1
	s_waitcnt lgkmcnt(0)
	v_mfma_f32_16x16x32_bf16 v[20:23], v[28:31], v[38:41], v[20:23]
	v_lshlrev_b32_e32 v28, 16, v84
	v_mul_f32_e32 v12, v12, v28
	v_and_b32_e32 v28, 0xffff0000, v84
	v_mul_f32_e32 v13, v13, v28
	v_cvt_pk_bf16_f32 v12, v12, v13
	v_add_f32_e32 v13, v139, v14
	v_lshlrev_b32_e32 v14, 16, v85
	v_mul_f32_e32 v13, v13, v14
	v_add_f32_e32 v14, v139, v15
	v_and_b32_e32 v15, 0xffff0000, v85
	v_mul_f32_e32 v14, v14, v15
	v_cvt_pk_bf16_f32 v13, v13, v14
	global_store_dwordx2 v[10:11], v[12:13], off offset:640
	v_add_f32_e32 v12, v139, v16
	v_lshlrev_b32_e32 v13, 16, v82
	v_mul_f32_e32 v12, v12, v13
	v_add_f32_e32 v13, v139, v17
	v_and_b32_e32 v14, 0xffff0000, v82
	v_mul_f32_e32 v13, v13, v14
	v_cvt_pk_bf16_f32 v12, v12, v13
	v_add_f32_e32 v13, v139, v18
	v_lshlrev_b32_e32 v14, 16, v83
	v_mul_f32_e32 v13, v13, v14
	v_add_f32_e32 v14, v139, v19
	v_and_b32_e32 v15, 0xffff0000, v83
	v_mul_f32_e32 v14, v14, v15
	v_cvt_pk_bf16_f32 v13, v13, v14
	global_store_dwordx2 v[10:11], v[12:13], off offset:672
	v_add_f32_e32 v12, v139, v24
	v_lshlrev_b32_e32 v13, 16, v80
	v_mul_f32_e32 v12, v12, v13
	v_add_f32_e32 v13, v139, v25
	v_and_b32_e32 v14, 0xffff0000, v80
	v_mul_f32_e32 v13, v13, v14
	v_cvt_pk_bf16_f32 v12, v12, v13
	v_add_f32_e32 v13, v139, v26
	v_lshlrev_b32_e32 v14, 16, v81
	v_mul_f32_e32 v13, v13, v14
	v_add_f32_e32 v14, v139, v27
	v_and_b32_e32 v15, 0xffff0000, v81
	v_mul_f32_e32 v14, v14, v15
	v_cvt_pk_bf16_f32 v13, v13, v14
	global_store_dwordx2 v[10:11], v[12:13], off offset:704
	v_add_f32_e32 v12, v139, v20
	v_lshlrev_b32_e32 v13, 16, v78
	v_mul_f32_e32 v12, v12, v13
	v_add_f32_e32 v13, v139, v21
	v_and_b32_e32 v14, 0xffff0000, v78
	v_mul_f32_e32 v13, v13, v14
	v_cvt_pk_bf16_f32 v12, v12, v13
	v_add_f32_e32 v13, v139, v22
	v_lshlrev_b32_e32 v14, 16, v79
	v_mul_f32_e32 v13, v13, v14
	v_add_f32_e32 v14, v139, v23
	v_and_b32_e32 v15, 0xffff0000, v79
	v_mul_f32_e32 v14, v14, v15
	v_cvt_pk_bf16_f32 v13, v13, v14
	global_store_dwordx2 v[10:11], v[12:13], off offset:736
	ds_read2st64_b32 v[10:11], v136 offset0:144 offset1:148
	ds_read2st64_b32 v[12:13], v136 offset0:180 offset1:184
	ds_read2st64_b32 v[14:15], v136 offset0:184 offset1:188
	ds_read2st64_b32 v[16:17], v136 offset0:188 offset1:192
	ds_read2st64_b32 v[18:19], v136 offset0:192 offset1:196
	s_waitcnt lgkmcnt(4)
	v_fma_f32 v46, v116, v10, v120
	v_fmac_f32_e32 v46, v117, v11
	v_fma_f32 v47, v116, v11, v120
	ds_read2st64_b32 v[10:11], v136 offset0:152 offset1:156
	ds_read2st64_b32 v[20:21], v136 offset0:196 offset1:200
	ds_read2st64_b32 v[22:23], v136 offset0:200 offset1:204
	ds_read2st64_b32 v[24:25], v136 offset0:204 offset1:208
	ds_read2st64_b32 v[26:27], v136 offset0:212 offset1:216
	s_waitcnt lgkmcnt(4)
	v_fmac_f32_e32 v46, v118, v10
	v_fmac_f32_e32 v47, v117, v10
	v_fma_f32 v48, v116, v10, v120
	v_fmac_f32_e32 v46, v119, v11
	v_fmac_f32_e32 v47, v118, v11
	v_fmac_f32_e32 v48, v117, v11
	v_fma_f32 v49, v116, v11, v120
	ds_read2st64_b32 v[10:11], v136 offset0:160 offset1:164
	ds_read2st64_b32 v[28:29], v136 offset0:220 offset1:224
	ds_read2st64_b32 v[30:31], v136 offset0:228 offset1:232
	ds_read2st64_b32 v[32:33], v136 offset0:236 offset1:240
	ds_read2st64_b32 v[34:35], v136 offset0:244 offset1:248
	s_waitcnt lgkmcnt(4)
	v_fmac_f32_e32 v46, v89, v10
	v_fmac_f32_e32 v47, v119, v10
	v_fmac_f32_e32 v48, v118, v10
	v_fmac_f32_e32 v49, v117, v10
	v_fma_f32 v68, v116, v10, v120
	v_fmac_f32_e32 v46, v97, v11
	v_fmac_f32_e32 v47, v89, v11
	v_fmac_f32_e32 v48, v119, v11
	v_fmac_f32_e32 v49, v118, v11
	v_fmac_f32_e32 v68, v117, v11
	v_fma_f32 v69, v116, v11, v120
	ds_read2st64_b32 v[10:11], v136 offset0:168 offset1:172
	ds_read2st64_b32 v[36:37], v137 offset0:112 offset1:116
	ds_read2st64_b32 v[38:39], v137 offset0:120 offset1:124
	ds_read2st64_b32 v[40:41], v137 offset0:128 offset1:132
	ds_read2st64_b32 v[42:43], v137 offset0:136 offset1:140
	s_waitcnt lgkmcnt(4)
	v_fmac_f32_e32 v46, v98, v10
	v_fmac_f32_e32 v47, v97, v10
	v_fmac_f32_e32 v48, v89, v10
	v_fmac_f32_e32 v49, v119, v10
	v_fmac_f32_e32 v68, v118, v10
	v_fmac_f32_e32 v69, v117, v10
	v_fma_f32 v70, v116, v10, v120
	v_fmac_f32_e32 v46, v99, v11
	v_fmac_f32_e32 v47, v98, v11
	v_fmac_f32_e32 v48, v97, v11
	v_fmac_f32_e32 v49, v89, v11
	v_fmac_f32_e32 v68, v119, v11
	v_fmac_f32_e32 v69, v118, v11
	v_fmac_f32_e32 v70, v117, v11
	v_fma_f32 v71, v116, v11, v120
	ds_read2st64_b32 v[10:11], v136 offset0:176 offset1:180
	ds_read2st64_b32 v[44:45], v137 offset0:144 offset1:148
	s_waitcnt lgkmcnt(1)
	v_fmac_f32_e32 v71, v117, v10
	v_fmac_f32_e32 v70, v118, v10
	v_fmac_f32_e32 v71, v118, v11
	v_fmac_f32_e32 v69, v119, v10
	v_fmac_f32_e32 v70, v119, v11
	v_fmac_f32_e32 v71, v119, v13
	v_fmac_f32_e32 v68, v89, v10
	v_fmac_f32_e32 v69, v89, v11
	v_fmac_f32_e32 v70, v89, v13
	v_fmac_f32_e32 v71, v89, v15
	v_fmac_f32_e32 v49, v97, v10
	v_fmac_f32_e32 v68, v97, v11
	v_fmac_f32_e32 v69, v97, v13
	v_fmac_f32_e32 v70, v97, v15
	v_fmac_f32_e32 v71, v97, v17
	v_fmac_f32_e32 v46, v90, v10
	v_fmac_f32_e32 v47, v99, v10
	v_fmac_f32_e32 v48, v98, v10
	v_fmac_f32_e32 v49, v98, v11
	v_fmac_f32_e32 v68, v98, v13
	v_fmac_f32_e32 v69, v98, v15
	v_fmac_f32_e32 v70, v98, v17
	v_fmac_f32_e32 v71, v98, v19
	v_fmac_f32_e32 v46, v91, v11
	v_fmac_f32_e32 v47, v90, v11
	v_fmac_f32_e32 v48, v99, v11
	v_fmac_f32_e32 v49, v99, v13
	v_fmac_f32_e32 v68, v99, v15
	v_fmac_f32_e32 v69, v99, v17
	v_fmac_f32_e32 v70, v99, v19
	v_fmac_f32_e32 v71, v99, v21
	v_fma_f32 v10, v116, v10, v120
	v_fma_f32 v11, v116, v12, v120
	v_fmac_f32_e32 v47, v91, v13
	v_fmac_f32_e32 v48, v90, v13
	v_fmac_f32_e32 v49, v90, v15
	v_fmac_f32_e32 v68, v90, v17
	v_fmac_f32_e32 v69, v90, v19
	v_fmac_f32_e32 v70, v90, v21
	v_fmac_f32_e32 v71, v90, v23
	v_fmac_f32_e32 v10, v117, v12
	v_fmac_f32_e32 v11, v117, v14
	v_fma_f32 v12, v116, v14, v120
	v_fmac_f32_e32 v46, v92, v13
	v_fmac_f32_e32 v47, v92, v15
	v_fmac_f32_e32 v48, v91, v15
	v_fmac_f32_e32 v49, v91, v17
	v_fmac_f32_e32 v68, v91, v19
	v_fmac_f32_e32 v69, v91, v21
	v_fmac_f32_e32 v70, v91, v23
	v_fmac_f32_e32 v71, v91, v25
	v_fmac_f32_e32 v10, v118, v14
	v_fmac_f32_e32 v11, v118, v16
	v_fmac_f32_e32 v12, v117, v16
	v_fma_f32 v13, v116, v16, v120
	v_fmac_f32_e32 v46, v93, v15
	v_fmac_f32_e32 v47, v93, v17
	v_fmac_f32_e32 v48, v92, v17
	v_fmac_f32_e32 v49, v92, v19
	v_fmac_f32_e32 v68, v92, v21
	v_fmac_f32_e32 v69, v92, v23
	v_fmac_f32_e32 v70, v92, v25
	v_fmac_f32_e32 v71, v92, v26
	v_fmac_f32_e32 v10, v119, v16
	v_fmac_f32_e32 v11, v119, v18
	v_fmac_f32_e32 v12, v118, v18
	v_fmac_f32_e32 v13, v117, v18
	v_fma_f32 v14, v116, v18, v120
	v_fmac_f32_e32 v46, v94, v17
	v_fmac_f32_e32 v47, v94, v19
	v_fmac_f32_e32 v48, v93, v19
	v_fmac_f32_e32 v49, v93, v21
	v_fmac_f32_e32 v68, v93, v23
	v_fmac_f32_e32 v69, v93, v25
	v_fmac_f32_e32 v70, v93, v26
	v_fmac_f32_e32 v71, v93, v27
	v_fmac_f32_e32 v10, v89, v18
	v_fmac_f32_e32 v11, v89, v20
	v_fmac_f32_e32 v12, v119, v20
	v_fmac_f32_e32 v13, v118, v20
	v_fmac_f32_e32 v14, v117, v20
	v_fma_f32 v15, v116, v20, v120
	v_fmac_f32_e32 v46, v100, v19
	v_fmac_f32_e32 v47, v100, v21
	v_fmac_f32_e32 v48, v94, v21
	v_fmac_f32_e32 v49, v94, v23
	v_fmac_f32_e32 v68, v94, v25
	v_fmac_f32_e32 v69, v94, v26
	v_fmac_f32_e32 v70, v94, v27
	v_fmac_f32_e32 v71, v94, v28
	v_fmac_f32_e32 v10, v97, v20
	v_fmac_f32_e32 v11, v97, v22
	v_fmac_f32_e32 v12, v89, v22
	v_fmac_f32_e32 v13, v119, v22
	v_fmac_f32_e32 v14, v118, v22
	v_fmac_f32_e32 v15, v117, v22
	v_fma_f32 v16, v116, v22, v120
	v_fmac_f32_e32 v46, v101, v21
	v_fmac_f32_e32 v47, v101, v23
	v_fmac_f32_e32 v48, v100, v23
	v_fmac_f32_e32 v49, v100, v25
	v_fmac_f32_e32 v68, v100, v26
	v_fmac_f32_e32 v69, v100, v27
	v_fmac_f32_e32 v70, v100, v28
	v_fmac_f32_e32 v71, v100, v29
	v_fmac_f32_e32 v10, v98, v22
	v_fmac_f32_e32 v11, v98, v24
	v_fmac_f32_e32 v12, v97, v24
	v_fmac_f32_e32 v13, v89, v24
	v_fmac_f32_e32 v14, v119, v24
	v_fmac_f32_e32 v15, v118, v24
	v_fmac_f32_e32 v16, v117, v24
	v_fma_f32 v18, v116, v24, v120
	v_fmac_f32_e32 v46, v102, v23
	v_fmac_f32_e32 v47, v102, v25
	v_fmac_f32_e32 v48, v101, v25
	v_fmac_f32_e32 v49, v101, v26
	v_fmac_f32_e32 v68, v101, v27
	v_fmac_f32_e32 v69, v101, v28
	v_fmac_f32_e32 v70, v101, v29
	v_fmac_f32_e32 v71, v101, v30
	v_fmac_f32_e32 v10, v99, v24
	v_fmac_f32_e32 v11, v99, v25
	v_fmac_f32_e32 v12, v98, v25
	v_fmac_f32_e32 v13, v97, v25
	v_fmac_f32_e32 v14, v89, v25
	v_fmac_f32_e32 v15, v119, v25
	v_fmac_f32_e32 v16, v118, v25
	v_fmac_f32_e32 v18, v117, v25
	v_fmac_f32_e32 v46, v95, v25
	v_fmac_f32_e32 v47, v95, v26
	v_fmac_f32_e32 v48, v102, v26
	v_fmac_f32_e32 v49, v102, v27
	v_fmac_f32_e32 v68, v102, v28
	v_fmac_f32_e32 v69, v102, v29
	v_fmac_f32_e32 v70, v102, v30
	v_fmac_f32_e32 v71, v102, v31
	ds_read_b32 v17, v136 offset:64512
	v_fmac_f32_e32 v10, v90, v25
	v_fmac_f32_e32 v11, v90, v26
	v_fmac_f32_e32 v12, v99, v26
	v_fmac_f32_e32 v13, v98, v26
	v_fmac_f32_e32 v14, v97, v26
	v_fmac_f32_e32 v15, v89, v26
	v_fmac_f32_e32 v16, v119, v26
	v_fmac_f32_e32 v18, v118, v26
	v_fmac_f32_e32 v46, v96, v26
	v_fmac_f32_e32 v47, v96, v27
	v_fmac_f32_e32 v48, v95, v27
	v_fmac_f32_e32 v49, v95, v28
	v_fmac_f32_e32 v68, v95, v29
	v_fmac_f32_e32 v69, v95, v30
	v_fmac_f32_e32 v70, v95, v31
	v_fmac_f32_e32 v71, v95, v32
	v_fmac_f32_e32 v10, v91, v26
	v_fmac_f32_e32 v11, v91, v27
	v_fmac_f32_e32 v12, v90, v27
	v_fmac_f32_e32 v13, v99, v27
	v_fmac_f32_e32 v14, v98, v27
	v_fmac_f32_e32 v15, v97, v27
	v_fmac_f32_e32 v16, v89, v27
	v_fmac_f32_e32 v18, v119, v27
	v_fmac_f32_e32 v46, v105, v27
	v_fmac_f32_e32 v47, v105, v28
	v_fmac_f32_e32 v48, v96, v28
	v_fmac_f32_e32 v49, v96, v29
	v_fmac_f32_e32 v68, v96, v30
	v_fmac_f32_e32 v69, v96, v31
	v_fmac_f32_e32 v70, v96, v32
	v_fmac_f32_e32 v71, v96, v33
	v_fmac_f32_e32 v10, v92, v27
	v_fmac_f32_e32 v11, v92, v28
	v_fmac_f32_e32 v12, v91, v28
	v_fmac_f32_e32 v13, v90, v28
	v_fmac_f32_e32 v14, v99, v28
	v_fmac_f32_e32 v15, v98, v28
	v_fmac_f32_e32 v16, v97, v28
	v_fmac_f32_e32 v18, v89, v28
	v_fmac_f32_e32 v46, v106, v28
	v_fmac_f32_e32 v47, v106, v29
	v_fmac_f32_e32 v48, v105, v29
	v_fmac_f32_e32 v49, v105, v30
	v_fmac_f32_e32 v68, v105, v31
	v_fmac_f32_e32 v69, v105, v32
	v_fmac_f32_e32 v70, v105, v33
	v_fmac_f32_e32 v71, v105, v34
	v_fmac_f32_e32 v10, v93, v28
	v_fmac_f32_e32 v11, v93, v29
	v_fmac_f32_e32 v12, v92, v29
	v_fmac_f32_e32 v13, v91, v29
	v_fmac_f32_e32 v14, v90, v29
	v_fmac_f32_e32 v15, v99, v29
	v_fmac_f32_e32 v16, v98, v29
	v_fmac_f32_e32 v18, v97, v29
	v_fmac_f32_e32 v46, v107, v29
	v_fmac_f32_e32 v47, v107, v30
	v_fmac_f32_e32 v48, v106, v30
	v_fmac_f32_e32 v49, v106, v31
	v_fmac_f32_e32 v68, v106, v32
	v_fmac_f32_e32 v69, v106, v33
	v_fmac_f32_e32 v70, v106, v34
	v_fmac_f32_e32 v71, v106, v35
	v_fmac_f32_e32 v10, v94, v29
	v_fmac_f32_e32 v11, v94, v30
	v_fmac_f32_e32 v12, v93, v30
	v_fmac_f32_e32 v13, v92, v30
	v_fmac_f32_e32 v14, v91, v30
	v_fmac_f32_e32 v15, v90, v30
	v_fmac_f32_e32 v16, v99, v30
	v_fmac_f32_e32 v18, v98, v30
	v_fmac_f32_e32 v46, v103, v30
	v_fmac_f32_e32 v47, v103, v31
	v_fmac_f32_e32 v48, v107, v31
	v_fmac_f32_e32 v49, v107, v32
	v_fmac_f32_e32 v68, v107, v33
	v_fmac_f32_e32 v69, v107, v34
	v_fmac_f32_e32 v70, v107, v35
	s_waitcnt lgkmcnt(0)
	v_fmac_f32_e32 v71, v107, v17
	v_fmac_f32_e32 v10, v100, v30
	v_fmac_f32_e32 v11, v100, v31
	v_fmac_f32_e32 v12, v94, v31
	v_fmac_f32_e32 v13, v93, v31
	v_fmac_f32_e32 v14, v92, v31
	v_fmac_f32_e32 v15, v91, v31
	v_fmac_f32_e32 v16, v90, v31
	v_fmac_f32_e32 v18, v99, v31
	v_fmac_f32_e32 v46, v104, v31
	v_fmac_f32_e32 v47, v104, v32
	v_fmac_f32_e32 v48, v103, v32
	v_fmac_f32_e32 v49, v103, v33
	v_fmac_f32_e32 v68, v103, v34
	v_fmac_f32_e32 v69, v103, v35
	v_fmac_f32_e32 v70, v103, v17
	v_fmac_f32_e32 v71, v103, v36
	v_fmac_f32_e32 v10, v101, v31
	v_fmac_f32_e32 v11, v101, v32
	v_fmac_f32_e32 v12, v100, v32
	v_fmac_f32_e32 v13, v94, v32
	v_fmac_f32_e32 v14, v93, v32
	v_fmac_f32_e32 v15, v92, v32
	v_fmac_f32_e32 v16, v91, v32
	v_fmac_f32_e32 v18, v90, v32
	v_fmac_f32_e32 v46, v112, v32
	v_fmac_f32_e32 v47, v112, v33
	v_fmac_f32_e32 v48, v104, v33
	v_fmac_f32_e32 v49, v104, v34
	v_fmac_f32_e32 v68, v104, v35
	v_fmac_f32_e32 v69, v104, v17
	v_fmac_f32_e32 v70, v104, v36
	v_fmac_f32_e32 v71, v104, v37
	v_fmac_f32_e32 v10, v102, v32
	v_fmac_f32_e32 v11, v102, v33
	v_fmac_f32_e32 v12, v101, v33
	v_fmac_f32_e32 v13, v100, v33
	v_fmac_f32_e32 v14, v94, v33
	v_fmac_f32_e32 v15, v93, v33
	v_fmac_f32_e32 v16, v92, v33
	v_fmac_f32_e32 v18, v91, v33
	v_fmac_f32_e32 v46, v108, v33
	v_fmac_f32_e32 v47, v108, v34
	v_fmac_f32_e32 v48, v112, v34
	v_fmac_f32_e32 v49, v112, v35
	v_fmac_f32_e32 v68, v112, v17
	v_fmac_f32_e32 v69, v112, v36
	v_fmac_f32_e32 v70, v112, v37
	v_fmac_f32_e32 v71, v112, v38
	v_fmac_f32_e32 v10, v95, v33
	v_fmac_f32_e32 v11, v95, v34
	v_fmac_f32_e32 v12, v102, v34
	v_fmac_f32_e32 v13, v101, v34
	v_fmac_f32_e32 v14, v100, v34
	v_fmac_f32_e32 v15, v94, v34
	v_fmac_f32_e32 v16, v93, v34
	v_fmac_f32_e32 v18, v92, v34
	v_fmac_f32_e32 v46, v109, v34
	v_fmac_f32_e32 v47, v109, v35
	v_fmac_f32_e32 v48, v108, v35
	v_fmac_f32_e32 v49, v108, v17
	v_fmac_f32_e32 v68, v108, v36
	v_fmac_f32_e32 v69, v108, v37
	v_fmac_f32_e32 v70, v108, v38
	v_fmac_f32_e32 v71, v108, v39
	v_fmac_f32_e32 v10, v96, v34
	v_fmac_f32_e32 v11, v96, v35
	v_fmac_f32_e32 v12, v95, v35
	v_fmac_f32_e32 v13, v102, v35
	v_fmac_f32_e32 v14, v101, v35
	v_fmac_f32_e32 v15, v100, v35
	v_fmac_f32_e32 v16, v94, v35
	v_fmac_f32_e32 v18, v93, v35
	v_fmac_f32_e32 v46, v110, v35
	v_fmac_f32_e32 v47, v110, v17
	v_fmac_f32_e32 v48, v109, v17
	v_fmac_f32_e32 v49, v109, v36
	v_fmac_f32_e32 v68, v109, v37
	v_fmac_f32_e32 v69, v109, v38
	v_fmac_f32_e32 v70, v109, v39
	v_fmac_f32_e32 v71, v109, v40
	v_fmac_f32_e32 v10, v105, v35
	v_fmac_f32_e32 v11, v105, v17
	v_fmac_f32_e32 v12, v96, v17
	v_fmac_f32_e32 v13, v95, v17
	v_fmac_f32_e32 v14, v102, v17
	v_fmac_f32_e32 v15, v101, v17
	v_fmac_f32_e32 v16, v100, v17
	v_fmac_f32_e32 v18, v94, v17
	v_fmac_f32_e32 v46, v111, v17
	v_fmac_f32_e32 v47, v111, v36
	v_fmac_f32_e32 v48, v110, v36
	v_fmac_f32_e32 v49, v110, v37
	v_fmac_f32_e32 v68, v110, v38
	v_fmac_f32_e32 v69, v110, v39
	v_fmac_f32_e32 v70, v110, v40
	v_fmac_f32_e32 v71, v110, v41
	v_fmac_f32_e32 v10, v106, v17
	v_fmac_f32_e32 v11, v106, v36
	v_fmac_f32_e32 v12, v105, v36
	v_fmac_f32_e32 v13, v96, v36
	v_fmac_f32_e32 v14, v95, v36
	v_fmac_f32_e32 v15, v102, v36
	v_fmac_f32_e32 v16, v101, v36
	v_fmac_f32_e32 v18, v100, v36
	v_fmac_f32_e32 v46, v113, v36
	v_fmac_f32_e32 v47, v113, v37
	v_fmac_f32_e32 v48, v111, v37
	v_fmac_f32_e32 v49, v111, v38
	v_fmac_f32_e32 v68, v111, v39
	v_fmac_f32_e32 v69, v111, v40
	v_fmac_f32_e32 v70, v111, v41
	v_fmac_f32_e32 v71, v111, v42
	v_fmac_f32_e32 v10, v107, v36
	v_fmac_f32_e32 v11, v107, v37
	v_fmac_f32_e32 v12, v106, v37
	v_fmac_f32_e32 v13, v105, v37
	v_fmac_f32_e32 v14, v96, v37
	v_fmac_f32_e32 v15, v95, v37
	v_fmac_f32_e32 v16, v102, v37
	v_fmac_f32_e32 v18, v101, v37
	v_fmac_f32_e32 v46, v114, v37
	v_fmac_f32_e32 v47, v114, v38
	v_fmac_f32_e32 v48, v113, v38
	v_fmac_f32_e32 v49, v113, v39
	v_fmac_f32_e32 v68, v113, v40
	v_fmac_f32_e32 v69, v113, v41
	v_fmac_f32_e32 v70, v113, v42
	v_fmac_f32_e32 v71, v113, v43
	v_fmac_f32_e32 v10, v103, v37
	v_fmac_f32_e32 v11, v103, v38
	v_fmac_f32_e32 v12, v107, v38
; __device__ __forceinline__ void mixer_bd(const bf16_t* __restrict__ Z, bf16_t* __restrict__ Y, const float* __restrict__ lng, const float* __restrict__ lnb, const float* __restrict__ wsp, const float* __restrict__ bsp, ...
;     ...
;         __syncthreads();
	v_fmac_f32_e32 v13, v106, v38
	v_fmac_f32_e32 v14, v105, v38
	v_fmac_f32_e32 v15, v96, v38
	v_fmac_f32_e32 v16, v95, v38
	v_fmac_f32_e32 v18, v102, v38
	v_fmac_f32_e32 v46, v115, v38
	v_fmac_f32_e32 v47, v115, v39
	v_fmac_f32_e32 v48, v114, v39
	v_fmac_f32_e32 v49, v114, v40
	v_fmac_f32_e32 v68, v114, v41
	v_fmac_f32_e32 v69, v114, v42
	v_fmac_f32_e32 v70, v114, v43
	v_fmac_f32_e32 v71, v114, v44
	v_fmac_f32_e32 v10, v104, v38
	v_fmac_f32_e32 v11, v104, v39
	v_fmac_f32_e32 v12, v103, v39
	v_fmac_f32_e32 v13, v107, v39
	v_fmac_f32_e32 v14, v106, v39
	v_fmac_f32_e32 v15, v105, v39
	v_fmac_f32_e32 v16, v96, v39
	v_fmac_f32_e32 v18, v95, v39
	v_fmac_f32_e32 v48, v115, v40
	v_fmac_f32_e32 v49, v115, v41
	v_fmac_f32_e32 v68, v115, v42
	v_fmac_f32_e32 v69, v115, v43
	v_fmac_f32_e32 v70, v115, v44
	v_fmac_f32_e32 v71, v115, v45
	ds_write2st64_b32 v55, v46, v47 offset1:4
	ds_write2st64_b32 v55, v48, v49 offset0:8 offset1:12
	ds_write2st64_b32 v55, v68, v69 offset0:16 offset1:20
	ds_write2st64_b32 v55, v70, v71 offset0:24 offset1:28
	v_fmac_f32_e32 v10, v112, v39
	v_fmac_f32_e32 v11, v112, v40
	v_fmac_f32_e32 v12, v104, v40
	v_fmac_f32_e32 v13, v103, v40
	v_fmac_f32_e32 v14, v107, v40
	v_fmac_f32_e32 v15, v106, v40
	v_fmac_f32_e32 v16, v105, v40
	v_fmac_f32_e32 v18, v96, v40
	v_fmac_f32_e32 v10, v108, v40
	v_fmac_f32_e32 v11, v108, v41
	v_fmac_f32_e32 v12, v112, v41
	v_fmac_f32_e32 v13, v104, v41
	v_fmac_f32_e32 v14, v103, v41
	v_fmac_f32_e32 v15, v107, v41
	v_fmac_f32_e32 v16, v106, v41
	v_fmac_f32_e32 v18, v105, v41
	ds_read2st64_b32 v[20:21], v137 offset0:152 offset1:156
	v_fmac_f32_e32 v10, v109, v41
	v_fmac_f32_e32 v11, v109, v42
	v_fmac_f32_e32 v12, v108, v42
	v_fmac_f32_e32 v13, v112, v42
	v_fmac_f32_e32 v14, v104, v42
	v_fmac_f32_e32 v15, v103, v42
	v_fmac_f32_e32 v16, v107, v42
	v_fmac_f32_e32 v18, v106, v42
	v_fmac_f32_e32 v10, v110, v42
	v_fmac_f32_e32 v11, v110, v43
	v_fmac_f32_e32 v12, v109, v43
	v_fmac_f32_e32 v13, v108, v43
	v_fmac_f32_e32 v14, v112, v43
	v_fmac_f32_e32 v15, v104, v43
	v_fmac_f32_e32 v16, v103, v43
	v_fmac_f32_e32 v18, v107, v43
	v_fmac_f32_e32 v10, v111, v43
	v_fmac_f32_e32 v11, v111, v44
	v_fmac_f32_e32 v12, v110, v44
	v_fmac_f32_e32 v13, v109, v44
	v_fmac_f32_e32 v14, v108, v44
	v_fmac_f32_e32 v15, v112, v44
	v_fmac_f32_e32 v16, v104, v44
	v_fmac_f32_e32 v18, v103, v44
	v_fmac_f32_e32 v10, v113, v44
	v_fmac_f32_e32 v11, v113, v45
	v_fmac_f32_e32 v12, v111, v45
	v_fmac_f32_e32 v13, v110, v45
	v_fmac_f32_e32 v14, v109, v45
	v_fmac_f32_e32 v15, v108, v45
	v_fmac_f32_e32 v16, v112, v45
	v_fmac_f32_e32 v18, v104, v45
	v_fmac_f32_e32 v10, v114, v45
	s_waitcnt lgkmcnt(0)
	v_fmac_f32_e32 v11, v114, v20
	v_fmac_f32_e32 v12, v113, v20
	v_fmac_f32_e32 v13, v111, v20
	v_fmac_f32_e32 v14, v110, v20
	v_fmac_f32_e32 v15, v109, v20
	v_fmac_f32_e32 v16, v108, v20
	v_fmac_f32_e32 v18, v112, v20
	v_fmac_f32_e32 v10, v115, v20
	v_fmac_f32_e32 v11, v115, v21
	v_fmac_f32_e32 v12, v114, v21
	v_fmac_f32_e32 v13, v113, v21
	v_fmac_f32_e32 v14, v111, v21
	v_fmac_f32_e32 v15, v110, v21
	v_fmac_f32_e32 v16, v109, v21
	v_fmac_f32_e32 v18, v108, v21
	ds_read2st64_b32 v[20:21], v137 offset0:160 offset1:164
	v_add_u32_e32 v46, s71, v121
	v_add_u32_e32 v48, s80, v121
	v_add_u32_e32 v49, s90, v121
	s_waitcnt lgkmcnt(0)
	v_fmac_f32_e32 v13, v114, v20
	v_fmac_f32_e32 v14, v113, v20
	v_fmac_f32_e32 v15, v111, v20
	v_fmac_f32_e32 v16, v110, v20
	v_fmac_f32_e32 v18, v109, v20
	v_fmac_f32_e32 v12, v115, v20
	v_fmac_f32_e32 v13, v115, v21
	v_fmac_f32_e32 v14, v114, v21
	v_fmac_f32_e32 v15, v113, v21
	v_fmac_f32_e32 v16, v111, v21
	v_fmac_f32_e32 v18, v110, v21
	ds_read2st64_b32 v[20:21], v137 offset0:168 offset1:172
	s_waitcnt lgkmcnt(0)
	v_fmac_f32_e32 v15, v114, v20
	v_fmac_f32_e32 v16, v113, v20
	v_fmac_f32_e32 v18, v111, v20
	v_fmac_f32_e32 v14, v115, v20
	v_fmac_f32_e32 v15, v115, v21
	v_fmac_f32_e32 v16, v114, v21
	v_fmac_f32_e32 v18, v113, v21
	ds_read2st64_b32 v[20:21], v137 offset0:176 offset1:180
	s_waitcnt lgkmcnt(0)
	v_fmac_f32_e32 v18, v114, v20
	v_fmac_f32_e32 v16, v115, v20
	v_fmac_f32_e32 v18, v115, v21
	ds_write2st64_b32 v55, v10, v11 offset0:32 offset1:36
	ds_write2st64_b32 v55, v12, v13 offset0:40 offset1:44
	ds_write2st64_b32 v55, v14, v15 offset0:48 offset1:52
	ds_write2st64_b32 v55, v16, v18 offset0:56 offset1:60
	s_waitcnt lgkmcnt(0)
	s_barrier
; #define DPPF(v, ctrl, rm) __int_as_float(__builtin_amdgcn_update_dpp(0, __float_as_int(v), ctrl, rm, 0xf, false))
; __device__ __forceinline__ float wave_sum(float v) {
;     v += DPPF(v, 0x111, 0xf); v += DPPF(v, 0x112, 0xf); v += DPPF(v, 0x114, 0xf); v += DPPF(v, 0x118, 0xf);
;     v += DPPF(v, 0x142, 0xa); v += DPPF(v, 0x143, 0xc);
;     return __int_as_float(__builtin_amdgcn_readlane(__float_as_int(v), 63));
; }
	ds_read_b128 v[10:13], v46
	s_waitcnt lgkmcnt(0)
	v_mov_b32_e32 v14, v11
	v_mov_b32_e32 v15, v12
	v_mov_b32_e32 v16, v10
	v_mov_b32_e32 v17, v13
	v_pk_add_f32 v[14:15], v[14:15], v[16:17]
	s_nop 0
	v_add_f32_e32 v14, v14, v15
	v_mov_b32_e32 v15, v1
	s_nop 0
	v_add_f32_dpp v14, v14, v14 row_shr:1 row_mask:0xf bank_mask:0xf bound_ctrl:1
	s_nop 1
	v_add_f32_dpp v14, v14, v14 row_shr:2 row_mask:0xf bank_mask:0xf bound_ctrl:1
	s_nop 1
	v_add_f32_dpp v14, v14, v14 row_shr:4 row_mask:0xf bank_mask:0xf bound_ctrl:1
	s_nop 1
	v_add_f32_dpp v14, v14, v14 row_shr:8 row_mask:0xf bank_mask:0xf bound_ctrl:1
	s_nop 1
	v_mov_b32_dpp v15, v14 row_bcast:15 row_mask:0xa bank_mask:0xf
	v_add_f32_e32 v14, v14, v15
	v_mov_b32_e32 v15, v1
	s_nop 1
	v_mov_b32_dpp v15, v14 row_bcast:31 row_mask:0xc bank_mask:0xf
	v_add_f32_e32 v14, v14, v15
	s_nop 0
	v_readlane_b32 s71, v14, 63
	s_nop 1
	v_fma_f32 v11, s71, v241, v11
	v_fma_f32 v10, s71, v241, v10
	v_fma_f32 v13, s71, v241, v13
	v_fmac_f32_e32 v12, s71, v241
	v_pk_mul_f32 v[14:15], v[12:13], v[12:13]
	v_pk_mul_f32 v[16:17], v[10:11], v[10:11]
	s_nop 0
	v_pk_mov_b32 v[18:19], v[16:17], v[14:15] op_sel:[1,0]
	v_mov_b32_e32 v17, v15
	v_pk_add_f32 v[14:15], v[18:19], v[16:17]
	s_nop 0
	v_add_f32_e32 v14, v14, v15
	v_mov_b32_e32 v15, v1
	s_nop 0
	v_add_f32_dpp v14, v14, v14 row_shr:1 row_mask:0xf bank_mask:0xf bound_ctrl:1
	s_nop 1
	v_add_f32_dpp v14, v14, v14 row_shr:2 row_mask:0xf bank_mask:0xf bound_ctrl:1
	s_nop 1
	v_add_f32_dpp v14, v14, v14 row_shr:4 row_mask:0xf bank_mask:0xf bound_ctrl:1
	s_nop 1
	v_add_f32_dpp v14, v14, v14 row_shr:8 row_mask:0xf bank_mask:0xf bound_ctrl:1
	s_nop 1
	v_mov_b32_dpp v15, v14 row_bcast:15 row_mask:0xa bank_mask:0xf
	v_add_f32_e32 v14, v14, v15
	v_mov_b32_e32 v15, v1
	s_nop 1
	v_mov_b32_dpp v15, v14 row_bcast:31 row_mask:0xc bank_mask:0xf
	v_add_f32_e32 v14, v14, v15
	s_nop 0
	v_readlane_b32 s71, v14, 63
	s_nop 1
	v_fma_f32 v14, s71, v242, v197
	v_rsq_f32_e32 v14, v14
	v_readlane_b32 s71, v255, 47
	v_pk_mul_f32 v[10:11], v[10:11], v[14:15] op_sel_hi:[1,0]
	s_nop 0
	v_pk_fma_f32 v[10:11], v[2:3], v[10:11], v[6:7]
	v_pk_mul_f32 v[12:13], v[12:13], v[14:15] op_sel_hi:[1,0]
	v_mul_f32_e32 v14, 0xbfb8aa3b, v10
	v_exp_f32_e32 v14, v14
	v_pk_fma_f32 v[12:13], v[4:5], v[12:13], v[8:9]
	v_add_u32_e32 v47, s71, v121
	v_add_f32_e32 v14, 1.0, v14
	v_rcp_f32_e32 v14, v14
	s_nop 0
	v_mul_f32_e32 v10, v10, v14
	v_mul_f32_e32 v14, 0xbfb8aa3b, v11
	v_exp_f32_e32 v14, v14
	s_nop 0
	v_add_f32_e32 v14, 1.0, v14
	v_rcp_f32_e32 v14, v14
	s_nop 0
	v_mul_f32_e32 v11, v11, v14
	v_cvt_pk_bf16_f32 v10, v10, v11
	v_mul_f32_e32 v11, 0xbfb8aa3b, v12
	v_exp_f32_e32 v11, v11
	s_nop 0
	v_add_f32_e32 v11, 1.0, v11
	v_rcp_f32_e32 v11, v11
	s_nop 0
	v_mul_f32_e32 v11, v12, v11
	v_mul_f32_e32 v12, 0xbfb8aa3b, v13
	v_exp_f32_e32 v12, v12
	s_nop 0
	v_add_f32_e32 v12, 1.0, v12
	v_rcp_f32_e32 v12, v12
	s_nop 0
	v_mul_f32_e32 v12, v13, v12
	v_cvt_pk_bf16_f32 v11, v11, v12
	v_lshl_add_u64 v[12:13], v[60:61], 0, s[72:73]
	global_store_dwordx2 v[12:13], v[10:11], off offset:1536
	ds_read_b128 v[10:13], v47
	s_add_i32 s72, s70, s88
	s_ashr_i32 s73, s72, 31
	s_lshl_b64 s[72:73], s[72:73], 11
	s_waitcnt lgkmcnt(0)
	v_mov_b32_e32 v14, v11
	v_mov_b32_e32 v15, v12
	v_mov_b32_e32 v16, v10
	v_mov_b32_e32 v17, v13
	v_pk_add_f32 v[14:15], v[14:15], v[16:17]
	s_nop 0
	v_add_f32_e32 v14, v14, v15
	v_mov_b32_e32 v15, v1
	s_nop 0
	v_add_f32_dpp v14, v14, v14 row_shr:1 row_mask:0xf bank_mask:0xf bound_ctrl:1
	s_nop 1
	v_add_f32_dpp v14, v14, v14 row_shr:2 row_mask:0xf bank_mask:0xf bound_ctrl:1
	s_nop 1
	v_add_f32_dpp v14, v14, v14 row_shr:4 row_mask:0xf bank_mask:0xf bound_ctrl:1
	s_nop 1
	v_add_f32_dpp v14, v14, v14 row_shr:8 row_mask:0xf bank_mask:0xf bound_ctrl:1
	s_nop 1
	v_mov_b32_dpp v15, v14 row_bcast:15 row_mask:0xa bank_mask:0xf
	v_add_f32_e32 v14, v14, v15
	v_mov_b32_e32 v15, v1
	s_nop 1
	v_mov_b32_dpp v15, v14 row_bcast:31 row_mask:0xc bank_mask:0xf
	v_add_f32_e32 v14, v14, v15
	s_nop 0
	v_readlane_b32 s71, v14, 63
	s_nop 1
	v_fma_f32 v11, s71, v241, v11
	v_fma_f32 v10, s71, v241, v10
	v_fma_f32 v13, s71, v241, v13
	v_fmac_f32_e32 v12, s71, v241
	v_pk_mul_f32 v[14:15], v[12:13], v[12:13]
	v_pk_mul_f32 v[16:17], v[10:11], v[10:11]
	s_nop 0
	v_pk_mov_b32 v[18:19], v[16:17], v[14:15] op_sel:[1,0]
	v_mov_b32_e32 v17, v15
	v_pk_add_f32 v[14:15], v[18:19], v[16:17]
	s_nop 0
	v_add_f32_e32 v14, v14, v15
	v_mov_b32_e32 v15, v1
	s_nop 0
	v_add_f32_dpp v14, v14, v14 row_shr:1 row_mask:0xf bank_mask:0xf bound_ctrl:1
	s_nop 1
	v_add_f32_dpp v14, v14, v14 row_shr:2 row_mask:0xf bank_mask:0xf bound_ctrl:1
	s_nop 1
	v_add_f32_dpp v14, v14, v14 row_shr:4 row_mask:0xf bank_mask:0xf bound_ctrl:1
	s_nop 1
	v_add_f32_dpp v14, v14, v14 row_shr:8 row_mask:0xf bank_mask:0xf bound_ctrl:1
	s_nop 1
	v_mov_b32_dpp v15, v14 row_bcast:15 row_mask:0xa bank_mask:0xf
	v_add_f32_e32 v14, v14, v15
	v_mov_b32_e32 v15, v1
	s_nop 1
	v_mov_b32_dpp v15, v14 row_bcast:31 row_mask:0xc bank_mask:0xf
	v_add_f32_e32 v14, v14, v15
	s_nop 0
	v_readlane_b32 s71, v14, 63
	s_nop 1
	v_fma_f32 v14, s71, v242, v197
	v_rsq_f32_e32 v14, v14
	s_nop 0
	v_pk_mul_f32 v[10:11], v[10:11], v[14:15] op_sel_hi:[1,0]
	s_nop 0
	v_pk_fma_f32 v[10:11], v[2:3], v[10:11], v[6:7]
	v_pk_mul_f32 v[12:13], v[12:13], v[14:15] op_sel_hi:[1,0]
	v_mul_f32_e32 v14, 0xbfb8aa3b, v10
	v_exp_f32_e32 v14, v14
	v_pk_fma_f32 v[12:13], v[4:5], v[12:13], v[8:9]
	v_add_f32_e32 v14, 1.0, v14
	v_rcp_f32_e32 v14, v14
	s_nop 0
	v_mul_f32_e32 v10, v10, v14
	v_mul_f32_e32 v14, 0xbfb8aa3b, v11
	v_exp_f32_e32 v14, v14
	s_nop 0
	v_add_f32_e32 v14, 1.0, v14
	v_rcp_f32_e32 v14, v14
	s_nop 0
	v_mul_f32_e32 v11, v11, v14
	v_cvt_pk_bf16_f32 v10, v10, v11
	v_mul_f32_e32 v11, 0xbfb8aa3b, v12
	v_exp_f32_e32 v11, v11
	s_nop 0
	v_add_f32_e32 v11, 1.0, v11
	v_rcp_f32_e32 v11, v11
	s_nop 0
	v_mul_f32_e32 v11, v12, v11
	v_mul_f32_e32 v12, 0xbfb8aa3b, v13
	v_exp_f32_e32 v12, v12
	s_nop 0
	v_add_f32_e32 v12, 1.0, v12
	v_rcp_f32_e32 v12, v12
	s_nop 0
	v_mul_f32_e32 v12, v13, v12
	v_cvt_pk_bf16_f32 v11, v11, v12
	v_lshl_add_u64 v[12:13], v[60:61], 0, s[72:73]
	global_store_dwordx2 v[12:13], v[10:11], off offset:1536
	ds_read_b128 v[10:13], v48
	s_add_i32 s72, s70, s91
	s_ashr_i32 s73, s72, 31
	s_lshl_b64 s[72:73], s[72:73], 11
	s_waitcnt lgkmcnt(0)
	v_mov_b32_e32 v14, v11
	v_mov_b32_e32 v15, v12
	v_mov_b32_e32 v16, v10
	v_mov_b32_e32 v17, v13
	v_pk_add_f32 v[14:15], v[14:15], v[16:17]
	s_nop 0
	v_add_f32_e32 v14, v14, v15
	v_mov_b32_e32 v15, v1
	s_nop 0
	v_add_f32_dpp v14, v14, v14 row_shr:1 row_mask:0xf bank_mask:0xf bound_ctrl:1
	s_nop 1
	v_add_f32_dpp v14, v14, v14 row_shr:2 row_mask:0xf bank_mask:0xf bound_ctrl:1
	s_nop 1
	v_add_f32_dpp v14, v14, v14 row_shr:4 row_mask:0xf bank_mask:0xf bound_ctrl:1
	s_nop 1
	v_add_f32_dpp v14, v14, v14 row_shr:8 row_mask:0xf bank_mask:0xf bound_ctrl:1
	s_nop 1
	v_mov_b32_dpp v15, v14 row_bcast:15 row_mask:0xa bank_mask:0xf
	v_add_f32_e32 v14, v14, v15
	v_mov_b32_e32 v15, v1
	s_nop 1
	v_mov_b32_dpp v15, v14 row_bcast:31 row_mask:0xc bank_mask:0xf
	v_add_f32_e32 v14, v14, v15
	s_nop 0
	v_readlane_b32 s71, v14, 63
	s_nop 1
	v_fma_f32 v11, s71, v241, v11
	v_fma_f32 v10, s71, v241, v10
	v_fma_f32 v13, s71, v241, v13
	v_fmac_f32_e32 v12, s71, v241
	v_pk_mul_f32 v[14:15], v[12:13], v[12:13]
	v_pk_mul_f32 v[16:17], v[10:11], v[10:11]
	s_nop 0
	v_pk_mov_b32 v[18:19], v[16:17], v[14:15] op_sel:[1,0]
	v_mov_b32_e32 v17, v15
	v_pk_add_f32 v[14:15], v[18:19], v[16:17]
	s_nop 0
	v_add_f32_e32 v14, v14, v15
	v_mov_b32_e32 v15, v1
	s_nop 0
	v_add_f32_dpp v14, v14, v14 row_shr:1 row_mask:0xf bank_mask:0xf bound_ctrl:1
	s_nop 1
	v_add_f32_dpp v14, v14, v14 row_shr:2 row_mask:0xf bank_mask:0xf bound_ctrl:1
	s_nop 1
	v_add_f32_dpp v14, v14, v14 row_shr:4 row_mask:0xf bank_mask:0xf bound_ctrl:1
	s_nop 1
	v_add_f32_dpp v14, v14, v14 row_shr:8 row_mask:0xf bank_mask:0xf bound_ctrl:1
	s_nop 1
	v_mov_b32_dpp v15, v14 row_bcast:15 row_mask:0xa bank_mask:0xf
	v_add_f32_e32 v14, v14, v15
	v_mov_b32_e32 v15, v1
	s_nop 1
	v_mov_b32_dpp v15, v14 row_bcast:31 row_mask:0xc bank_mask:0xf
	v_add_f32_e32 v14, v14, v15
	s_nop 0
	v_readlane_b32 s71, v14, 63
	s_nop 1
	v_fma_f32 v14, s71, v242, v197
	v_rsq_f32_e32 v14, v14
	s_nop 0
	v_pk_mul_f32 v[10:11], v[10:11], v[14:15] op_sel_hi:[1,0]
	s_nop 0
	v_pk_fma_f32 v[10:11], v[2:3], v[10:11], v[6:7]
	v_pk_mul_f32 v[12:13], v[12:13], v[14:15] op_sel_hi:[1,0]
	v_mul_f32_e32 v14, 0xbfb8aa3b, v10
	v_exp_f32_e32 v14, v14
	v_pk_fma_f32 v[12:13], v[4:5], v[12:13], v[8:9]
	v_add_f32_e32 v14, 1.0, v14
	v_rcp_f32_e32 v14, v14
	s_nop 0
	v_mul_f32_e32 v10, v10, v14
	v_mul_f32_e32 v14, 0xbfb8aa3b, v11
	v_exp_f32_e32 v14, v14
	s_nop 0
	v_add_f32_e32 v14, 1.0, v14
	v_rcp_f32_e32 v14, v14
	s_nop 0
	v_mul_f32_e32 v11, v11, v14
	v_cvt_pk_bf16_f32 v10, v10, v11
	v_mul_f32_e32 v11, 0xbfb8aa3b, v12
	v_exp_f32_e32 v11, v11
	s_nop 0
	v_add_f32_e32 v11, 1.0, v11
	v_rcp_f32_e32 v11, v11
	s_nop 0
	v_mul_f32_e32 v11, v12, v11
	v_mul_f32_e32 v12, 0xbfb8aa3b, v13
	v_exp_f32_e32 v12, v12
	s_nop 0
	v_add_f32_e32 v12, 1.0, v12
	v_rcp_f32_e32 v12, v12
	s_nop 0
	v_mul_f32_e32 v12, v13, v12
	v_cvt_pk_bf16_f32 v11, v11, v12
	v_lshl_add_u64 v[12:13], v[60:61], 0, s[72:73]
	global_store_dwordx2 v[12:13], v[10:11], off offset:1536
	ds_read_b128 v[10:13], v49
	s_add_i32 s72, s70, s87
	s_or_b32 s70, s70, 32
	s_ashr_i32 s73, s72, 31
	s_lshl_b64 s[72:73], s[72:73], 11
	s_waitcnt lgkmcnt(0)
	v_mov_b32_e32 v14, v11
	v_mov_b32_e32 v15, v12
	v_mov_b32_e32 v16, v10
	v_mov_b32_e32 v17, v13
	v_pk_add_f32 v[14:15], v[14:15], v[16:17]
	s_nop 0
	v_add_f32_e32 v14, v14, v15
	v_mov_b32_e32 v15, v1
	s_nop 0
	v_add_f32_dpp v14, v14, v14 row_shr:1 row_mask:0xf bank_mask:0xf bound_ctrl:1
	s_nop 1
	v_add_f32_dpp v14, v14, v14 row_shr:2 row_mask:0xf bank_mask:0xf bound_ctrl:1
	s_nop 1
	v_add_f32_dpp v14, v14, v14 row_shr:4 row_mask:0xf bank_mask:0xf bound_ctrl:1
	s_nop 1
	v_add_f32_dpp v14, v14, v14 row_shr:8 row_mask:0xf bank_mask:0xf bound_ctrl:1
	s_nop 1
	v_mov_b32_dpp v15, v14 row_bcast:15 row_mask:0xa bank_mask:0xf
	v_add_f32_e32 v14, v14, v15
	v_mov_b32_e32 v15, v1
	s_nop 1
	v_mov_b32_dpp v15, v14 row_bcast:31 row_mask:0xc bank_mask:0xf
	v_add_f32_e32 v14, v14, v15
	s_nop 0
	v_readlane_b32 s71, v14, 63
	s_nop 1
	v_fma_f32 v11, s71, v241, v11
	v_fma_f32 v10, s71, v241, v10
	v_fma_f32 v13, s71, v241, v13
	v_fmac_f32_e32 v12, s71, v241
	v_pk_mul_f32 v[14:15], v[12:13], v[12:13]
	v_pk_mul_f32 v[16:17], v[10:11], v[10:11]
	s_nop 0
	v_pk_mov_b32 v[18:19], v[16:17], v[14:15] op_sel:[1,0]
	v_mov_b32_e32 v17, v15
	v_pk_add_f32 v[14:15], v[18:19], v[16:17]
	s_nop 0
	v_add_f32_e32 v14, v14, v15
	v_mov_b32_e32 v15, v1
	s_nop 0
	v_add_f32_dpp v14, v14, v14 row_shr:1 row_mask:0xf bank_mask:0xf bound_ctrl:1
	s_nop 1
	v_add_f32_dpp v14, v14, v14 row_shr:2 row_mask:0xf bank_mask:0xf bound_ctrl:1
	s_nop 1
	v_add_f32_dpp v14, v14, v14 row_shr:4 row_mask:0xf bank_mask:0xf bound_ctrl:1
	s_nop 1
	v_add_f32_dpp v14, v14, v14 row_shr:8 row_mask:0xf bank_mask:0xf bound_ctrl:1
	s_nop 1
	v_mov_b32_dpp v15, v14 row_bcast:15 row_mask:0xa bank_mask:0xf
	v_add_f32_e32 v14, v14, v15
	v_mov_b32_e32 v15, v1
	s_nop 1
	v_mov_b32_dpp v15, v14 row_bcast:31 row_mask:0xc bank_mask:0xf
	v_add_f32_e32 v14, v14, v15
	s_nop 0
	v_readlane_b32 s71, v14, 63
	s_nop 1
	v_fma_f32 v14, s71, v242, v197
	v_rsq_f32_e32 v14, v14
	s_and_b32 s71, s70, 0xfe0
	s_sub_i32 s71, 29, s71
	v_cmp_lt_i32_e32 vcc, s71, v123
	v_pk_mul_f32 v[10:11], v[10:11], v[14:15] op_sel_hi:[1,0]
	v_pk_mul_f32 v[12:13], v[12:13], v[14:15] op_sel_hi:[1,0]
	v_pk_fma_f32 v[10:11], v[2:3], v[10:11], v[6:7]
	v_pk_fma_f32 v[12:13], v[4:5], v[12:13], v[8:9]
	v_mul_f32_e32 v14, 0xbfb8aa3b, v10
	v_exp_f32_e32 v14, v14
	v_cndmask_b32_e64 v18, 0, 1.0, vcc
	v_add_f32_e32 v14, 1.0, v14
	v_rcp_f32_e32 v14, v14
	s_nop 0
	v_mul_f32_e32 v10, v10, v14
	v_mul_f32_e32 v14, 0xbfb8aa3b, v11
	v_exp_f32_e32 v14, v14
	s_nop 0
	v_add_f32_e32 v14, 1.0, v14
	v_rcp_f32_e32 v14, v14
	s_nop 0
	v_mul_f32_e32 v11, v11, v14
	v_cvt_pk_bf16_f32 v10, v10, v11
	v_mul_f32_e32 v11, 0xbfb8aa3b, v12
	v_exp_f32_e32 v11, v11
	s_nop 0
	v_add_f32_e32 v11, 1.0, v11
	v_rcp_f32_e32 v11, v11
	s_nop 0
	v_mul_f32_e32 v11, v12, v11
	v_mul_f32_e32 v12, 0xbfb8aa3b, v13
	v_exp_f32_e32 v12, v12
	s_nop 0
	v_add_f32_e32 v12, 1.0, v12
	v_rcp_f32_e32 v12, v12
	s_nop 0
	v_mul_f32_e32 v12, v13, v12
	v_cvt_pk_bf16_f32 v11, v11, v12
	v_lshl_add_u64 v[12:13], v[60:61], 0, s[72:73]
	global_store_dwordx2 v[12:13], v[10:11], off offset:1536
	v_cndmask_b32_e32 v10, 0, v124, vcc
	v_add_u32_e32 v10, s70, v10
	v_mad_i64_i32 v[10:11], s[72:73], v10, s33, v[86:87]
	v_lshl_add_u64 v[10:11], v[10:11], 0, v[0:1]
	v_add_co_u32_e32 v14, vcc, s82, v10
	s_nop 1
	v_addc_co_u32_e32 v15, vcc, 0, v11, vcc
	global_load_dwordx4 v[10:13], v[14:15], off offset:512
	s_nop 0
	global_load_dwordx4 v[14:17], v[14:15], off offset:1024
	v_cmp_lt_i32_e32 vcc, s71, v126
	s_waitcnt vmcnt(1)
	v_lshlrev_b32_e32 v22, 16, v10
	s_waitcnt vmcnt(0)
	v_lshlrev_b32_e32 v19, 16, v14
	v_and_b32_e32 v14, 0xffff0000, v14
	v_and_b32_e32 v23, 0xffff0000, v10
	v_lshlrev_b32_e32 v10, 16, v15
	v_mul_f32_e32 v19, 0xbfb8aa3b, v19
	v_mul_f32_e32 v14, 0xbfb8aa3b, v14
	v_mul_f32_e32 v10, 0xbfb8aa3b, v10
	v_exp_f32_e32 v19, v19
	v_exp_f32_e32 v14, v14
	v_exp_f32_e32 v10, v10
	v_add_f32_e32 v19, 1.0, v19
	v_add_f32_e32 v14, 1.0, v14
	v_add_f32_e32 v10, 1.0, v10
	v_rcp_f32_e32 v20, v19
	v_rcp_f32_e32 v21, v14
	v_rcp_f32_e32 v14, v10
	v_and_b32_e32 v10, 0xffff0000, v15
	v_mul_f32_e32 v10, 0xbfb8aa3b, v10
	v_exp_f32_e32 v10, v10
	v_pk_mul_f32 v[20:21], v[20:21], v[22:23]
	v_lshlrev_b32_e32 v22, 16, v12
	v_and_b32_e32 v23, 0xffff0000, v12
	v_lshlrev_b32_e32 v12, 16, v17
	v_mul_f32_e32 v12, 0xbfb8aa3b, v12
	v_add_f32_e32 v10, 1.0, v10
	v_exp_f32_e32 v12, v12
	v_rcp_f32_e32 v15, v10
	v_lshlrev_b32_e32 v10, 16, v11
	v_and_b32_e32 v11, 0xffff0000, v11
	v_add_f32_e32 v12, 1.0, v12
	v_pk_mul_f32 v[10:11], v[14:15], v[10:11]
	v_lshlrev_b32_e32 v14, 16, v16
	v_and_b32_e32 v15, 0xffff0000, v16
	v_rcp_f32_e32 v16, v12
	v_and_b32_e32 v12, 0xffff0000, v17
	v_mul_f32_e32 v14, 0xbfb8aa3b, v14
	v_mul_f32_e32 v15, 0xbfb8aa3b, v15
	v_mul_f32_e32 v12, 0xbfb8aa3b, v12
	v_exp_f32_e32 v14, v14
	v_exp_f32_e32 v15, v15
	v_exp_f32_e32 v12, v12
	v_add_f32_e32 v14, 1.0, v14
	v_add_f32_e32 v15, 1.0, v15
	v_add_f32_e32 v12, 1.0, v12
	v_rcp_f32_e32 v14, v14
	v_rcp_f32_e32 v15, v15
	v_rcp_f32_e32 v17, v12
	v_lshlrev_b32_e32 v12, 16, v13
	v_and_b32_e32 v13, 0xffff0000, v13
	v_pk_mul_f32 v[14:15], v[14:15], v[22:23]
	v_pk_mul_f32 v[16:17], v[16:17], v[12:13]
	v_pk_mul_f32 v[12:13], v[18:19], v[10:11] op_sel_hi:[0,1]
	v_pk_mul_f32 v[10:11], v[18:19], v[20:21] op_sel_hi:[0,1]
	ds_write_b128 v125, v[10:13] offset:36864
	v_pk_mul_f32 v[12:13], v[18:19], v[16:17] op_sel_hi:[0,1]
	v_pk_mul_f32 v[10:11], v[18:19], v[14:15] op_sel_hi:[0,1]
	ds_write_b128 v125, v[10:13] offset:36880
	v_cndmask_b32_e32 v10, 0, v127, vcc
	v_add_u32_e32 v10, s70, v10
	v_mad_i64_i32 v[10:11], s[72:73], v10, s33, v[86:87]
	v_lshl_add_u64 v[10:11], v[10:11], 0, v[62:63]
	v_cndmask_b32_e64 v18, 0, 1.0, vcc
	v_add_co_u32_e32 v14, vcc, s82, v10
	s_nop 1
	v_addc_co_u32_e32 v15, vcc, 0, v11, vcc
	global_load_dwordx4 v[10:13], v[14:15], off offset:512
	s_nop 0
	global_load_dwordx4 v[14:17], v[14:15], off offset:1024
	v_cmp_lt_i32_e32 vcc, s71, v129
	s_waitcnt vmcnt(1)
	v_lshlrev_b32_e32 v22, 16, v10
	s_waitcnt vmcnt(0)
	v_lshlrev_b32_e32 v19, 16, v14
	v_and_b32_e32 v14, 0xffff0000, v14
	v_and_b32_e32 v23, 0xffff0000, v10
	v_lshlrev_b32_e32 v10, 16, v15
	v_mul_f32_e32 v19, 0xbfb8aa3b, v19
	v_mul_f32_e32 v14, 0xbfb8aa3b, v14
	v_mul_f32_e32 v10, 0xbfb8aa3b, v10
	v_exp_f32_e32 v19, v19
	v_exp_f32_e32 v14, v14
	v_exp_f32_e32 v10, v10
	v_add_f32_e32 v19, 1.0, v19
	v_add_f32_e32 v14, 1.0, v14
	v_add_f32_e32 v10, 1.0, v10
	v_rcp_f32_e32 v20, v19
	v_rcp_f32_e32 v21, v14
	v_rcp_f32_e32 v14, v10
	v_and_b32_e32 v10, 0xffff0000, v15
	v_mul_f32_e32 v10, 0xbfb8aa3b, v10
	v_exp_f32_e32 v10, v10
	v_pk_mul_f32 v[20:21], v[20:21], v[22:23]
	v_lshlrev_b32_e32 v22, 16, v12
	v_and_b32_e32 v23, 0xffff0000, v12
	v_lshlrev_b32_e32 v12, 16, v17
	v_mul_f32_e32 v12, 0xbfb8aa3b, v12
	v_add_f32_e32 v10, 1.0, v10
	v_exp_f32_e32 v12, v12
	v_rcp_f32_e32 v15, v10
	v_lshlrev_b32_e32 v10, 16, v11
	v_and_b32_e32 v11, 0xffff0000, v11
	v_add_f32_e32 v12, 1.0, v12
	v_pk_mul_f32 v[10:11], v[14:15], v[10:11]
	v_lshlrev_b32_e32 v14, 16, v16
	v_and_b32_e32 v15, 0xffff0000, v16
	v_rcp_f32_e32 v16, v12
	v_and_b32_e32 v12, 0xffff0000, v17
	v_mul_f32_e32 v14, 0xbfb8aa3b, v14
	v_mul_f32_e32 v15, 0xbfb8aa3b, v15
	v_mul_f32_e32 v12, 0xbfb8aa3b, v12
	v_exp_f32_e32 v14, v14
	v_exp_f32_e32 v15, v15
	v_exp_f32_e32 v12, v12
	v_add_f32_e32 v14, 1.0, v14
	v_add_f32_e32 v15, 1.0, v15
	v_add_f32_e32 v12, 1.0, v12
	v_rcp_f32_e32 v14, v14
	v_rcp_f32_e32 v15, v15
	v_rcp_f32_e32 v17, v12
	v_lshlrev_b32_e32 v12, 16, v13
	v_and_b32_e32 v13, 0xffff0000, v13
	v_pk_mul_f32 v[14:15], v[14:15], v[22:23]
	v_pk_mul_f32 v[16:17], v[16:17], v[12:13]
	v_pk_mul_f32 v[12:13], v[18:19], v[10:11] op_sel_hi:[0,1]
	v_pk_mul_f32 v[10:11], v[18:19], v[20:21] op_sel_hi:[0,1]
	ds_write_b128 v128, v[10:13] offset:36864
	v_pk_mul_f32 v[12:13], v[18:19], v[16:17] op_sel_hi:[0,1]
	v_pk_mul_f32 v[10:11], v[18:19], v[14:15] op_sel_hi:[0,1]
	ds_write_b128 v128, v[10:13] offset:36880
	v_cndmask_b32_e32 v10, 0, v130, vcc
	v_add_u32_e32 v10, s70, v10
	v_mad_i64_i32 v[10:11], s[72:73], v10, s33, v[86:87]
	v_lshl_add_u64 v[10:11], v[10:11], 0, v[64:65]
	v_cndmask_b32_e64 v18, 0, 1.0, vcc
	v_add_co_u32_e32 v14, vcc, s82, v10
	s_nop 1
	v_addc_co_u32_e32 v15, vcc, 0, v11, vcc
	global_load_dwordx4 v[10:13], v[14:15], off offset:512
	s_nop 0
	global_load_dwordx4 v[14:17], v[14:15], off offset:1024
	v_cmp_lt_i32_e32 vcc, s71, v132
	s_waitcnt vmcnt(1)
	v_lshlrev_b32_e32 v22, 16, v10
	s_waitcnt vmcnt(0)
; __device__ __forceinline__ void mixer_bd(const bf16_t* __restrict__ Z, bf16_t* __restrict__ Y, const float* __restrict__ lng, const float* __restrict__ lnb, const float* __restrict__ wsp, const float* __restrict__ bsp, ...
;     ...
;         __syncthreads();
	v_lshlrev_b32_e32 v19, 16, v14
	v_and_b32_e32 v14, 0xffff0000, v14
	v_and_b32_e32 v23, 0xffff0000, v10
	v_lshlrev_b32_e32 v10, 16, v15
	v_mul_f32_e32 v19, 0xbfb8aa3b, v19
	v_mul_f32_e32 v14, 0xbfb8aa3b, v14
	v_mul_f32_e32 v10, 0xbfb8aa3b, v10
	v_exp_f32_e32 v19, v19
	v_exp_f32_e32 v14, v14
	v_exp_f32_e32 v10, v10
	v_add_f32_e32 v19, 1.0, v19
	v_add_f32_e32 v14, 1.0, v14
	v_add_f32_e32 v10, 1.0, v10
	v_rcp_f32_e32 v20, v19
	v_rcp_f32_e32 v21, v14
	v_rcp_f32_e32 v14, v10
	v_and_b32_e32 v10, 0xffff0000, v15
	v_mul_f32_e32 v10, 0xbfb8aa3b, v10
	v_exp_f32_e32 v10, v10
	v_pk_mul_f32 v[20:21], v[20:21], v[22:23]
	v_lshlrev_b32_e32 v22, 16, v12
	v_and_b32_e32 v23, 0xffff0000, v12
	v_lshlrev_b32_e32 v12, 16, v17
	v_mul_f32_e32 v12, 0xbfb8aa3b, v12
	v_add_f32_e32 v10, 1.0, v10
	v_exp_f32_e32 v12, v12
	v_rcp_f32_e32 v15, v10
	v_lshlrev_b32_e32 v10, 16, v11
	v_and_b32_e32 v11, 0xffff0000, v11
	v_add_f32_e32 v12, 1.0, v12
	v_pk_mul_f32 v[10:11], v[14:15], v[10:11]
	v_lshlrev_b32_e32 v14, 16, v16
	v_and_b32_e32 v15, 0xffff0000, v16
	v_rcp_f32_e32 v16, v12
	v_and_b32_e32 v12, 0xffff0000, v17
	v_mul_f32_e32 v14, 0xbfb8aa3b, v14
	v_mul_f32_e32 v15, 0xbfb8aa3b, v15
	v_mul_f32_e32 v12, 0xbfb8aa3b, v12
	v_exp_f32_e32 v14, v14
	v_exp_f32_e32 v15, v15
	v_exp_f32_e32 v12, v12
	v_add_f32_e32 v14, 1.0, v14
	v_add_f32_e32 v15, 1.0, v15
	v_add_f32_e32 v12, 1.0, v12
	v_rcp_f32_e32 v14, v14
	v_rcp_f32_e32 v15, v15
	v_rcp_f32_e32 v17, v12
	v_lshlrev_b32_e32 v12, 16, v13
	v_and_b32_e32 v13, 0xffff0000, v13
	v_pk_mul_f32 v[14:15], v[14:15], v[22:23]
	v_pk_mul_f32 v[16:17], v[16:17], v[12:13]
	v_pk_mul_f32 v[12:13], v[18:19], v[10:11] op_sel_hi:[0,1]
	v_pk_mul_f32 v[10:11], v[18:19], v[20:21] op_sel_hi:[0,1]
	ds_write_b128 v131, v[10:13] offset:36864
	v_pk_mul_f32 v[12:13], v[18:19], v[16:17] op_sel_hi:[0,1]
	v_pk_mul_f32 v[10:11], v[18:19], v[14:15] op_sel_hi:[0,1]
	ds_write_b128 v131, v[10:13] offset:36880
	v_cndmask_b32_e32 v10, 0, v133, vcc
	v_add_u32_e32 v10, s70, v10
	v_mad_i64_i32 v[10:11], s[72:73], v10, s33, v[86:87]
	v_lshl_add_u64 v[10:11], v[10:11], 0, v[66:67]
	v_cndmask_b32_e64 v18, 0, 1.0, vcc
	v_add_co_u32_e32 v14, vcc, s82, v10
	s_add_i32 s72, s70, s84
	s_nop 0
	v_addc_co_u32_e32 v15, vcc, 0, v11, vcc
	global_load_dwordx4 v[10:13], v[14:15], off offset:512
	s_nop 0
	global_load_dwordx4 v[14:17], v[14:15], off offset:1024
	s_ashr_i32 s73, s72, 31
	s_lshl_b64 s[72:73], s[72:73], 11
	s_waitcnt vmcnt(1)
	v_lshlrev_b32_e32 v22, 16, v10
	s_waitcnt vmcnt(0)
	v_lshlrev_b32_e32 v19, 16, v14
	v_and_b32_e32 v14, 0xffff0000, v14
	v_and_b32_e32 v23, 0xffff0000, v10
	v_lshlrev_b32_e32 v10, 16, v15
	v_mul_f32_e32 v19, 0xbfb8aa3b, v19
	v_mul_f32_e32 v14, 0xbfb8aa3b, v14
	v_mul_f32_e32 v10, 0xbfb8aa3b, v10
	v_exp_f32_e32 v19, v19
	v_exp_f32_e32 v14, v14
	v_exp_f32_e32 v10, v10
	v_add_f32_e32 v19, 1.0, v19
	v_add_f32_e32 v14, 1.0, v14
	v_add_f32_e32 v10, 1.0, v10
	v_rcp_f32_e32 v20, v19
	v_rcp_f32_e32 v21, v14
	v_rcp_f32_e32 v14, v10
	v_and_b32_e32 v10, 0xffff0000, v15
	v_mul_f32_e32 v10, 0xbfb8aa3b, v10
	v_exp_f32_e32 v10, v10
	v_pk_mul_f32 v[20:21], v[20:21], v[22:23]
	v_lshlrev_b32_e32 v22, 16, v12
	v_and_b32_e32 v23, 0xffff0000, v12
	v_lshlrev_b32_e32 v12, 16, v17
	v_mul_f32_e32 v12, 0xbfb8aa3b, v12
	v_add_f32_e32 v10, 1.0, v10
	v_exp_f32_e32 v12, v12
	v_rcp_f32_e32 v15, v10
	v_lshlrev_b32_e32 v10, 16, v11
	v_and_b32_e32 v11, 0xffff0000, v11
	v_add_f32_e32 v12, 1.0, v12
	v_pk_mul_f32 v[10:11], v[14:15], v[10:11]
	v_lshlrev_b32_e32 v14, 16, v16
	v_and_b32_e32 v15, 0xffff0000, v16
	v_rcp_f32_e32 v16, v12
	v_and_b32_e32 v12, 0xffff0000, v17
	v_mul_f32_e32 v14, 0xbfb8aa3b, v14
	v_mul_f32_e32 v15, 0xbfb8aa3b, v15
	v_mul_f32_e32 v12, 0xbfb8aa3b, v12
	v_exp_f32_e32 v14, v14
	v_exp_f32_e32 v15, v15
	v_exp_f32_e32 v12, v12
	v_add_f32_e32 v14, 1.0, v14
	v_add_f32_e32 v15, 1.0, v15
	v_add_f32_e32 v12, 1.0, v12
	v_rcp_f32_e32 v14, v14
	v_rcp_f32_e32 v15, v15
	v_rcp_f32_e32 v17, v12
	v_lshlrev_b32_e32 v12, 16, v13
	v_and_b32_e32 v13, 0xffff0000, v13
	v_pk_mul_f32 v[14:15], v[14:15], v[22:23]
	v_pk_mul_f32 v[16:17], v[16:17], v[12:13]
	v_pk_mul_f32 v[12:13], v[18:19], v[10:11] op_sel_hi:[0,1]
	v_pk_mul_f32 v[10:11], v[18:19], v[20:21] op_sel_hi:[0,1]
	ds_write_b128 v134, v[10:13] offset:36864
	v_pk_mul_f32 v[12:13], v[18:19], v[16:17] op_sel_hi:[0,1]
	v_pk_mul_f32 v[10:11], v[18:19], v[14:15] op_sel_hi:[0,1]
	ds_write_b128 v134, v[10:13] offset:36880
	s_waitcnt lgkmcnt(0)
	s_barrier
	ds_read2st64_b32 v[10:11], v136 offset0:144 offset1:148
	ds_read2st64_b32 v[12:13], v136 offset0:180 offset1:184
	ds_read2st64_b32 v[14:15], v136 offset0:184 offset1:188
	ds_read2st64_b32 v[16:17], v136 offset0:188 offset1:192
	ds_read2st64_b32 v[18:19], v136 offset0:192 offset1:196
	s_waitcnt lgkmcnt(4)
	v_fma_f32 v63, v116, v10, v120
	v_fmac_f32_e32 v63, v117, v11
	v_fma_f32 v65, v116, v11, v120
	ds_read2st64_b32 v[10:11], v136 offset0:152 offset1:156
	ds_read2st64_b32 v[20:21], v136 offset0:196 offset1:200
	ds_read2st64_b32 v[22:23], v136 offset0:200 offset1:204
	ds_read2st64_b32 v[24:25], v136 offset0:204 offset1:208
	ds_read2st64_b32 v[26:27], v136 offset0:212 offset1:216
	s_waitcnt lgkmcnt(4)
	v_fmac_f32_e32 v63, v118, v10
	v_fmac_f32_e32 v65, v117, v10
	v_fma_f32 v67, v116, v10, v120
	v_fmac_f32_e32 v63, v119, v11
	v_fmac_f32_e32 v65, v118, v11
	v_fmac_f32_e32 v67, v117, v11
	v_fma_f32 v68, v116, v11, v120
	ds_read2st64_b32 v[10:11], v136 offset0:160 offset1:164
	ds_read2st64_b32 v[28:29], v136 offset0:220 offset1:224
	ds_read2st64_b32 v[30:31], v136 offset0:228 offset1:232
	ds_read2st64_b32 v[32:33], v136 offset0:236 offset1:240
	ds_read2st64_b32 v[34:35], v136 offset0:244 offset1:248
	s_waitcnt lgkmcnt(4)
	v_fmac_f32_e32 v63, v89, v10
	v_fmac_f32_e32 v65, v119, v10
	v_fmac_f32_e32 v67, v118, v10
	v_fmac_f32_e32 v68, v117, v10
	v_fma_f32 v69, v116, v10, v120
	v_fmac_f32_e32 v63, v97, v11
	v_fmac_f32_e32 v65, v89, v11
	v_fmac_f32_e32 v67, v119, v11
	v_fmac_f32_e32 v68, v118, v11
	v_fmac_f32_e32 v69, v117, v11
	v_fma_f32 v70, v116, v11, v120
	ds_read2st64_b32 v[10:11], v136 offset0:168 offset1:172
	ds_read2st64_b32 v[36:37], v137 offset0:112 offset1:116
	ds_read2st64_b32 v[38:39], v137 offset0:120 offset1:124
	ds_read2st64_b32 v[40:41], v137 offset0:128 offset1:132
	ds_read2st64_b32 v[42:43], v137 offset0:136 offset1:140
	s_waitcnt lgkmcnt(4)
	v_fmac_f32_e32 v63, v98, v10
	v_fmac_f32_e32 v65, v97, v10
	v_fmac_f32_e32 v67, v89, v10
	v_fmac_f32_e32 v68, v119, v10
	v_fmac_f32_e32 v69, v118, v10
	v_fmac_f32_e32 v70, v117, v10
	v_fma_f32 v71, v116, v10, v120
	v_fmac_f32_e32 v63, v99, v11
	v_fmac_f32_e32 v65, v98, v11
	v_fmac_f32_e32 v67, v97, v11
	v_fmac_f32_e32 v68, v89, v11
	v_fmac_f32_e32 v69, v119, v11
	v_fmac_f32_e32 v70, v118, v11
	v_fmac_f32_e32 v71, v117, v11
	v_fma_f32 v72, v116, v11, v120
	ds_read2st64_b32 v[10:11], v136 offset0:176 offset1:180
	ds_read2st64_b32 v[44:45], v137 offset0:144 offset1:148
	s_waitcnt lgkmcnt(1)
	v_fmac_f32_e32 v72, v117, v10
	v_fmac_f32_e32 v71, v118, v10
	v_fmac_f32_e32 v72, v118, v11
	v_fmac_f32_e32 v70, v119, v10
	v_fmac_f32_e32 v71, v119, v11
	v_fmac_f32_e32 v72, v119, v13
	v_fmac_f32_e32 v69, v89, v10
	v_fmac_f32_e32 v70, v89, v11
	v_fmac_f32_e32 v71, v89, v13
	v_fmac_f32_e32 v72, v89, v15
	v_fmac_f32_e32 v68, v97, v10
	v_fmac_f32_e32 v69, v97, v11
	v_fmac_f32_e32 v70, v97, v13
	v_fmac_f32_e32 v71, v97, v15
	v_fmac_f32_e32 v72, v97, v17
	v_fmac_f32_e32 v63, v90, v10
	v_fmac_f32_e32 v65, v99, v10
	v_fmac_f32_e32 v67, v98, v10
	v_fmac_f32_e32 v68, v98, v11
	v_fmac_f32_e32 v69, v98, v13
	v_fmac_f32_e32 v70, v98, v15
	v_fmac_f32_e32 v71, v98, v17
	v_fmac_f32_e32 v72, v98, v19
	v_fmac_f32_e32 v63, v91, v11
	v_fmac_f32_e32 v65, v90, v11
	v_fmac_f32_e32 v67, v99, v11
	v_fmac_f32_e32 v68, v99, v13
	v_fmac_f32_e32 v69, v99, v15
	v_fmac_f32_e32 v70, v99, v17
	v_fmac_f32_e32 v71, v99, v19
	v_fmac_f32_e32 v72, v99, v21
	v_fma_f32 v10, v116, v10, v120
	v_fma_f32 v11, v116, v12, v120
	v_fmac_f32_e32 v65, v91, v13
	v_fmac_f32_e32 v67, v90, v13
	v_fmac_f32_e32 v68, v90, v15
	v_fmac_f32_e32 v69, v90, v17
	v_fmac_f32_e32 v70, v90, v19
	v_fmac_f32_e32 v71, v90, v21
	v_fmac_f32_e32 v72, v90, v23
	v_fmac_f32_e32 v10, v117, v12
	v_fmac_f32_e32 v11, v117, v14
	v_fma_f32 v12, v116, v14, v120
	v_fmac_f32_e32 v63, v92, v13
	v_fmac_f32_e32 v65, v92, v15
	v_fmac_f32_e32 v67, v91, v15
	v_fmac_f32_e32 v68, v91, v17
	v_fmac_f32_e32 v69, v91, v19
	v_fmac_f32_e32 v70, v91, v21
	v_fmac_f32_e32 v71, v91, v23
	v_fmac_f32_e32 v72, v91, v25
	v_fmac_f32_e32 v10, v118, v14
	v_fmac_f32_e32 v11, v118, v16
	v_fmac_f32_e32 v12, v117, v16
	v_fma_f32 v13, v116, v16, v120
	v_fmac_f32_e32 v63, v93, v15
	v_fmac_f32_e32 v65, v93, v17
	v_fmac_f32_e32 v67, v92, v17
	v_fmac_f32_e32 v68, v92, v19
	v_fmac_f32_e32 v69, v92, v21
	v_fmac_f32_e32 v70, v92, v23
	v_fmac_f32_e32 v71, v92, v25
	v_fmac_f32_e32 v72, v92, v26
	v_fmac_f32_e32 v10, v119, v16
	v_fmac_f32_e32 v11, v119, v18
	v_fmac_f32_e32 v12, v118, v18
	v_fmac_f32_e32 v13, v117, v18
	v_fma_f32 v14, v116, v18, v120
	v_fmac_f32_e32 v63, v94, v17
	v_fmac_f32_e32 v65, v94, v19
	v_fmac_f32_e32 v67, v93, v19
	v_fmac_f32_e32 v68, v93, v21
	v_fmac_f32_e32 v69, v93, v23
	v_fmac_f32_e32 v70, v93, v25
	v_fmac_f32_e32 v71, v93, v26
	v_fmac_f32_e32 v72, v93, v27
	v_fmac_f32_e32 v10, v89, v18
	v_fmac_f32_e32 v11, v89, v20
	v_fmac_f32_e32 v12, v119, v20
	v_fmac_f32_e32 v13, v118, v20
	v_fmac_f32_e32 v14, v117, v20
	v_fma_f32 v15, v116, v20, v120
	v_fmac_f32_e32 v63, v100, v19
	v_fmac_f32_e32 v65, v100, v21
	v_fmac_f32_e32 v67, v94, v21
	v_fmac_f32_e32 v68, v94, v23
	v_fmac_f32_e32 v69, v94, v25
	v_fmac_f32_e32 v70, v94, v26
	v_fmac_f32_e32 v71, v94, v27
	v_fmac_f32_e32 v72, v94, v28
	v_fmac_f32_e32 v10, v97, v20
	v_fmac_f32_e32 v11, v97, v22
	v_fmac_f32_e32 v12, v89, v22
	v_fmac_f32_e32 v13, v119, v22
	v_fmac_f32_e32 v14, v118, v22
	v_fmac_f32_e32 v15, v117, v22
	v_fma_f32 v16, v116, v22, v120
	v_fmac_f32_e32 v63, v101, v21
	v_fmac_f32_e32 v65, v101, v23
	v_fmac_f32_e32 v67, v100, v23
	v_fmac_f32_e32 v68, v100, v25
	v_fmac_f32_e32 v69, v100, v26
	v_fmac_f32_e32 v70, v100, v27
	v_fmac_f32_e32 v71, v100, v28
	v_fmac_f32_e32 v72, v100, v29
	v_fmac_f32_e32 v10, v98, v22
	v_fmac_f32_e32 v11, v98, v24
	v_fmac_f32_e32 v12, v97, v24
	v_fmac_f32_e32 v13, v89, v24
	v_fmac_f32_e32 v14, v119, v24
	v_fmac_f32_e32 v15, v118, v24
	v_fmac_f32_e32 v16, v117, v24
	v_fma_f32 v18, v116, v24, v120
	v_fmac_f32_e32 v63, v102, v23
	v_fmac_f32_e32 v65, v102, v25
	v_fmac_f32_e32 v67, v101, v25
	v_fmac_f32_e32 v68, v101, v26
	v_fmac_f32_e32 v69, v101, v27
	v_fmac_f32_e32 v70, v101, v28
	v_fmac_f32_e32 v71, v101, v29
	v_fmac_f32_e32 v72, v101, v30
	v_fmac_f32_e32 v10, v99, v24
	v_fmac_f32_e32 v11, v99, v25
	v_fmac_f32_e32 v12, v98, v25
	v_fmac_f32_e32 v13, v97, v25
	v_fmac_f32_e32 v14, v89, v25
	v_fmac_f32_e32 v15, v119, v25
	v_fmac_f32_e32 v16, v118, v25
	v_fmac_f32_e32 v18, v117, v25
	v_fmac_f32_e32 v63, v95, v25
	v_fmac_f32_e32 v65, v95, v26
	v_fmac_f32_e32 v67, v102, v26
	v_fmac_f32_e32 v68, v102, v27
	v_fmac_f32_e32 v69, v102, v28
	v_fmac_f32_e32 v70, v102, v29
	v_fmac_f32_e32 v71, v102, v30
	v_fmac_f32_e32 v72, v102, v31
	ds_read_b32 v17, v136 offset:64512
	v_fmac_f32_e32 v10, v90, v25
	v_fmac_f32_e32 v11, v90, v26
	v_fmac_f32_e32 v12, v99, v26
	v_fmac_f32_e32 v13, v98, v26
	v_fmac_f32_e32 v14, v97, v26
	v_fmac_f32_e32 v15, v89, v26
	v_fmac_f32_e32 v16, v119, v26
	v_fmac_f32_e32 v18, v118, v26
	v_fmac_f32_e32 v63, v96, v26
	v_fmac_f32_e32 v65, v96, v27
	v_fmac_f32_e32 v67, v95, v27
	v_fmac_f32_e32 v68, v95, v28
	v_fmac_f32_e32 v69, v95, v29
	v_fmac_f32_e32 v70, v95, v30
	v_fmac_f32_e32 v71, v95, v31
	v_fmac_f32_e32 v72, v95, v32
	v_fmac_f32_e32 v10, v91, v26
	v_fmac_f32_e32 v11, v91, v27
	v_fmac_f32_e32 v12, v90, v27
	v_fmac_f32_e32 v13, v99, v27
	v_fmac_f32_e32 v14, v98, v27
	v_fmac_f32_e32 v15, v97, v27
	v_fmac_f32_e32 v16, v89, v27
	v_fmac_f32_e32 v18, v119, v27
	v_fmac_f32_e32 v63, v105, v27
	v_fmac_f32_e32 v65, v105, v28
	v_fmac_f32_e32 v67, v96, v28
	v_fmac_f32_e32 v68, v96, v29
	v_fmac_f32_e32 v69, v96, v30
	v_fmac_f32_e32 v70, v96, v31
	v_fmac_f32_e32 v71, v96, v32
	v_fmac_f32_e32 v72, v96, v33
	v_fmac_f32_e32 v10, v92, v27
	v_fmac_f32_e32 v11, v92, v28
	v_fmac_f32_e32 v12, v91, v28
	v_fmac_f32_e32 v13, v90, v28
	v_fmac_f32_e32 v14, v99, v28
	v_fmac_f32_e32 v15, v98, v28
	v_fmac_f32_e32 v16, v97, v28
	v_fmac_f32_e32 v18, v89, v28
	v_fmac_f32_e32 v63, v106, v28
	v_fmac_f32_e32 v65, v106, v29
	v_fmac_f32_e32 v67, v105, v29
	v_fmac_f32_e32 v68, v105, v30
	v_fmac_f32_e32 v69, v105, v31
	v_fmac_f32_e32 v70, v105, v32
	v_fmac_f32_e32 v71, v105, v33
	v_fmac_f32_e32 v72, v105, v34
	v_fmac_f32_e32 v10, v93, v28
	v_fmac_f32_e32 v11, v93, v29
	v_fmac_f32_e32 v12, v92, v29
	v_fmac_f32_e32 v13, v91, v29
	v_fmac_f32_e32 v14, v90, v29
	v_fmac_f32_e32 v15, v99, v29
	v_fmac_f32_e32 v16, v98, v29
	v_fmac_f32_e32 v18, v97, v29
	v_fmac_f32_e32 v63, v107, v29
	v_fmac_f32_e32 v65, v107, v30
	v_fmac_f32_e32 v67, v106, v30
	v_fmac_f32_e32 v68, v106, v31
	v_fmac_f32_e32 v69, v106, v32
	v_fmac_f32_e32 v70, v106, v33
	v_fmac_f32_e32 v71, v106, v34
	v_fmac_f32_e32 v72, v106, v35
	v_fmac_f32_e32 v10, v94, v29
	v_fmac_f32_e32 v11, v94, v30
	v_fmac_f32_e32 v12, v93, v30
	v_fmac_f32_e32 v13, v92, v30
	v_fmac_f32_e32 v14, v91, v30
	v_fmac_f32_e32 v15, v90, v30
	v_fmac_f32_e32 v16, v99, v30
	v_fmac_f32_e32 v18, v98, v30
	v_fmac_f32_e32 v63, v103, v30
	v_fmac_f32_e32 v65, v103, v31
	v_fmac_f32_e32 v67, v107, v31
	v_fmac_f32_e32 v68, v107, v32
	v_fmac_f32_e32 v69, v107, v33
	v_fmac_f32_e32 v70, v107, v34
	v_fmac_f32_e32 v71, v107, v35
	s_waitcnt lgkmcnt(0)
	v_fmac_f32_e32 v72, v107, v17
	v_fmac_f32_e32 v10, v100, v30
	v_fmac_f32_e32 v11, v100, v31
	v_fmac_f32_e32 v12, v94, v31
	v_fmac_f32_e32 v13, v93, v31
	v_fmac_f32_e32 v14, v92, v31
	v_fmac_f32_e32 v15, v91, v31
	v_fmac_f32_e32 v16, v90, v31
	v_fmac_f32_e32 v18, v99, v31
	v_fmac_f32_e32 v63, v104, v31
	v_fmac_f32_e32 v65, v104, v32
	v_fmac_f32_e32 v67, v103, v32
	v_fmac_f32_e32 v68, v103, v33
	v_fmac_f32_e32 v69, v103, v34
	v_fmac_f32_e32 v70, v103, v35
	v_fmac_f32_e32 v71, v103, v17
	v_fmac_f32_e32 v72, v103, v36
	v_fmac_f32_e32 v10, v101, v31
	v_fmac_f32_e32 v11, v101, v32
	v_fmac_f32_e32 v12, v100, v32
	v_fmac_f32_e32 v13, v94, v32
	v_fmac_f32_e32 v14, v93, v32
	v_fmac_f32_e32 v15, v92, v32
	v_fmac_f32_e32 v16, v91, v32
	v_fmac_f32_e32 v18, v90, v32
	v_fmac_f32_e32 v63, v112, v32
	v_fmac_f32_e32 v65, v112, v33
	v_fmac_f32_e32 v67, v104, v33
	v_fmac_f32_e32 v68, v104, v34
	v_fmac_f32_e32 v69, v104, v35
	v_fmac_f32_e32 v70, v104, v17
	v_fmac_f32_e32 v71, v104, v36
	v_fmac_f32_e32 v72, v104, v37
	v_fmac_f32_e32 v10, v102, v32
	v_fmac_f32_e32 v11, v102, v33
	v_fmac_f32_e32 v12, v101, v33
	v_fmac_f32_e32 v13, v100, v33
	v_fmac_f32_e32 v14, v94, v33
	v_fmac_f32_e32 v15, v93, v33
	v_fmac_f32_e32 v16, v92, v33
	v_fmac_f32_e32 v18, v91, v33
	v_fmac_f32_e32 v63, v108, v33
	v_fmac_f32_e32 v65, v108, v34
	v_fmac_f32_e32 v67, v112, v34
	v_fmac_f32_e32 v68, v112, v35
	v_fmac_f32_e32 v69, v112, v17
	v_fmac_f32_e32 v70, v112, v36
	v_fmac_f32_e32 v71, v112, v37
	v_fmac_f32_e32 v72, v112, v38
	v_fmac_f32_e32 v10, v95, v33
	v_fmac_f32_e32 v11, v95, v34
	v_fmac_f32_e32 v12, v102, v34
	v_fmac_f32_e32 v13, v101, v34
	v_fmac_f32_e32 v14, v100, v34
	v_fmac_f32_e32 v15, v94, v34
	v_fmac_f32_e32 v16, v93, v34
	v_fmac_f32_e32 v18, v92, v34
	v_fmac_f32_e32 v63, v109, v34
	v_fmac_f32_e32 v65, v109, v35
	v_fmac_f32_e32 v67, v108, v35
	v_fmac_f32_e32 v68, v108, v17
	v_fmac_f32_e32 v69, v108, v36
	v_fmac_f32_e32 v70, v108, v37
	v_fmac_f32_e32 v71, v108, v38
	v_fmac_f32_e32 v72, v108, v39
	v_fmac_f32_e32 v10, v96, v34
	v_fmac_f32_e32 v11, v96, v35
	v_fmac_f32_e32 v12, v95, v35
	v_fmac_f32_e32 v13, v102, v35
	v_fmac_f32_e32 v14, v101, v35
	v_fmac_f32_e32 v15, v100, v35
; __device__ __forceinline__ void mixer_bd(const bf16_t* __restrict__ Z, bf16_t* __restrict__ Y, const float* __restrict__ lng, const float* __restrict__ lnb, const float* __restrict__ wsp, const float* __restrict__ bsp, ...
;     ...
;         __syncthreads();
	v_fmac_f32_e32 v16, v94, v35
	v_fmac_f32_e32 v18, v93, v35
	v_fmac_f32_e32 v63, v110, v35
	v_fmac_f32_e32 v65, v110, v17
	v_fmac_f32_e32 v67, v109, v17
	v_fmac_f32_e32 v68, v109, v36
	v_fmac_f32_e32 v69, v109, v37
	v_fmac_f32_e32 v70, v109, v38
	v_fmac_f32_e32 v71, v109, v39
	v_fmac_f32_e32 v72, v109, v40
	v_fmac_f32_e32 v10, v105, v35
	v_fmac_f32_e32 v11, v105, v17
	v_fmac_f32_e32 v12, v96, v17
	v_fmac_f32_e32 v13, v95, v17
	v_fmac_f32_e32 v14, v102, v17
	v_fmac_f32_e32 v15, v101, v17
	v_fmac_f32_e32 v16, v100, v17
	v_fmac_f32_e32 v18, v94, v17
	v_fmac_f32_e32 v63, v111, v17
	v_fmac_f32_e32 v65, v111, v36
	v_fmac_f32_e32 v67, v110, v36
	v_fmac_f32_e32 v68, v110, v37
	v_fmac_f32_e32 v69, v110, v38
	v_fmac_f32_e32 v70, v110, v39
	v_fmac_f32_e32 v71, v110, v40
	v_fmac_f32_e32 v72, v110, v41
	v_fmac_f32_e32 v10, v106, v17
	v_fmac_f32_e32 v11, v106, v36
	v_fmac_f32_e32 v12, v105, v36
	v_fmac_f32_e32 v13, v96, v36
	v_fmac_f32_e32 v14, v95, v36
	v_fmac_f32_e32 v15, v102, v36
	v_fmac_f32_e32 v16, v101, v36
	v_fmac_f32_e32 v18, v100, v36
	v_fmac_f32_e32 v63, v113, v36
	v_fmac_f32_e32 v65, v113, v37
	v_fmac_f32_e32 v67, v111, v37
	v_fmac_f32_e32 v68, v111, v38
	v_fmac_f32_e32 v69, v111, v39
	v_fmac_f32_e32 v70, v111, v40
	v_fmac_f32_e32 v71, v111, v41
	v_fmac_f32_e32 v72, v111, v42
	v_fmac_f32_e32 v10, v107, v36
	v_fmac_f32_e32 v11, v107, v37
	v_fmac_f32_e32 v12, v106, v37
	v_fmac_f32_e32 v13, v105, v37
	v_fmac_f32_e32 v14, v96, v37
	v_fmac_f32_e32 v15, v95, v37
	v_fmac_f32_e32 v16, v102, v37
	v_fmac_f32_e32 v18, v101, v37
	v_fmac_f32_e32 v63, v114, v37
	v_fmac_f32_e32 v65, v114, v38
	v_fmac_f32_e32 v67, v113, v38
	v_fmac_f32_e32 v68, v113, v39
	v_fmac_f32_e32 v69, v113, v40
	v_fmac_f32_e32 v70, v113, v41
	v_fmac_f32_e32 v71, v113, v42
	v_fmac_f32_e32 v72, v113, v43
	v_fmac_f32_e32 v10, v103, v37
	v_fmac_f32_e32 v11, v103, v38
	v_fmac_f32_e32 v12, v107, v38
	v_fmac_f32_e32 v13, v106, v38
	v_fmac_f32_e32 v14, v105, v38
	v_fmac_f32_e32 v15, v96, v38
	v_fmac_f32_e32 v16, v95, v38
	v_fmac_f32_e32 v18, v102, v38
	v_fmac_f32_e32 v63, v115, v38
	v_fmac_f32_e32 v65, v115, v39
	v_fmac_f32_e32 v67, v114, v39
	v_fmac_f32_e32 v68, v114, v40
	v_fmac_f32_e32 v69, v114, v41
	v_fmac_f32_e32 v70, v114, v42
	v_fmac_f32_e32 v71, v114, v43
	v_fmac_f32_e32 v72, v114, v44
	v_fmac_f32_e32 v10, v104, v38
	v_fmac_f32_e32 v11, v104, v39
	v_fmac_f32_e32 v12, v103, v39
	v_fmac_f32_e32 v13, v107, v39
	v_fmac_f32_e32 v14, v106, v39
	v_fmac_f32_e32 v15, v105, v39
	v_fmac_f32_e32 v16, v96, v39
	v_fmac_f32_e32 v18, v95, v39
	v_fmac_f32_e32 v67, v115, v40
	v_fmac_f32_e32 v68, v115, v41
	v_fmac_f32_e32 v69, v115, v42
	v_fmac_f32_e32 v70, v115, v43
	v_fmac_f32_e32 v71, v115, v44
	v_fmac_f32_e32 v72, v115, v45
	ds_write2st64_b32 v55, v63, v65 offset1:4
	ds_write2st64_b32 v55, v67, v68 offset0:8 offset1:12
	ds_write2st64_b32 v55, v69, v70 offset0:16 offset1:20
	ds_write2st64_b32 v55, v71, v72 offset0:24 offset1:28
	v_fmac_f32_e32 v10, v112, v39
	v_fmac_f32_e32 v11, v112, v40
	v_fmac_f32_e32 v12, v104, v40
	v_fmac_f32_e32 v13, v103, v40
	v_fmac_f32_e32 v14, v107, v40
	v_fmac_f32_e32 v15, v106, v40
	v_fmac_f32_e32 v16, v105, v40
	v_fmac_f32_e32 v18, v96, v40
	v_fmac_f32_e32 v10, v108, v40
	v_fmac_f32_e32 v11, v108, v41
	v_fmac_f32_e32 v12, v112, v41
	v_fmac_f32_e32 v13, v104, v41
	v_fmac_f32_e32 v14, v103, v41
	v_fmac_f32_e32 v15, v107, v41
	v_fmac_f32_e32 v16, v106, v41
	v_fmac_f32_e32 v18, v105, v41
	ds_read2st64_b32 v[20:21], v137 offset0:152 offset1:156
	v_fmac_f32_e32 v10, v109, v41
	v_fmac_f32_e32 v11, v109, v42
	v_fmac_f32_e32 v12, v108, v42
	v_fmac_f32_e32 v13, v112, v42
	v_fmac_f32_e32 v14, v104, v42
	v_fmac_f32_e32 v15, v103, v42
	v_fmac_f32_e32 v16, v107, v42
	v_fmac_f32_e32 v18, v106, v42
	v_fmac_f32_e32 v10, v110, v42
	v_fmac_f32_e32 v11, v110, v43
	v_fmac_f32_e32 v12, v109, v43
	v_fmac_f32_e32 v13, v108, v43
	v_fmac_f32_e32 v14, v112, v43
	v_fmac_f32_e32 v15, v104, v43
	v_fmac_f32_e32 v16, v103, v43
	v_fmac_f32_e32 v18, v107, v43
	v_fmac_f32_e32 v10, v111, v43
	v_fmac_f32_e32 v11, v111, v44
	v_fmac_f32_e32 v12, v110, v44
	v_fmac_f32_e32 v13, v109, v44
	v_fmac_f32_e32 v14, v108, v44
	v_fmac_f32_e32 v15, v112, v44
	v_fmac_f32_e32 v16, v104, v44
	v_fmac_f32_e32 v18, v103, v44
	v_fmac_f32_e32 v10, v113, v44
	v_fmac_f32_e32 v11, v113, v45
	v_fmac_f32_e32 v12, v111, v45
	v_fmac_f32_e32 v13, v110, v45
	v_fmac_f32_e32 v14, v109, v45
	v_fmac_f32_e32 v15, v108, v45
	v_fmac_f32_e32 v16, v112, v45
	v_fmac_f32_e32 v18, v104, v45
	v_fmac_f32_e32 v10, v114, v45
	s_waitcnt lgkmcnt(0)
	v_fmac_f32_e32 v11, v114, v20
	v_fmac_f32_e32 v12, v113, v20
	v_fmac_f32_e32 v13, v111, v20
	v_fmac_f32_e32 v14, v110, v20
	v_fmac_f32_e32 v15, v109, v20
	v_fmac_f32_e32 v16, v108, v20
	v_fmac_f32_e32 v18, v112, v20
	v_fmac_f32_e32 v10, v115, v20
	v_fmac_f32_e32 v11, v115, v21
	v_fmac_f32_e32 v12, v114, v21
	v_fmac_f32_e32 v13, v113, v21
	v_fmac_f32_e32 v14, v111, v21
	v_fmac_f32_e32 v15, v110, v21
	v_fmac_f32_e32 v16, v109, v21
	v_fmac_f32_e32 v18, v108, v21
	ds_read2st64_b32 v[20:21], v137 offset0:160 offset1:164
	s_waitcnt lgkmcnt(0)
	v_fmac_f32_e32 v13, v114, v20
	v_fmac_f32_e32 v14, v113, v20
	v_fmac_f32_e32 v15, v111, v20
	v_fmac_f32_e32 v16, v110, v20
	v_fmac_f32_e32 v18, v109, v20
	v_fmac_f32_e32 v12, v115, v20
	v_fmac_f32_e32 v13, v115, v21
	v_fmac_f32_e32 v14, v114, v21
	v_fmac_f32_e32 v15, v113, v21
	v_fmac_f32_e32 v16, v111, v21
	v_fmac_f32_e32 v18, v110, v21
	ds_read2st64_b32 v[20:21], v137 offset0:168 offset1:172
	s_waitcnt lgkmcnt(0)
	v_fmac_f32_e32 v15, v114, v20
	v_fmac_f32_e32 v16, v113, v20
	v_fmac_f32_e32 v18, v111, v20
	v_fmac_f32_e32 v14, v115, v20
	v_fmac_f32_e32 v15, v115, v21
	v_fmac_f32_e32 v16, v114, v21
	v_fmac_f32_e32 v18, v113, v21
	ds_read2st64_b32 v[20:21], v137 offset0:176 offset1:180
	s_waitcnt lgkmcnt(0)
	v_fmac_f32_e32 v18, v114, v20
	v_fmac_f32_e32 v16, v115, v20
	v_fmac_f32_e32 v18, v115, v21
	ds_write2st64_b32 v55, v10, v11 offset0:32 offset1:36
	ds_write2st64_b32 v55, v12, v13 offset0:40 offset1:44
	ds_write2st64_b32 v55, v14, v15 offset0:48 offset1:52
	ds_write2st64_b32 v55, v16, v18 offset0:56 offset1:60
	s_waitcnt lgkmcnt(0)
	s_barrier
	ds_read_b128 v[10:13], v46
	s_waitcnt lgkmcnt(0)
	v_mov_b32_e32 v14, v11
	v_mov_b32_e32 v15, v12
	v_mov_b32_e32 v16, v10
	v_mov_b32_e32 v17, v13
	v_pk_add_f32 v[14:15], v[14:15], v[16:17]
	s_nop 0
	v_add_f32_e32 v14, v14, v15
	v_mov_b32_e32 v15, v1
	s_nop 0
	v_add_f32_dpp v14, v14, v14 row_shr:1 row_mask:0xf bank_mask:0xf bound_ctrl:1
	s_nop 1
	v_add_f32_dpp v14, v14, v14 row_shr:2 row_mask:0xf bank_mask:0xf bound_ctrl:1
	s_nop 1
	v_add_f32_dpp v14, v14, v14 row_shr:4 row_mask:0xf bank_mask:0xf bound_ctrl:1
	s_nop 1
	v_add_f32_dpp v14, v14, v14 row_shr:8 row_mask:0xf bank_mask:0xf bound_ctrl:1
	s_nop 1
	v_mov_b32_dpp v15, v14 row_bcast:15 row_mask:0xa bank_mask:0xf
	v_add_f32_e32 v14, v14, v15
	v_mov_b32_e32 v15, v1
	s_nop 1
	v_mov_b32_dpp v15, v14 row_bcast:31 row_mask:0xc bank_mask:0xf
	v_add_f32_e32 v14, v14, v15
	s_nop 0
	v_readlane_b32 s71, v14, 63
	s_nop 1
	v_fma_f32 v11, s71, v241, v11
	v_fma_f32 v10, s71, v241, v10
	v_fma_f32 v13, s71, v241, v13
	v_fmac_f32_e32 v12, s71, v241
	v_pk_mul_f32 v[14:15], v[12:13], v[12:13]
	v_pk_mul_f32 v[16:17], v[10:11], v[10:11]
	s_nop 0
	v_pk_mov_b32 v[18:19], v[16:17], v[14:15] op_sel:[1,0]
	v_mov_b32_e32 v17, v15
	v_pk_add_f32 v[14:15], v[18:19], v[16:17]
	s_nop 0
	v_add_f32_e32 v14, v14, v15
	v_mov_b32_e32 v15, v1
	s_nop 0
	v_add_f32_dpp v14, v14, v14 row_shr:1 row_mask:0xf bank_mask:0xf bound_ctrl:1
	s_nop 1
	v_add_f32_dpp v14, v14, v14 row_shr:2 row_mask:0xf bank_mask:0xf bound_ctrl:1
	s_nop 1
	v_add_f32_dpp v14, v14, v14 row_shr:4 row_mask:0xf bank_mask:0xf bound_ctrl:1
	s_nop 1
	v_add_f32_dpp v14, v14, v14 row_shr:8 row_mask:0xf bank_mask:0xf bound_ctrl:1
	s_nop 1
	v_mov_b32_dpp v15, v14 row_bcast:15 row_mask:0xa bank_mask:0xf
	v_add_f32_e32 v14, v14, v15
	v_mov_b32_e32 v15, v1
	s_nop 1
	v_mov_b32_dpp v15, v14 row_bcast:31 row_mask:0xc bank_mask:0xf
	v_add_f32_e32 v14, v14, v15
	s_nop 0
	v_readlane_b32 s71, v14, 63
	s_nop 1
	v_fma_f32 v14, s71, v242, v197
	v_rsq_f32_e32 v14, v14
	s_nop 0
	v_pk_mul_f32 v[10:11], v[10:11], v[14:15] op_sel_hi:[1,0]
	s_nop 0
	v_pk_fma_f32 v[10:11], v[2:3], v[10:11], v[6:7]
	v_pk_mul_f32 v[12:13], v[12:13], v[14:15] op_sel_hi:[1,0]
	v_mul_f32_e32 v14, 0xbfb8aa3b, v10
	v_exp_f32_e32 v14, v14
	v_pk_fma_f32 v[12:13], v[4:5], v[12:13], v[8:9]
	v_add_f32_e32 v14, 1.0, v14
	v_rcp_f32_e32 v14, v14
	s_nop 0
	v_mul_f32_e32 v10, v10, v14
	v_mul_f32_e32 v14, 0xbfb8aa3b, v11
	v_exp_f32_e32 v14, v14
	s_nop 0
	v_add_f32_e32 v14, 1.0, v14
	v_rcp_f32_e32 v14, v14
	s_nop 0
	v_mul_f32_e32 v11, v11, v14
	v_cvt_pk_bf16_f32 v10, v10, v11
	v_mul_f32_e32 v11, 0xbfb8aa3b, v12
	v_exp_f32_e32 v11, v11
	s_nop 0
	v_add_f32_e32 v11, 1.0, v11
	v_rcp_f32_e32 v11, v11
	s_nop 0
	v_mul_f32_e32 v11, v12, v11
	v_mul_f32_e32 v12, 0xbfb8aa3b, v13
	v_exp_f32_e32 v12, v12
	s_nop 0
	v_add_f32_e32 v12, 1.0, v12
	v_rcp_f32_e32 v12, v12
	s_nop 0
	v_mul_f32_e32 v12, v13, v12
	v_cvt_pk_bf16_f32 v11, v11, v12
	v_lshl_add_u64 v[12:13], v[60:61], 0, s[72:73]
	global_store_dwordx2 v[12:13], v[10:11], off offset:1536
	ds_read_b128 v[10:13], v47
	s_add_i32 s72, s70, s88
	s_ashr_i32 s73, s72, 31
	s_lshl_b64 s[72:73], s[72:73], 11
	s_waitcnt lgkmcnt(0)
	v_mov_b32_e32 v14, v11
	v_mov_b32_e32 v15, v12
	v_mov_b32_e32 v16, v10
	v_mov_b32_e32 v17, v13
	v_pk_add_f32 v[14:15], v[14:15], v[16:17]
	s_nop 0
	v_add_f32_e32 v14, v14, v15
	v_mov_b32_e32 v15, v1
	s_nop 0
	v_add_f32_dpp v14, v14, v14 row_shr:1 row_mask:0xf bank_mask:0xf bound_ctrl:1
	s_nop 1
	v_add_f32_dpp v14, v14, v14 row_shr:2 row_mask:0xf bank_mask:0xf bound_ctrl:1
	s_nop 1
	v_add_f32_dpp v14, v14, v14 row_shr:4 row_mask:0xf bank_mask:0xf bound_ctrl:1
	s_nop 1
	v_add_f32_dpp v14, v14, v14 row_shr:8 row_mask:0xf bank_mask:0xf bound_ctrl:1
	s_nop 1
	v_mov_b32_dpp v15, v14 row_bcast:15 row_mask:0xa bank_mask:0xf
	v_add_f32_e32 v14, v14, v15
	v_mov_b32_e32 v15, v1
	s_nop 1
	v_mov_b32_dpp v15, v14 row_bcast:31 row_mask:0xc bank_mask:0xf
	v_add_f32_e32 v14, v14, v15
	s_nop 0
	v_readlane_b32 s71, v14, 63
	s_nop 1
	v_fma_f32 v11, s71, v241, v11
	v_fma_f32 v10, s71, v241, v10
	v_fma_f32 v13, s71, v241, v13
	v_fmac_f32_e32 v12, s71, v241
	v_pk_mul_f32 v[14:15], v[12:13], v[12:13]
	v_pk_mul_f32 v[16:17], v[10:11], v[10:11]
	s_nop 0
	v_pk_mov_b32 v[18:19], v[16:17], v[14:15] op_sel:[1,0]
	v_mov_b32_e32 v17, v15
	v_pk_add_f32 v[14:15], v[18:19], v[16:17]
	s_nop 0
	v_add_f32_e32 v14, v14, v15
	v_mov_b32_e32 v15, v1
	s_nop 0
	v_add_f32_dpp v14, v14, v14 row_shr:1 row_mask:0xf bank_mask:0xf bound_ctrl:1
	s_nop 1
	v_add_f32_dpp v14, v14, v14 row_shr:2 row_mask:0xf bank_mask:0xf bound_ctrl:1
	s_nop 1
	v_add_f32_dpp v14, v14, v14 row_shr:4 row_mask:0xf bank_mask:0xf bound_ctrl:1
	s_nop 1
	v_add_f32_dpp v14, v14, v14 row_shr:8 row_mask:0xf bank_mask:0xf bound_ctrl:1
	s_nop 1
	v_mov_b32_dpp v15, v14 row_bcast:15 row_mask:0xa bank_mask:0xf
	v_add_f32_e32 v14, v14, v15
	v_mov_b32_e32 v15, v1
	s_nop 1
	v_mov_b32_dpp v15, v14 row_bcast:31 row_mask:0xc bank_mask:0xf
	v_add_f32_e32 v14, v14, v15
	s_nop 0
	v_readlane_b32 s71, v14, 63
	s_nop 1
	v_fma_f32 v14, s71, v242, v197
	v_rsq_f32_e32 v14, v14
	s_nop 0
	v_pk_mul_f32 v[10:11], v[10:11], v[14:15] op_sel_hi:[1,0]
	s_nop 0
	v_pk_fma_f32 v[10:11], v[2:3], v[10:11], v[6:7]
	v_pk_mul_f32 v[12:13], v[12:13], v[14:15] op_sel_hi:[1,0]
	v_mul_f32_e32 v14, 0xbfb8aa3b, v10
	v_exp_f32_e32 v14, v14
	v_pk_fma_f32 v[12:13], v[4:5], v[12:13], v[8:9]
	v_add_f32_e32 v14, 1.0, v14
	v_rcp_f32_e32 v14, v14
	s_nop 0
	v_mul_f32_e32 v10, v10, v14
	v_mul_f32_e32 v14, 0xbfb8aa3b, v11
	v_exp_f32_e32 v14, v14
	s_nop 0
	v_add_f32_e32 v14, 1.0, v14
	v_rcp_f32_e32 v14, v14
	s_nop 0
	v_mul_f32_e32 v11, v11, v14
	v_cvt_pk_bf16_f32 v10, v10, v11
	v_mul_f32_e32 v11, 0xbfb8aa3b, v12
	v_exp_f32_e32 v11, v11
	s_nop 0
	v_add_f32_e32 v11, 1.0, v11
	v_rcp_f32_e32 v11, v11
	s_nop 0
	v_mul_f32_e32 v11, v12, v11
	v_mul_f32_e32 v12, 0xbfb8aa3b, v13
	v_exp_f32_e32 v12, v12
	s_nop 0
	v_add_f32_e32 v12, 1.0, v12
	v_rcp_f32_e32 v12, v12
	s_nop 0
	v_mul_f32_e32 v12, v13, v12
	v_cvt_pk_bf16_f32 v11, v11, v12
	v_lshl_add_u64 v[12:13], v[60:61], 0, s[72:73]
	global_store_dwordx2 v[12:13], v[10:11], off offset:1536
	ds_read_b128 v[10:13], v48
	s_add_i32 s72, s70, s91
	s_ashr_i32 s73, s72, 31
	s_lshl_b64 s[72:73], s[72:73], 11
	s_add_i32 s70, s70, s87
	s_waitcnt lgkmcnt(0)
; __device__ __forceinline__ void mixer_bd(const bf16_t* __restrict__ Z, bf16_t* __restrict__ Y, const float* __restrict__ lng, const float* __restrict__ lnb, const float* __restrict__ wsp, const float* __restrict__ bsp, ...
;     ...
;         MD_LN(2 * un + 1);
;         __syncthreads();
;     }
	v_mov_b32_e32 v14, v11
	v_mov_b32_e32 v15, v12
	v_mov_b32_e32 v16, v10
	v_mov_b32_e32 v17, v13
	v_pk_add_f32 v[14:15], v[14:15], v[16:17]
	s_nop 0
	v_add_f32_e32 v14, v14, v15
	v_mov_b32_e32 v15, v1
	s_nop 0
	v_add_f32_dpp v14, v14, v14 row_shr:1 row_mask:0xf bank_mask:0xf bound_ctrl:1
	s_nop 1
	v_add_f32_dpp v14, v14, v14 row_shr:2 row_mask:0xf bank_mask:0xf bound_ctrl:1
	s_nop 1
	v_add_f32_dpp v14, v14, v14 row_shr:4 row_mask:0xf bank_mask:0xf bound_ctrl:1
	s_nop 1
	v_add_f32_dpp v14, v14, v14 row_shr:8 row_mask:0xf bank_mask:0xf bound_ctrl:1
	s_nop 1
	v_mov_b32_dpp v15, v14 row_bcast:15 row_mask:0xa bank_mask:0xf
	v_add_f32_e32 v14, v14, v15
	v_mov_b32_e32 v15, v1
	s_nop 1
	v_mov_b32_dpp v15, v14 row_bcast:31 row_mask:0xc bank_mask:0xf
	v_add_f32_e32 v14, v14, v15
	s_nop 0
	v_readlane_b32 s71, v14, 63
	s_nop 1
	v_fma_f32 v11, s71, v241, v11
	v_fma_f32 v10, s71, v241, v10
	v_fma_f32 v13, s71, v241, v13
	v_fmac_f32_e32 v12, s71, v241
	v_pk_mul_f32 v[14:15], v[12:13], v[12:13]
	v_pk_mul_f32 v[16:17], v[10:11], v[10:11]
	s_nop 0
	v_pk_mov_b32 v[18:19], v[16:17], v[14:15] op_sel:[1,0]
	v_mov_b32_e32 v17, v15
	v_pk_add_f32 v[14:15], v[18:19], v[16:17]
	s_nop 0
	v_add_f32_e32 v14, v14, v15
	v_mov_b32_e32 v15, v1
	s_nop 0
	v_add_f32_dpp v14, v14, v14 row_shr:1 row_mask:0xf bank_mask:0xf bound_ctrl:1
	s_nop 1
	v_add_f32_dpp v14, v14, v14 row_shr:2 row_mask:0xf bank_mask:0xf bound_ctrl:1
	s_nop 1
	v_add_f32_dpp v14, v14, v14 row_shr:4 row_mask:0xf bank_mask:0xf bound_ctrl:1
	s_nop 1
	v_add_f32_dpp v14, v14, v14 row_shr:8 row_mask:0xf bank_mask:0xf bound_ctrl:1
	s_nop 1
	v_mov_b32_dpp v15, v14 row_bcast:15 row_mask:0xa bank_mask:0xf
	v_add_f32_e32 v14, v14, v15
	v_mov_b32_e32 v15, v1
	s_nop 1
	v_mov_b32_dpp v15, v14 row_bcast:31 row_mask:0xc bank_mask:0xf
	v_add_f32_e32 v14, v14, v15
	s_nop 0
	v_readlane_b32 s71, v14, 63
	s_nop 1
	v_fma_f32 v14, s71, v242, v197
	v_rsq_f32_e32 v14, v14
	s_nop 0
	v_pk_mul_f32 v[10:11], v[10:11], v[14:15] op_sel_hi:[1,0]
	s_nop 0
	v_pk_fma_f32 v[10:11], v[2:3], v[10:11], v[6:7]
	v_pk_mul_f32 v[12:13], v[12:13], v[14:15] op_sel_hi:[1,0]
	v_mul_f32_e32 v14, 0xbfb8aa3b, v10
	v_exp_f32_e32 v14, v14
	v_pk_fma_f32 v[12:13], v[4:5], v[12:13], v[8:9]
	v_add_f32_e32 v14, 1.0, v14
	v_rcp_f32_e32 v14, v14
	s_nop 0
	v_mul_f32_e32 v10, v10, v14
	v_mul_f32_e32 v14, 0xbfb8aa3b, v11
	v_exp_f32_e32 v14, v14
	s_nop 0
	v_add_f32_e32 v14, 1.0, v14
	v_rcp_f32_e32 v14, v14
	s_nop 0
	v_mul_f32_e32 v11, v11, v14
	v_cvt_pk_bf16_f32 v10, v10, v11
	v_mul_f32_e32 v11, 0xbfb8aa3b, v12
	v_exp_f32_e32 v11, v11
	s_nop 0
	v_add_f32_e32 v11, 1.0, v11
	v_rcp_f32_e32 v11, v11
	s_nop 0
	v_mul_f32_e32 v11, v12, v11
	v_mul_f32_e32 v12, 0xbfb8aa3b, v13
	v_exp_f32_e32 v12, v12
	s_nop 0
	v_add_f32_e32 v12, 1.0, v12
	v_rcp_f32_e32 v12, v12
	s_nop 0
	v_mul_f32_e32 v12, v13, v12
	v_cvt_pk_bf16_f32 v11, v11, v12
	v_lshl_add_u64 v[12:13], v[60:61], 0, s[72:73]
	global_store_dwordx2 v[12:13], v[10:11], off offset:1536
	ds_read_b128 v[10:13], v49
	s_waitcnt lgkmcnt(0)
	v_mov_b32_e32 v14, v11
	v_mov_b32_e32 v15, v12
	v_mov_b32_e32 v16, v10
	v_mov_b32_e32 v17, v13
	v_pk_add_f32 v[14:15], v[14:15], v[16:17]
	s_nop 0
	v_add_f32_e32 v14, v14, v15
	v_mov_b32_e32 v15, v1
	s_nop 0
	v_add_f32_dpp v14, v14, v14 row_shr:1 row_mask:0xf bank_mask:0xf bound_ctrl:1
	s_nop 1
	v_add_f32_dpp v14, v14, v14 row_shr:2 row_mask:0xf bank_mask:0xf bound_ctrl:1
	s_nop 1
	v_add_f32_dpp v14, v14, v14 row_shr:4 row_mask:0xf bank_mask:0xf bound_ctrl:1
	s_nop 1
	v_add_f32_dpp v14, v14, v14 row_shr:8 row_mask:0xf bank_mask:0xf bound_ctrl:1
	s_nop 1
	v_mov_b32_dpp v15, v14 row_bcast:15 row_mask:0xa bank_mask:0xf
	v_add_f32_e32 v14, v14, v15
	v_mov_b32_e32 v15, v1
	s_nop 1
	v_mov_b32_dpp v15, v14 row_bcast:31 row_mask:0xc bank_mask:0xf
	v_add_f32_e32 v14, v14, v15
	s_nop 0
	v_readlane_b32 s71, v14, 63
	s_nop 1
	v_fma_f32 v11, s71, v241, v11
	v_fma_f32 v10, s71, v241, v10
	v_fma_f32 v13, s71, v241, v13
	v_fmac_f32_e32 v12, s71, v241
	v_pk_mul_f32 v[14:15], v[12:13], v[12:13]
	v_pk_mul_f32 v[16:17], v[10:11], v[10:11]
	s_nop 0
	v_pk_mov_b32 v[18:19], v[16:17], v[14:15] op_sel:[1,0]
	v_mov_b32_e32 v17, v15
	v_pk_add_f32 v[14:15], v[18:19], v[16:17]
	s_nop 0
	v_add_f32_e32 v14, v14, v15
	v_mov_b32_e32 v15, v1
	s_nop 0
	v_add_f32_dpp v14, v14, v14 row_shr:1 row_mask:0xf bank_mask:0xf bound_ctrl:1
	s_nop 1
	v_add_f32_dpp v14, v14, v14 row_shr:2 row_mask:0xf bank_mask:0xf bound_ctrl:1
	s_nop 1
	v_add_f32_dpp v14, v14, v14 row_shr:4 row_mask:0xf bank_mask:0xf bound_ctrl:1
	s_nop 1
	v_add_f32_dpp v14, v14, v14 row_shr:8 row_mask:0xf bank_mask:0xf bound_ctrl:1
	s_nop 1
	v_mov_b32_dpp v15, v14 row_bcast:15 row_mask:0xa bank_mask:0xf
	v_add_f32_e32 v14, v14, v15
	v_mov_b32_e32 v15, v1
	s_nop 1
	v_mov_b32_dpp v15, v14 row_bcast:31 row_mask:0xc bank_mask:0xf
	v_add_f32_e32 v14, v14, v15
	s_nop 0
	v_readlane_b32 s71, v14, 63
	s_nop 1
	v_fma_f32 v14, s71, v242, v197
	v_rsq_f32_e32 v14, v14
	s_ashr_i32 s71, s70, 31
	s_lshl_b64 s[70:71], s[70:71], 11
	s_cmpk_gt_i32 s86, 0xff
	v_pk_mul_f32 v[10:11], v[10:11], v[14:15] op_sel_hi:[1,0]
	v_pk_mul_f32 v[12:13], v[12:13], v[14:15] op_sel_hi:[1,0]
	v_pk_fma_f32 v[10:11], v[2:3], v[10:11], v[6:7]
	v_pk_fma_f32 v[12:13], v[4:5], v[12:13], v[8:9]
	v_mul_f32_e32 v14, 0xbfb8aa3b, v10
	v_exp_f32_e32 v14, v14
	s_nop 0
	v_add_f32_e32 v14, 1.0, v14
	v_rcp_f32_e32 v14, v14
	s_nop 0
	v_mul_f32_e32 v10, v10, v14
	v_mul_f32_e32 v14, 0xbfb8aa3b, v11
	v_exp_f32_e32 v14, v14
	s_nop 0
	v_add_f32_e32 v14, 1.0, v14
	v_rcp_f32_e32 v14, v14
	s_nop 0
	v_mul_f32_e32 v11, v11, v14
	v_cvt_pk_bf16_f32 v10, v10, v11
	v_mul_f32_e32 v11, 0xbfb8aa3b, v12
	v_exp_f32_e32 v11, v11
	s_nop 0
	v_add_f32_e32 v11, 1.0, v11
	v_rcp_f32_e32 v11, v11
	s_nop 0
	v_mul_f32_e32 v11, v12, v11
	v_mul_f32_e32 v12, 0xbfb8aa3b, v13
	v_exp_f32_e32 v12, v12
	s_nop 0
	v_add_f32_e32 v12, 1.0, v12
	v_rcp_f32_e32 v12, v12
	s_nop 0
	v_mul_f32_e32 v12, v13, v12
	v_cvt_pk_bf16_f32 v11, v11, v12
	v_lshl_add_u64 v[12:13], v[60:61], 0, s[70:71]
	global_store_dwordx2 v[12:13], v[10:11], off offset:1536
	s_barrier
	s_cbranch_scc0 .LBB0_248
